# GEMM K loops: peeled first iteration with C=0 on the first MFMA of each accumulator block; no accumulator zeroing
# speedup vs baseline: 1.0081x; 1.0020x over previous
.LBB0_271:
	s_ashr_i32 s37, s36, 31
	s_lshl_b64 s[38:39], s[36:37], 19
	s_add_u32 s38, s58, s38
	s_addc_u32 s39, s59, s39
	s_and_b64 s[40:41], s[4:5], exec
	s_cselect_b32 s37, s39, s61
	s_cselect_b32 s43, s38, s60
	s_ashr_i32 s35, s34, 31
	s_lshl_b64 s[40:41], s[34:35], 19
	s_add_u32 s40, s66, s40
	s_addc_u32 s41, s67, s41
	s_and_b64 s[64:65], s[4:5], exec
	s_cselect_b32 s35, s41, s63
	s_cselect_b32 s55, s40, s62
	s_add_u32 s60, s60, 0x40080
	s_addc_u32 s61, s61, 0
	s_add_u32 s84, s62, 0x100
	s_addc_u32 s85, s63, 0
	s_mov_b32 s86, -2
	ds_read_b128 v[146:149], v153
	ds_read_b128 v[156:159], v153 offset:1024
	ds_read_b128 v[160:163], v153 offset:2048
	ds_read_b128 v[164:167], v153 offset:3072
	ds_read_b128 v[168:171], v154
	ds_read_b128 v[172:175], v154 offset:1024
	ds_read_b128 v[176:179], v154 offset:2048
	ds_read_b128 v[180:183], v154 offset:3072
	s_add_u32 s62, s60, 0xfffc0080
	s_addc_u32 s63, s61, -1
	s_cmp_eq_u32 s86, 12
	s_cselect_b32 s65, s37, s63
	s_cselect_b32 s64, s43, s62
	s_cselect_b32 s63, s35, s85
	s_cselect_b32 s62, s55, s84
	s_add_i32 m0, s69, 0xc000
	ds_read_b128 v[184:187], v155
	ds_read_b128 v[192:195], v155 offset:1024
	ds_read_b128 v[196:199], v155 offset:2048
	ds_read_b128 v[200:203], v155 offset:3072
	ds_read_b128 v[204:207], v155 offset:4096
	ds_read_b128 v[208:211], v155 offset:5120
	ds_read_b128 v[212:215], v155 offset:6144
	ds_read_b128 v[216:219], v155 offset:7168
	global_load_lds_dwordx4 v138, s[60:61]
	v_lshl_add_u64 v[188:189], s[60:61], 0, v[140:141]
	s_add_i32 m0, s69, 0xe000
	s_nop 0
	global_load_lds_dwordx4 v[188:189], off
	s_waitcnt vmcnt(8)
	s_waitcnt lgkmcnt(0)
	s_barrier
	s_setprio 1
	s_waitcnt lgkmcnt(0)
	v_mfma_f32_16x16x32_bf16 v[124:127], v[146:149], v[184:187], 0
	v_mfma_f32_16x16x32_bf16 v[120:123], v[160:163], v[184:187], 0
	v_mfma_f32_16x16x32_bf16 v[116:119], v[146:149], v[196:199], 0
	v_mfma_f32_16x16x32_bf16 v[108:111], v[160:163], v[196:199], 0
	v_mfma_f32_16x16x32_bf16 v[100:103], v[146:149], v[204:207], 0
	v_mfma_f32_16x16x32_bf16 v[92:95], v[160:163], v[204:207], 0
	v_mfma_f32_16x16x32_bf16 v[84:87], v[146:149], v[212:215], 0
	v_mfma_f32_16x16x32_bf16 v[76:79], v[160:163], v[212:215], 0
	v_mfma_f32_16x16x32_bf16 v[124:127], v[156:159], v[192:195], v[124:127]
	v_mfma_f32_16x16x32_bf16 v[120:123], v[164:167], v[192:195], v[120:123]
	v_mfma_f32_16x16x32_bf16 v[116:119], v[156:159], v[200:203], v[116:119]
	v_mfma_f32_16x16x32_bf16 v[108:111], v[164:167], v[200:203], v[108:111]
	v_mfma_f32_16x16x32_bf16 v[100:103], v[156:159], v[208:211], v[100:103]
	v_mfma_f32_16x16x32_bf16 v[92:95], v[164:167], v[208:211], v[92:95]
	v_mfma_f32_16x16x32_bf16 v[84:87], v[156:159], v[216:219], v[84:87]
	v_mfma_f32_16x16x32_bf16 v[76:79], v[164:167], v[216:219], v[76:79]
	s_setprio 0
	s_setprio 1
	v_mfma_f32_16x16x32_bf16 v[112:115], v[168:171], v[184:187], 0
	v_mfma_f32_16x16x32_bf16 v[104:107], v[176:179], v[184:187], 0
	v_mfma_f32_16x16x32_bf16 v[96:99], v[168:171], v[196:199], 0
	v_mfma_f32_16x16x32_bf16 v[88:91], v[176:179], v[196:199], 0
	v_mfma_f32_16x16x32_bf16 v[80:83], v[168:171], v[204:207], 0
	v_mfma_f32_16x16x32_bf16 v[72:75], v[176:179], v[204:207], 0
	v_mfma_f32_16x16x32_bf16 v[68:71], v[168:171], v[212:215], 0
	v_mfma_f32_16x16x32_bf16 v[64:67], v[176:179], v[212:215], 0
	v_mfma_f32_16x16x32_bf16 v[112:115], v[172:175], v[192:195], v[112:115]
	v_mfma_f32_16x16x32_bf16 v[104:107], v[180:183], v[192:195], v[104:107]
	v_mfma_f32_16x16x32_bf16 v[96:99], v[172:175], v[200:203], v[96:99]
	v_mfma_f32_16x16x32_bf16 v[88:91], v[180:183], v[200:203], v[88:91]
	v_mfma_f32_16x16x32_bf16 v[80:83], v[172:175], v[208:211], v[80:83]
	v_mfma_f32_16x16x32_bf16 v[72:75], v[180:183], v[208:211], v[72:75]
	v_mfma_f32_16x16x32_bf16 v[68:71], v[172:175], v[216:219], v[68:71]
	v_mfma_f32_16x16x32_bf16 v[64:67], v[180:183], v[216:219], v[64:67]
	s_setprio 0
	s_barrier
	s_add_i32 s87, s76, s68
	v_lshl_add_u64 v[188:189], s[62:63], 0, v[132:133]
	s_mov_b32 m0, s87
	ds_read_b128 v[184:187], v155 offset:16384
	ds_read_b128 v[192:195], v155 offset:17408
	ds_read_b128 v[196:199], v155 offset:18432
	ds_read_b128 v[200:203], v155 offset:19456
	ds_read_b128 v[204:207], v155 offset:20480
	ds_read_b128 v[208:211], v155 offset:21504
	ds_read_b128 v[212:215], v155 offset:22528
	ds_read_b128 v[216:219], v155 offset:23552
	global_load_lds_dwordx4 v[188:189], off
	s_add_i32 m0, s87, 0x2000
	s_add_u32 s88, s62, 0x40000
	v_lshl_add_u64 v[220:221], s[62:63], 0, v[128:129]
	s_addc_u32 s89, s63, 0
	s_add_i32 s87, s77, s68
	global_load_lds_dwordx4 v[220:221], off
	s_mov_b32 m0, s87
	v_lshl_add_u64 v[224:225], s[64:65], 0, v[130:131]
	global_load_lds_dwordx4 v132, s[88:89]
	s_add_i32 m0, s87, 0x2000
	s_nop 0
	global_load_lds_dwordx4 v128, s[88:89]
	v_lshl_add_u64 v[222:223], s[64:65], 0, v[134:135]
	s_mov_b32 m0, s69
	s_nop 0
	global_load_lds_dwordx4 v[222:223], off
	s_mov_b32 m0, s70
	s_nop 0
	global_load_lds_dwordx4 v[224:225], off
	s_waitcnt vmcnt(8)
	s_waitcnt lgkmcnt(0)
	s_barrier
	s_setprio 1
	s_waitcnt lgkmcnt(0)
	v_mfma_f32_16x16x32_bf16 v[60:63], v[146:149], v[184:187], 0
	v_mfma_f32_16x16x32_bf16 v[56:59], v[160:163], v[184:187], 0
	v_mfma_f32_16x16x32_bf16 v[52:55], v[146:149], v[196:199], 0
	v_mfma_f32_16x16x32_bf16 v[44:47], v[160:163], v[196:199], 0
	v_mfma_f32_16x16x32_bf16 v[36:39], v[146:149], v[204:207], 0
	v_mfma_f32_16x16x32_bf16 v[28:31], v[160:163], v[204:207], 0
	v_mfma_f32_16x16x32_bf16 v[20:23], v[146:149], v[212:215], 0
	v_mfma_f32_16x16x32_bf16 v[12:15], v[160:163], v[212:215], 0
	v_mfma_f32_16x16x32_bf16 v[60:63], v[156:159], v[192:195], v[60:63]
	v_mfma_f32_16x16x32_bf16 v[56:59], v[164:167], v[192:195], v[56:59]
	v_mfma_f32_16x16x32_bf16 v[52:55], v[156:159], v[200:203], v[52:55]
	v_mfma_f32_16x16x32_bf16 v[44:47], v[164:167], v[200:203], v[44:47]
	v_mfma_f32_16x16x32_bf16 v[36:39], v[156:159], v[208:211], v[36:39]
	v_mfma_f32_16x16x32_bf16 v[28:31], v[164:167], v[208:211], v[28:31]
	v_mfma_f32_16x16x32_bf16 v[20:23], v[156:159], v[216:219], v[20:23]
	v_mfma_f32_16x16x32_bf16 v[12:15], v[164:167], v[216:219], v[12:15]
	s_setprio 0
	s_setprio 1
	v_mfma_f32_16x16x32_bf16 v[48:51], v[168:171], v[184:187], 0
	v_mfma_f32_16x16x32_bf16 v[40:43], v[176:179], v[184:187], 0
	v_mfma_f32_16x16x32_bf16 v[32:35], v[168:171], v[196:199], 0
	v_mfma_f32_16x16x32_bf16 v[24:27], v[176:179], v[196:199], 0
	v_mfma_f32_16x16x32_bf16 v[16:19], v[168:171], v[204:207], 0
	v_mfma_f32_16x16x32_bf16 v[8:11], v[176:179], v[204:207], 0
	v_mfma_f32_16x16x32_bf16 v[4:7], v[168:171], v[212:215], 0
	v_mfma_f32_16x16x32_bf16 v[0:3], v[176:179], v[212:215], 0
	v_mfma_f32_16x16x32_bf16 v[48:51], v[172:175], v[192:195], v[48:51]
	v_mfma_f32_16x16x32_bf16 v[40:43], v[180:183], v[192:195], v[40:43]
	v_mfma_f32_16x16x32_bf16 v[32:35], v[172:175], v[200:203], v[32:35]
	v_mfma_f32_16x16x32_bf16 v[24:27], v[180:183], v[200:203], v[24:27]
	v_mfma_f32_16x16x32_bf16 v[16:19], v[172:175], v[208:211], v[16:19]
	v_mfma_f32_16x16x32_bf16 v[8:11], v[180:183], v[208:211], v[8:11]
	v_mfma_f32_16x16x32_bf16 v[4:7], v[172:175], v[216:219], v[4:7]
	v_mfma_f32_16x16x32_bf16 v[0:3], v[180:183], v[216:219], v[0:3]
	s_setprio 0
	s_barrier
	s_add_i32 s87, 0, 0x18000
	s_add_i32 s88, 0, 0x1c000
	v_add_u32_e32 v164, s87, v151
	v_add_u32_e32 v180, s88, v151
	ds_read_b128 v[146:149], v164
	ds_read_b128 v[156:159], v164 offset:1024
	ds_read_b128 v[160:163], v164 offset:2048
	ds_read_b128 v[164:167], v164 offset:3072
	ds_read_b128 v[168:171], v180
	ds_read_b128 v[172:175], v180 offset:1024
	ds_read_b128 v[176:179], v180 offset:2048
	ds_read_b128 v[180:183], v180 offset:3072
	s_add_u32 s64, s64, 0x40000
	s_addc_u32 s65, s65, 0
	s_mov_b32 m0, s71
	ds_read_b128 v[184:187], v155 offset:32768
	ds_read_b128 v[192:195], v155 offset:33792
	ds_read_b128 v[196:199], v155 offset:34816
	ds_read_b128 v[200:203], v155 offset:35840
	ds_read_b128 v[204:207], v155 offset:36864
	ds_read_b128 v[208:211], v155 offset:37888
	ds_read_b128 v[212:215], v155 offset:38912
	ds_read_b128 v[216:219], v155 offset:39936
	global_load_lds_dwordx4 v134, s[64:65]
	s_mov_b32 m0, s72
	s_nop 0
	global_load_lds_dwordx4 v130, s[64:65]
	s_waitcnt vmcnt(8)
	s_waitcnt lgkmcnt(0)
	s_barrier
	s_setprio 1
	s_waitcnt lgkmcnt(0)
	v_mfma_f32_16x16x32_bf16 v[124:127], v[146:149], v[184:187], v[124:127]
	v_mfma_f32_16x16x32_bf16 v[120:123], v[160:163], v[184:187], v[120:123]
	v_mfma_f32_16x16x32_bf16 v[116:119], v[146:149], v[196:199], v[116:119]
	v_mfma_f32_16x16x32_bf16 v[108:111], v[160:163], v[196:199], v[108:111]
	v_mfma_f32_16x16x32_bf16 v[100:103], v[146:149], v[204:207], v[100:103]
	v_mfma_f32_16x16x32_bf16 v[92:95], v[160:163], v[204:207], v[92:95]
	v_mfma_f32_16x16x32_bf16 v[84:87], v[146:149], v[212:215], v[84:87]
	v_mfma_f32_16x16x32_bf16 v[76:79], v[160:163], v[212:215], v[76:79]
	v_mfma_f32_16x16x32_bf16 v[124:127], v[156:159], v[192:195], v[124:127]
	v_mfma_f32_16x16x32_bf16 v[120:123], v[164:167], v[192:195], v[120:123]
	v_mfma_f32_16x16x32_bf16 v[116:119], v[156:159], v[200:203], v[116:119]
	v_mfma_f32_16x16x32_bf16 v[108:111], v[164:167], v[200:203], v[108:111]
	v_mfma_f32_16x16x32_bf16 v[100:103], v[156:159], v[208:211], v[100:103]
	v_mfma_f32_16x16x32_bf16 v[92:95], v[164:167], v[208:211], v[92:95]
	v_mfma_f32_16x16x32_bf16 v[84:87], v[156:159], v[216:219], v[84:87]
	v_mfma_f32_16x16x32_bf16 v[76:79], v[164:167], v[216:219], v[76:79]
	s_setprio 0
	s_setprio 1
	v_mfma_f32_16x16x32_bf16 v[112:115], v[168:171], v[184:187], v[112:115]
	v_mfma_f32_16x16x32_bf16 v[104:107], v[176:179], v[184:187], v[104:107]
	v_mfma_f32_16x16x32_bf16 v[96:99], v[168:171], v[196:199], v[96:99]
	v_mfma_f32_16x16x32_bf16 v[88:91], v[176:179], v[196:199], v[88:91]
	v_mfma_f32_16x16x32_bf16 v[80:83], v[168:171], v[204:207], v[80:83]
	v_mfma_f32_16x16x32_bf16 v[72:75], v[176:179], v[204:207], v[72:75]
	v_mfma_f32_16x16x32_bf16 v[68:71], v[168:171], v[212:215], v[68:71]
	v_mfma_f32_16x16x32_bf16 v[64:67], v[176:179], v[212:215], v[64:67]
	v_mfma_f32_16x16x32_bf16 v[112:115], v[172:175], v[192:195], v[112:115]
	v_mfma_f32_16x16x32_bf16 v[104:107], v[180:183], v[192:195], v[104:107]
	v_mfma_f32_16x16x32_bf16 v[96:99], v[172:175], v[200:203], v[96:99]
	v_mfma_f32_16x16x32_bf16 v[88:91], v[180:183], v[200:203], v[88:91]
	v_mfma_f32_16x16x32_bf16 v[80:83], v[172:175], v[208:211], v[80:83]
	v_mfma_f32_16x16x32_bf16 v[72:75], v[180:183], v[208:211], v[72:75]
	v_mfma_f32_16x16x32_bf16 v[68:71], v[172:175], v[216:219], v[68:71]
	v_mfma_f32_16x16x32_bf16 v[64:67], v[180:183], v[216:219], v[64:67]
	s_setprio 0
	s_barrier
	s_add_i32 s64, s87, s68
	v_lshl_add_u64 v[188:189], v[188:189], 0, s[10:11]
	s_mov_b32 m0, s64
	ds_read_b128 v[184:187], v155 offset:49152
	ds_read_b128 v[192:195], v155 offset:50176
	ds_read_b128 v[196:199], v155 offset:51200
	ds_read_b128 v[200:203], v155 offset:52224
	ds_read_b128 v[204:207], v155 offset:53248
	ds_read_b128 v[208:211], v155 offset:54272
	ds_read_b128 v[212:215], v155 offset:55296
	ds_read_b128 v[216:219], v155 offset:56320
	global_load_lds_dwordx4 v[188:189], off
	s_add_i32 m0, s64, 0x2000
	s_add_u32 s62, s62, 0x40080
	v_lshl_add_u64 v[188:189], v[220:221], 0, s[10:11]
	s_addc_u32 s63, s63, 0
	s_add_i32 s64, s88, s68
	global_load_lds_dwordx4 v[188:189], off
	s_mov_b32 m0, s64
	s_nop 0
	global_load_lds_dwordx4 v132, s[62:63]
	s_add_i32 m0, s64, 0x2000
	s_nop 0
	global_load_lds_dwordx4 v128, s[62:63]
	v_lshl_add_u64 v[188:189], v[222:223], 0, s[10:11]
	s_mov_b32 m0, s33
	s_nop 0
	global_load_lds_dwordx4 v[188:189], off
	v_lshl_add_u64 v[188:189], v[224:225], 0, s[10:11]
	s_mov_b32 m0, s74
	s_nop 0
	global_load_lds_dwordx4 v[188:189], off
	s_waitcnt vmcnt(8)
	s_waitcnt lgkmcnt(0)
	s_barrier
	s_setprio 1
	s_waitcnt lgkmcnt(0)
	v_mfma_f32_16x16x32_bf16 v[60:63], v[146:149], v[184:187], v[60:63]
	v_mfma_f32_16x16x32_bf16 v[56:59], v[160:163], v[184:187], v[56:59]
	v_mfma_f32_16x16x32_bf16 v[52:55], v[146:149], v[196:199], v[52:55]
	v_mfma_f32_16x16x32_bf16 v[44:47], v[160:163], v[196:199], v[44:47]
	v_mfma_f32_16x16x32_bf16 v[36:39], v[146:149], v[204:207], v[36:39]
	v_mfma_f32_16x16x32_bf16 v[28:31], v[160:163], v[204:207], v[28:31]
	v_mfma_f32_16x16x32_bf16 v[20:23], v[146:149], v[212:215], v[20:23]
	v_mfma_f32_16x16x32_bf16 v[12:15], v[160:163], v[212:215], v[12:15]
	v_mfma_f32_16x16x32_bf16 v[60:63], v[156:159], v[192:195], v[60:63]
	v_mfma_f32_16x16x32_bf16 v[56:59], v[164:167], v[192:195], v[56:59]
	v_mfma_f32_16x16x32_bf16 v[52:55], v[156:159], v[200:203], v[52:55]
	v_mfma_f32_16x16x32_bf16 v[44:47], v[164:167], v[200:203], v[44:47]
	v_mfma_f32_16x16x32_bf16 v[36:39], v[156:159], v[208:211], v[36:39]
	v_mfma_f32_16x16x32_bf16 v[28:31], v[164:167], v[208:211], v[28:31]
	v_mfma_f32_16x16x32_bf16 v[20:23], v[156:159], v[216:219], v[20:23]
	v_mfma_f32_16x16x32_bf16 v[12:15], v[164:167], v[216:219], v[12:15]
	s_setprio 0
	s_setprio 1
	v_mfma_f32_16x16x32_bf16 v[48:51], v[168:171], v[184:187], v[48:51]
	v_mfma_f32_16x16x32_bf16 v[40:43], v[176:179], v[184:187], v[40:43]
	v_mfma_f32_16x16x32_bf16 v[32:35], v[168:171], v[196:199], v[32:35]
	v_mfma_f32_16x16x32_bf16 v[24:27], v[176:179], v[196:199], v[24:27]
	v_mfma_f32_16x16x32_bf16 v[16:19], v[168:171], v[204:207], v[16:19]
	v_mfma_f32_16x16x32_bf16 v[8:11], v[176:179], v[204:207], v[8:11]
	v_mfma_f32_16x16x32_bf16 v[4:7], v[168:171], v[212:215], v[4:7]
	v_mfma_f32_16x16x32_bf16 v[0:3], v[176:179], v[212:215], v[0:3]
	v_mfma_f32_16x16x32_bf16 v[48:51], v[172:175], v[192:195], v[48:51]
	v_mfma_f32_16x16x32_bf16 v[40:43], v[180:183], v[192:195], v[40:43]
	v_mfma_f32_16x16x32_bf16 v[32:35], v[172:175], v[200:203], v[32:35]
	v_mfma_f32_16x16x32_bf16 v[24:27], v[180:183], v[200:203], v[24:27]
	v_mfma_f32_16x16x32_bf16 v[16:19], v[172:175], v[208:211], v[16:19]
	v_mfma_f32_16x16x32_bf16 v[8:11], v[180:183], v[208:211], v[8:11]
	v_mfma_f32_16x16x32_bf16 v[4:7], v[172:175], v[216:219], v[4:7]
	v_mfma_f32_16x16x32_bf16 v[0:3], v[180:183], v[216:219], v[0:3]
	s_setprio 0
	s_barrier
	s_add_i32 s86, s86, 2
	s_add_u32 s60, s60, 0x100
	s_addc_u32 s61, s61, 0
	s_add_u32 s84, s84, 0x100
	s_addc_u32 s85, s85, 0
	s_cmp_gt_u32 s86, 13
	s_cbranch_scc0 .LBB0_272
	s_branch .Lpeel_exit0

.Lpeel_exit0:
	s_and_b64 vcc, exec, s[12:13]
	s_cbranch_vccz .LBB0_277
	s_barrier
	v_lshl_add_u32 v148, s42, 8, v150
	s_cmp_gt_i32 s54, 7
	s_mov_b64 s[42:43], -1
	s_cbranch_scc1 .LBB0_278

.LBB0_301:
	s_ashr_i32 s27, s26, 31
	s_lshl_b64 s[28:29], s[26:27], 19
	s_add_u32 s28, s43, s28
	s_addc_u32 s29, s52, s29
	s_and_b64 s[30:31], s[4:5], exec
	s_cselect_b32 s27, s29, s37
	s_cselect_b32 s55, s28, s36
	s_ashr_i32 s25, s24, 31
	s_lshl_b64 s[30:31], s[24:25], 19
	s_add_u32 s30, s58, s30
	s_addc_u32 s31, s59, s31
	s_and_b64 s[40:41], s[4:5], exec
	s_cselect_b32 s25, s31, s39
	s_cselect_b32 s72, s30, s38
	s_add_u32 s36, s36, 0x40080
	s_addc_u32 s37, s37, 0
	s_add_u32 s73, s38, 0x100
	s_addc_u32 s74, s39, 0
	s_mov_b32 s75, -2
	ds_read_b128 v[152:155], v149
	ds_read_b128 v[156:159], v149 offset:1024
	ds_read_b128 v[160:163], v149 offset:2048
	ds_read_b128 v[164:167], v149 offset:3072
	ds_read_b128 v[168:171], v150
	ds_read_b128 v[172:175], v150 offset:1024
	ds_read_b128 v[176:179], v150 offset:2048
	ds_read_b128 v[180:183], v150 offset:3072
	s_add_u32 s38, s36, 0xfffc0080
	s_addc_u32 s39, s37, -1
	s_cmp_eq_u32 s75, 12
	s_cselect_b32 s41, s27, s39
	s_cselect_b32 s40, s55, s38
	s_cselect_b32 s39, s25, s74
	s_cselect_b32 s38, s72, s73
	v_lshl_add_u64 v[144:145], s[36:37], 0, v[136:137]
	s_add_i32 m0, s35, 0xc000
	ds_read_b128 v[184:187], v151
	ds_read_b128 v[192:195], v151 offset:1024
	ds_read_b128 v[196:199], v151 offset:2048
	ds_read_b128 v[200:203], v151 offset:3072
	ds_read_b128 v[204:207], v151 offset:4096
	ds_read_b128 v[208:211], v151 offset:5120
	ds_read_b128 v[212:215], v151 offset:6144
	ds_read_b128 v[216:219], v151 offset:7168
	global_load_lds_dwordx4 v[144:145], off
	s_add_i32 m0, s35, 0xe000
	s_nop 0
	global_load_lds_dwordx4 v138, s[36:37]
	s_waitcnt vmcnt(8)
	s_waitcnt lgkmcnt(0)
	s_barrier
	s_setprio 1
	s_waitcnt lgkmcnt(0)
	v_mfma_f32_16x16x32_bf16 v[124:127], v[152:155], v[184:187], 0
	v_mfma_f32_16x16x32_bf16 v[120:123], v[160:163], v[184:187], 0
	v_mfma_f32_16x16x32_bf16 v[116:119], v[152:155], v[196:199], 0
	v_mfma_f32_16x16x32_bf16 v[108:111], v[160:163], v[196:199], 0
	v_mfma_f32_16x16x32_bf16 v[100:103], v[152:155], v[204:207], 0
	v_mfma_f32_16x16x32_bf16 v[92:95], v[160:163], v[204:207], 0
	v_mfma_f32_16x16x32_bf16 v[84:87], v[152:155], v[212:215], 0
	v_mfma_f32_16x16x32_bf16 v[76:79], v[160:163], v[212:215], 0
	v_mfma_f32_16x16x32_bf16 v[124:127], v[156:159], v[192:195], v[124:127]
	v_mfma_f32_16x16x32_bf16 v[120:123], v[164:167], v[192:195], v[120:123]
	v_mfma_f32_16x16x32_bf16 v[116:119], v[156:159], v[200:203], v[116:119]
	v_mfma_f32_16x16x32_bf16 v[108:111], v[164:167], v[200:203], v[108:111]
	v_mfma_f32_16x16x32_bf16 v[100:103], v[156:159], v[208:211], v[100:103]
	v_mfma_f32_16x16x32_bf16 v[92:95], v[164:167], v[208:211], v[92:95]
	v_mfma_f32_16x16x32_bf16 v[84:87], v[156:159], v[216:219], v[84:87]
	v_mfma_f32_16x16x32_bf16 v[76:79], v[164:167], v[216:219], v[76:79]
	s_setprio 0
	s_setprio 1
	v_mfma_f32_16x16x32_bf16 v[112:115], v[168:171], v[184:187], 0
	v_mfma_f32_16x16x32_bf16 v[104:107], v[176:179], v[184:187], 0
	v_mfma_f32_16x16x32_bf16 v[96:99], v[168:171], v[196:199], 0
	v_mfma_f32_16x16x32_bf16 v[88:91], v[176:179], v[196:199], 0
	v_mfma_f32_16x16x32_bf16 v[80:83], v[168:171], v[204:207], 0
	v_mfma_f32_16x16x32_bf16 v[72:75], v[176:179], v[204:207], 0
	v_mfma_f32_16x16x32_bf16 v[68:71], v[168:171], v[212:215], 0
	v_mfma_f32_16x16x32_bf16 v[64:67], v[176:179], v[212:215], 0
	v_mfma_f32_16x16x32_bf16 v[112:115], v[172:175], v[192:195], v[112:115]
	v_mfma_f32_16x16x32_bf16 v[104:107], v[180:183], v[192:195], v[104:107]
	v_mfma_f32_16x16x32_bf16 v[96:99], v[172:175], v[200:203], v[96:99]
	v_mfma_f32_16x16x32_bf16 v[88:91], v[180:183], v[200:203], v[88:91]
	v_mfma_f32_16x16x32_bf16 v[80:83], v[172:175], v[208:211], v[80:83]
	v_mfma_f32_16x16x32_bf16 v[72:75], v[180:183], v[208:211], v[72:75]
	v_mfma_f32_16x16x32_bf16 v[68:71], v[172:175], v[216:219], v[68:71]
	v_mfma_f32_16x16x32_bf16 v[64:67], v[180:183], v[216:219], v[64:67]
	s_setprio 0
	s_barrier
	s_add_i32 s76, s66, s53
	v_lshl_add_u64 v[144:145], s[38:39], 0, v[130:131]
	s_mov_b32 m0, s76
	ds_read_b128 v[184:187], v151 offset:16384
	ds_read_b128 v[192:195], v151 offset:17408
	ds_read_b128 v[196:199], v151 offset:18432
	ds_read_b128 v[200:203], v151 offset:19456
	ds_read_b128 v[204:207], v151 offset:20480
	ds_read_b128 v[208:211], v151 offset:21504
	ds_read_b128 v[212:215], v151 offset:22528
	ds_read_b128 v[216:219], v151 offset:23552
	global_load_lds_dwordx4 v[144:145], off
	s_add_i32 m0, s76, 0x2000
	s_add_u32 s76, s38, 0x40000
	v_lshl_add_u64 v[188:189], s[38:39], 0, v[134:135]
	s_addc_u32 s77, s39, 0
	s_add_i32 s80, s67, s53
	global_load_lds_dwordx4 v[188:189], off
	s_mov_b32 m0, s80
	v_lshl_add_u64 v[222:223], s[40:41], 0, v[132:133]
	global_load_lds_dwordx4 v130, s[76:77]
	s_add_i32 m0, s80, 0x2000
	s_nop 0
	global_load_lds_dwordx4 v134, s[76:77]
	v_lshl_add_u64 v[220:221], s[40:41], 0, v[128:129]
	s_mov_b32 m0, s35
	s_nop 0
	global_load_lds_dwordx4 v[220:221], off
	s_mov_b32 m0, s33
	s_nop 0
	global_load_lds_dwordx4 v[222:223], off
	s_waitcnt vmcnt(8)
	s_waitcnt lgkmcnt(0)
	s_barrier
	s_setprio 1
	s_waitcnt lgkmcnt(0)
	v_mfma_f32_16x16x32_bf16 v[60:63], v[152:155], v[184:187], 0
	v_mfma_f32_16x16x32_bf16 v[56:59], v[160:163], v[184:187], 0
	v_mfma_f32_16x16x32_bf16 v[52:55], v[152:155], v[196:199], 0
	v_mfma_f32_16x16x32_bf16 v[44:47], v[160:163], v[196:199], 0
	v_mfma_f32_16x16x32_bf16 v[36:39], v[152:155], v[204:207], 0
	v_mfma_f32_16x16x32_bf16 v[28:31], v[160:163], v[204:207], 0
	v_mfma_f32_16x16x32_bf16 v[20:23], v[152:155], v[212:215], 0
	v_mfma_f32_16x16x32_bf16 v[12:15], v[160:163], v[212:215], 0
	v_mfma_f32_16x16x32_bf16 v[60:63], v[156:159], v[192:195], v[60:63]
	v_mfma_f32_16x16x32_bf16 v[56:59], v[164:167], v[192:195], v[56:59]
	v_mfma_f32_16x16x32_bf16 v[52:55], v[156:159], v[200:203], v[52:55]
	v_mfma_f32_16x16x32_bf16 v[44:47], v[164:167], v[200:203], v[44:47]
	v_mfma_f32_16x16x32_bf16 v[36:39], v[156:159], v[208:211], v[36:39]
	v_mfma_f32_16x16x32_bf16 v[28:31], v[164:167], v[208:211], v[28:31]
	v_mfma_f32_16x16x32_bf16 v[20:23], v[156:159], v[216:219], v[20:23]
	v_mfma_f32_16x16x32_bf16 v[12:15], v[164:167], v[216:219], v[12:15]
	s_setprio 0
	s_setprio 1
	v_mfma_f32_16x16x32_bf16 v[48:51], v[168:171], v[184:187], 0
	v_mfma_f32_16x16x32_bf16 v[40:43], v[176:179], v[184:187], 0
	v_mfma_f32_16x16x32_bf16 v[32:35], v[168:171], v[196:199], 0
	v_mfma_f32_16x16x32_bf16 v[24:27], v[176:179], v[196:199], 0
	v_mfma_f32_16x16x32_bf16 v[16:19], v[168:171], v[204:207], 0
	v_mfma_f32_16x16x32_bf16 v[8:11], v[176:179], v[204:207], 0
	v_mfma_f32_16x16x32_bf16 v[4:7], v[168:171], v[212:215], 0
	v_mfma_f32_16x16x32_bf16 v[0:3], v[176:179], v[212:215], 0
	v_mfma_f32_16x16x32_bf16 v[48:51], v[172:175], v[192:195], v[48:51]
	v_mfma_f32_16x16x32_bf16 v[40:43], v[180:183], v[192:195], v[40:43]
	v_mfma_f32_16x16x32_bf16 v[32:35], v[172:175], v[200:203], v[32:35]
	v_mfma_f32_16x16x32_bf16 v[24:27], v[180:183], v[200:203], v[24:27]
	v_mfma_f32_16x16x32_bf16 v[16:19], v[172:175], v[208:211], v[16:19]
	v_mfma_f32_16x16x32_bf16 v[8:11], v[180:183], v[208:211], v[8:11]
	v_mfma_f32_16x16x32_bf16 v[4:7], v[172:175], v[216:219], v[4:7]
	v_mfma_f32_16x16x32_bf16 v[0:3], v[180:183], v[216:219], v[0:3]
	s_setprio 0
	s_barrier
	s_add_i32 s76, 0, 0x18000
	s_add_i32 s77, 0, 0x1c000
	v_add_u32_e32 v164, s76, v147
	v_add_u32_e32 v180, s77, v147
	ds_read_b128 v[152:155], v164
	ds_read_b128 v[156:159], v164 offset:1024
	ds_read_b128 v[160:163], v164 offset:2048
	ds_read_b128 v[164:167], v164 offset:3072
	ds_read_b128 v[168:171], v180
	ds_read_b128 v[172:175], v180 offset:1024
	ds_read_b128 v[176:179], v180 offset:2048
	ds_read_b128 v[180:183], v180 offset:3072
	s_add_u32 s40, s40, 0x40000
	s_addc_u32 s41, s41, 0
	s_mov_b32 m0, s60
	ds_read_b128 v[184:187], v151 offset:32768
	ds_read_b128 v[192:195], v151 offset:33792
	ds_read_b128 v[196:199], v151 offset:34816
	ds_read_b128 v[200:203], v151 offset:35840
	ds_read_b128 v[204:207], v151 offset:36864
	ds_read_b128 v[208:211], v151 offset:37888
	ds_read_b128 v[212:215], v151 offset:38912
	ds_read_b128 v[216:219], v151 offset:39936
	global_load_lds_dwordx4 v128, s[40:41]
	s_mov_b32 m0, s61
	s_nop 0
	global_load_lds_dwordx4 v132, s[40:41]
	s_waitcnt vmcnt(8)
	s_waitcnt lgkmcnt(0)
	s_barrier
	s_setprio 1
	s_waitcnt lgkmcnt(0)
	v_mfma_f32_16x16x32_bf16 v[124:127], v[152:155], v[184:187], v[124:127]
	v_mfma_f32_16x16x32_bf16 v[120:123], v[160:163], v[184:187], v[120:123]
	v_mfma_f32_16x16x32_bf16 v[116:119], v[152:155], v[196:199], v[116:119]
	v_mfma_f32_16x16x32_bf16 v[108:111], v[160:163], v[196:199], v[108:111]
	v_mfma_f32_16x16x32_bf16 v[100:103], v[152:155], v[204:207], v[100:103]
	v_mfma_f32_16x16x32_bf16 v[92:95], v[160:163], v[204:207], v[92:95]
	v_mfma_f32_16x16x32_bf16 v[84:87], v[152:155], v[212:215], v[84:87]
	v_mfma_f32_16x16x32_bf16 v[76:79], v[160:163], v[212:215], v[76:79]
	v_mfma_f32_16x16x32_bf16 v[124:127], v[156:159], v[192:195], v[124:127]
	v_mfma_f32_16x16x32_bf16 v[120:123], v[164:167], v[192:195], v[120:123]
	v_mfma_f32_16x16x32_bf16 v[116:119], v[156:159], v[200:203], v[116:119]
	v_mfma_f32_16x16x32_bf16 v[108:111], v[164:167], v[200:203], v[108:111]
	v_mfma_f32_16x16x32_bf16 v[100:103], v[156:159], v[208:211], v[100:103]
	v_mfma_f32_16x16x32_bf16 v[92:95], v[164:167], v[208:211], v[92:95]
	v_mfma_f32_16x16x32_bf16 v[84:87], v[156:159], v[216:219], v[84:87]
	v_mfma_f32_16x16x32_bf16 v[76:79], v[164:167], v[216:219], v[76:79]
	s_setprio 0
	s_setprio 1
	v_mfma_f32_16x16x32_bf16 v[112:115], v[168:171], v[184:187], v[112:115]
	v_mfma_f32_16x16x32_bf16 v[104:107], v[176:179], v[184:187], v[104:107]
	v_mfma_f32_16x16x32_bf16 v[96:99], v[168:171], v[196:199], v[96:99]
	v_mfma_f32_16x16x32_bf16 v[88:91], v[176:179], v[196:199], v[88:91]
	v_mfma_f32_16x16x32_bf16 v[80:83], v[168:171], v[204:207], v[80:83]
	v_mfma_f32_16x16x32_bf16 v[72:75], v[176:179], v[204:207], v[72:75]
	v_mfma_f32_16x16x32_bf16 v[68:71], v[168:171], v[212:215], v[68:71]
	v_mfma_f32_16x16x32_bf16 v[64:67], v[176:179], v[212:215], v[64:67]
	v_mfma_f32_16x16x32_bf16 v[112:115], v[172:175], v[192:195], v[112:115]
	v_mfma_f32_16x16x32_bf16 v[104:107], v[180:183], v[192:195], v[104:107]
	v_mfma_f32_16x16x32_bf16 v[96:99], v[172:175], v[200:203], v[96:99]
	v_mfma_f32_16x16x32_bf16 v[88:91], v[180:183], v[200:203], v[88:91]
	v_mfma_f32_16x16x32_bf16 v[80:83], v[172:175], v[208:211], v[80:83]
	v_mfma_f32_16x16x32_bf16 v[72:75], v[180:183], v[208:211], v[72:75]
	v_mfma_f32_16x16x32_bf16 v[68:71], v[172:175], v[216:219], v[68:71]
	v_mfma_f32_16x16x32_bf16 v[64:67], v[180:183], v[216:219], v[64:67]
	s_setprio 0
	s_barrier
	s_add_i32 s40, s76, s53
	v_lshl_add_u64 v[144:145], v[144:145], 0, s[12:13]
	s_mov_b32 m0, s40
	ds_read_b128 v[184:187], v151 offset:49152
	ds_read_b128 v[192:195], v151 offset:50176
	ds_read_b128 v[196:199], v151 offset:51200
	ds_read_b128 v[200:203], v151 offset:52224
	ds_read_b128 v[204:207], v151 offset:53248
	ds_read_b128 v[208:211], v151 offset:54272
	ds_read_b128 v[212:215], v151 offset:55296
	ds_read_b128 v[216:219], v151 offset:56320
	global_load_lds_dwordx4 v[144:145], off
	s_add_i32 m0, s40, 0x2000
	s_add_u32 s38, s38, 0x40080
	v_lshl_add_u64 v[144:145], v[188:189], 0, s[12:13]
	s_addc_u32 s39, s39, 0
	s_add_i32 s40, s77, s53
	global_load_lds_dwordx4 v[144:145], off
	s_mov_b32 m0, s40
	s_nop 0
	global_load_lds_dwordx4 v130, s[38:39]
	s_add_i32 m0, s40, 0x2000
	s_nop 0
	global_load_lds_dwordx4 v134, s[38:39]
	v_lshl_add_u64 v[144:145], v[220:221], 0, s[12:13]
	s_mov_b32 m0, s63
	s_nop 0
	global_load_lds_dwordx4 v[144:145], off
	v_lshl_add_u64 v[144:145], v[222:223], 0, s[12:13]
	s_mov_b32 m0, s64
	s_nop 0
	global_load_lds_dwordx4 v[144:145], off
	s_waitcnt vmcnt(8)
	s_waitcnt lgkmcnt(0)
	s_barrier
	s_setprio 1
	s_waitcnt lgkmcnt(0)
	v_mfma_f32_16x16x32_bf16 v[60:63], v[152:155], v[184:187], v[60:63]
	v_mfma_f32_16x16x32_bf16 v[56:59], v[160:163], v[184:187], v[56:59]
	v_mfma_f32_16x16x32_bf16 v[52:55], v[152:155], v[196:199], v[52:55]
	v_mfma_f32_16x16x32_bf16 v[44:47], v[160:163], v[196:199], v[44:47]
	v_mfma_f32_16x16x32_bf16 v[36:39], v[152:155], v[204:207], v[36:39]
	v_mfma_f32_16x16x32_bf16 v[28:31], v[160:163], v[204:207], v[28:31]
	v_mfma_f32_16x16x32_bf16 v[20:23], v[152:155], v[212:215], v[20:23]
	v_mfma_f32_16x16x32_bf16 v[12:15], v[160:163], v[212:215], v[12:15]
	v_mfma_f32_16x16x32_bf16 v[60:63], v[156:159], v[192:195], v[60:63]
	v_mfma_f32_16x16x32_bf16 v[56:59], v[164:167], v[192:195], v[56:59]
	v_mfma_f32_16x16x32_bf16 v[52:55], v[156:159], v[200:203], v[52:55]
	v_mfma_f32_16x16x32_bf16 v[44:47], v[164:167], v[200:203], v[44:47]
	v_mfma_f32_16x16x32_bf16 v[36:39], v[156:159], v[208:211], v[36:39]
	v_mfma_f32_16x16x32_bf16 v[28:31], v[164:167], v[208:211], v[28:31]
	v_mfma_f32_16x16x32_bf16 v[20:23], v[156:159], v[216:219], v[20:23]
	v_mfma_f32_16x16x32_bf16 v[12:15], v[164:167], v[216:219], v[12:15]
	s_setprio 0
	s_setprio 1
	v_mfma_f32_16x16x32_bf16 v[48:51], v[168:171], v[184:187], v[48:51]
	v_mfma_f32_16x16x32_bf16 v[40:43], v[176:179], v[184:187], v[40:43]
	v_mfma_f32_16x16x32_bf16 v[32:35], v[168:171], v[196:199], v[32:35]
	v_mfma_f32_16x16x32_bf16 v[24:27], v[176:179], v[196:199], v[24:27]
	v_mfma_f32_16x16x32_bf16 v[16:19], v[168:171], v[204:207], v[16:19]
	v_mfma_f32_16x16x32_bf16 v[8:11], v[176:179], v[204:207], v[8:11]
	v_mfma_f32_16x16x32_bf16 v[4:7], v[168:171], v[212:215], v[4:7]
	v_mfma_f32_16x16x32_bf16 v[0:3], v[176:179], v[212:215], v[0:3]
	v_mfma_f32_16x16x32_bf16 v[48:51], v[172:175], v[192:195], v[48:51]
	v_mfma_f32_16x16x32_bf16 v[40:43], v[180:183], v[192:195], v[40:43]
	v_mfma_f32_16x16x32_bf16 v[32:35], v[172:175], v[200:203], v[32:35]
	v_mfma_f32_16x16x32_bf16 v[24:27], v[180:183], v[200:203], v[24:27]
	v_mfma_f32_16x16x32_bf16 v[16:19], v[172:175], v[208:211], v[16:19]
	v_mfma_f32_16x16x32_bf16 v[8:11], v[180:183], v[208:211], v[8:11]
	v_mfma_f32_16x16x32_bf16 v[4:7], v[172:175], v[216:219], v[4:7]
	v_mfma_f32_16x16x32_bf16 v[0:3], v[180:183], v[216:219], v[0:3]
	s_setprio 0
	s_barrier
	s_add_i32 s75, s75, 2
	s_add_u32 s36, s36, 0x100
	s_addc_u32 s37, s37, 0
	s_add_u32 s73, s73, 0x100
	s_addc_u32 s74, s74, 0
	s_cmp_gt_u32 s75, 13
	s_cbranch_scc0 .LBB0_302
	s_branch .Lpeel_exit1

.Lpeel_exit1:
	s_and_b64 vcc, exec, s[14:15]
	s_cbranch_vccz .LBB0_305
	s_barrier

.LBB0_699:
	s_ashr_i32 s25, s24, 31
	s_lshl_b64 s[26:27], s[24:25], 19
	s_add_u32 s26, s58, s26
	s_addc_u32 s27, s59, s27
	s_and_b64 s[28:29], s[4:5], exec
	s_cselect_b32 s25, s27, s35
	s_cselect_b32 s55, s26, s34
	s_ashr_i32 s23, s22, 31
	s_lshl_b64 s[28:29], s[22:23], 19
	s_add_u32 s28, s43, s28
	s_addc_u32 s29, s52, s29
	s_and_b64 s[40:41], s[4:5], exec
	s_cselect_b32 s23, s29, s39
	s_cselect_b32 s72, s28, s38
	s_add_u32 s34, s34, 0x40080
	s_addc_u32 s35, s35, 0
	s_add_u32 s73, s38, 0x100
	s_addc_u32 s74, s39, 0
	s_mov_b32 s75, -2
	ds_read_b128 v[152:155], v149
	ds_read_b128 v[156:159], v149 offset:1024
	ds_read_b128 v[160:163], v149 offset:2048
	ds_read_b128 v[164:167], v149 offset:3072
	ds_read_b128 v[168:171], v150
	ds_read_b128 v[172:175], v150 offset:1024
	ds_read_b128 v[176:179], v150 offset:2048
	ds_read_b128 v[180:183], v150 offset:3072
	s_add_u32 s38, s34, 0xfffc0080
	s_addc_u32 s39, s35, -1
	s_cmp_eq_u32 s75, 12
	s_cselect_b32 s41, s25, s39
	s_cselect_b32 s40, s55, s38
	s_cselect_b32 s39, s23, s74
	s_cselect_b32 s38, s72, s73
	s_add_i32 m0, s31, 0xc000
	ds_read_b128 v[184:187], v151
	ds_read_b128 v[192:195], v151 offset:1024
	ds_read_b128 v[196:199], v151 offset:2048
	ds_read_b128 v[200:203], v151 offset:3072
	ds_read_b128 v[204:207], v151 offset:4096
	ds_read_b128 v[208:211], v151 offset:5120
	ds_read_b128 v[212:215], v151 offset:6144
	ds_read_b128 v[216:219], v151 offset:7168
	global_load_lds_dwordx4 v136, s[34:35]
	s_add_i32 m0, s31, 0xe000
	s_nop 0
	global_load_lds_dwordx4 v138, s[34:35]
	s_waitcnt vmcnt(8)
	s_waitcnt lgkmcnt(0)
	s_barrier
	s_setprio 1
	s_waitcnt lgkmcnt(0)
	v_mfma_f32_16x16x32_bf16 v[124:127], v[152:155], v[184:187], 0
	v_mfma_f32_16x16x32_bf16 v[120:123], v[160:163], v[184:187], 0
	v_mfma_f32_16x16x32_bf16 v[116:119], v[152:155], v[196:199], 0
	v_mfma_f32_16x16x32_bf16 v[108:111], v[160:163], v[196:199], 0
	v_mfma_f32_16x16x32_bf16 v[100:103], v[152:155], v[204:207], 0
	v_mfma_f32_16x16x32_bf16 v[92:95], v[160:163], v[204:207], 0
	v_mfma_f32_16x16x32_bf16 v[84:87], v[152:155], v[212:215], 0
	v_mfma_f32_16x16x32_bf16 v[76:79], v[160:163], v[212:215], 0
	v_mfma_f32_16x16x32_bf16 v[124:127], v[156:159], v[192:195], v[124:127]
	v_mfma_f32_16x16x32_bf16 v[120:123], v[164:167], v[192:195], v[120:123]
	v_mfma_f32_16x16x32_bf16 v[116:119], v[156:159], v[200:203], v[116:119]
	v_mfma_f32_16x16x32_bf16 v[108:111], v[164:167], v[200:203], v[108:111]
	v_mfma_f32_16x16x32_bf16 v[100:103], v[156:159], v[208:211], v[100:103]
	v_mfma_f32_16x16x32_bf16 v[92:95], v[164:167], v[208:211], v[92:95]
	v_mfma_f32_16x16x32_bf16 v[84:87], v[156:159], v[216:219], v[84:87]
	v_mfma_f32_16x16x32_bf16 v[76:79], v[164:167], v[216:219], v[76:79]
	s_setprio 0
	s_setprio 1
	v_mfma_f32_16x16x32_bf16 v[112:115], v[168:171], v[184:187], 0
	v_mfma_f32_16x16x32_bf16 v[104:107], v[176:179], v[184:187], 0
	v_mfma_f32_16x16x32_bf16 v[96:99], v[168:171], v[196:199], 0
	v_mfma_f32_16x16x32_bf16 v[88:91], v[176:179], v[196:199], 0
	v_mfma_f32_16x16x32_bf16 v[80:83], v[168:171], v[204:207], 0
	v_mfma_f32_16x16x32_bf16 v[72:75], v[176:179], v[204:207], 0
	v_mfma_f32_16x16x32_bf16 v[68:71], v[168:171], v[212:215], 0
	v_mfma_f32_16x16x32_bf16 v[64:67], v[176:179], v[212:215], 0
	v_mfma_f32_16x16x32_bf16 v[112:115], v[172:175], v[192:195], v[112:115]
	v_mfma_f32_16x16x32_bf16 v[104:107], v[180:183], v[192:195], v[104:107]
	v_mfma_f32_16x16x32_bf16 v[96:99], v[172:175], v[200:203], v[96:99]
	v_mfma_f32_16x16x32_bf16 v[88:91], v[180:183], v[200:203], v[88:91]
	v_mfma_f32_16x16x32_bf16 v[80:83], v[172:175], v[208:211], v[80:83]
	v_mfma_f32_16x16x32_bf16 v[72:75], v[180:183], v[208:211], v[72:75]
	v_mfma_f32_16x16x32_bf16 v[68:71], v[172:175], v[216:219], v[68:71]
	v_mfma_f32_16x16x32_bf16 v[64:67], v[180:183], v[216:219], v[64:67]
	s_setprio 0
	s_barrier
	s_add_i32 s76, s66, s53
	v_lshl_add_u64 v[144:145], s[38:39], 0, v[130:131]
	s_mov_b32 m0, s76
	ds_read_b128 v[184:187], v151 offset:16384
	ds_read_b128 v[192:195], v151 offset:17408
	ds_read_b128 v[196:199], v151 offset:18432
	ds_read_b128 v[200:203], v151 offset:19456
	ds_read_b128 v[204:207], v151 offset:20480
	ds_read_b128 v[208:211], v151 offset:21504
	ds_read_b128 v[212:215], v151 offset:22528
	ds_read_b128 v[216:219], v151 offset:23552
	global_load_lds_dwordx4 v[144:145], off
	s_add_i32 m0, s76, 0x2000
	s_add_u32 s76, s38, 0x40000
	v_lshl_add_u64 v[188:189], s[38:39], 0, v[134:135]
	s_addc_u32 s77, s39, 0
	s_add_i32 s79, s67, s53
	global_load_lds_dwordx4 v[188:189], off
	s_mov_b32 m0, s79
	v_lshl_add_u64 v[222:223], s[40:41], 0, v[132:133]
	global_load_lds_dwordx4 v130, s[76:77]
	s_add_i32 m0, s79, 0x2000
	s_nop 0
	global_load_lds_dwordx4 v134, s[76:77]
	v_lshl_add_u64 v[220:221], s[40:41], 0, v[128:129]
	s_mov_b32 m0, s31
	s_nop 0
	global_load_lds_dwordx4 v[220:221], off
	s_mov_b32 m0, s33
	s_nop 0
	global_load_lds_dwordx4 v[222:223], off
	s_waitcnt vmcnt(8)
	s_waitcnt lgkmcnt(0)
	s_barrier
	s_setprio 1
	s_waitcnt lgkmcnt(0)
	v_mfma_f32_16x16x32_bf16 v[60:63], v[152:155], v[184:187], 0
	v_mfma_f32_16x16x32_bf16 v[56:59], v[160:163], v[184:187], 0
	v_mfma_f32_16x16x32_bf16 v[52:55], v[152:155], v[196:199], 0
	v_mfma_f32_16x16x32_bf16 v[44:47], v[160:163], v[196:199], 0
	v_mfma_f32_16x16x32_bf16 v[36:39], v[152:155], v[204:207], 0
	v_mfma_f32_16x16x32_bf16 v[28:31], v[160:163], v[204:207], 0
	v_mfma_f32_16x16x32_bf16 v[20:23], v[152:155], v[212:215], 0
	v_mfma_f32_16x16x32_bf16 v[12:15], v[160:163], v[212:215], 0
	v_mfma_f32_16x16x32_bf16 v[60:63], v[156:159], v[192:195], v[60:63]
	v_mfma_f32_16x16x32_bf16 v[56:59], v[164:167], v[192:195], v[56:59]
	v_mfma_f32_16x16x32_bf16 v[52:55], v[156:159], v[200:203], v[52:55]
	v_mfma_f32_16x16x32_bf16 v[44:47], v[164:167], v[200:203], v[44:47]
	v_mfma_f32_16x16x32_bf16 v[36:39], v[156:159], v[208:211], v[36:39]
	v_mfma_f32_16x16x32_bf16 v[28:31], v[164:167], v[208:211], v[28:31]
	v_mfma_f32_16x16x32_bf16 v[20:23], v[156:159], v[216:219], v[20:23]
	v_mfma_f32_16x16x32_bf16 v[12:15], v[164:167], v[216:219], v[12:15]
	s_setprio 0
	s_setprio 1
	v_mfma_f32_16x16x32_bf16 v[48:51], v[168:171], v[184:187], 0
	v_mfma_f32_16x16x32_bf16 v[40:43], v[176:179], v[184:187], 0
	v_mfma_f32_16x16x32_bf16 v[32:35], v[168:171], v[196:199], 0
	v_mfma_f32_16x16x32_bf16 v[24:27], v[176:179], v[196:199], 0
	v_mfma_f32_16x16x32_bf16 v[16:19], v[168:171], v[204:207], 0
	v_mfma_f32_16x16x32_bf16 v[8:11], v[176:179], v[204:207], 0
	v_mfma_f32_16x16x32_bf16 v[4:7], v[168:171], v[212:215], 0
	v_mfma_f32_16x16x32_bf16 v[0:3], v[176:179], v[212:215], 0
	v_mfma_f32_16x16x32_bf16 v[48:51], v[172:175], v[192:195], v[48:51]
	v_mfma_f32_16x16x32_bf16 v[40:43], v[180:183], v[192:195], v[40:43]
	v_mfma_f32_16x16x32_bf16 v[32:35], v[172:175], v[200:203], v[32:35]
	v_mfma_f32_16x16x32_bf16 v[24:27], v[180:183], v[200:203], v[24:27]
	v_mfma_f32_16x16x32_bf16 v[16:19], v[172:175], v[208:211], v[16:19]
	v_mfma_f32_16x16x32_bf16 v[8:11], v[180:183], v[208:211], v[8:11]
	v_mfma_f32_16x16x32_bf16 v[4:7], v[172:175], v[216:219], v[4:7]
	v_mfma_f32_16x16x32_bf16 v[0:3], v[180:183], v[216:219], v[0:3]
	s_setprio 0
	s_barrier
	s_add_i32 s76, 0, 0x18000
	s_add_i32 s77, 0, 0x1c000
	v_add_u32_e32 v164, s76, v147
	v_add_u32_e32 v180, s77, v147
	ds_read_b128 v[152:155], v164
	ds_read_b128 v[156:159], v164 offset:1024
	ds_read_b128 v[160:163], v164 offset:2048
	ds_read_b128 v[164:167], v164 offset:3072
	ds_read_b128 v[168:171], v180
	ds_read_b128 v[172:175], v180 offset:1024
	ds_read_b128 v[176:179], v180 offset:2048
	ds_read_b128 v[180:183], v180 offset:3072
	s_add_u32 s40, s40, 0x40000
	s_addc_u32 s41, s41, 0
	s_mov_b32 m0, s60
	ds_read_b128 v[184:187], v151 offset:32768
	ds_read_b128 v[192:195], v151 offset:33792
	ds_read_b128 v[196:199], v151 offset:34816
	ds_read_b128 v[200:203], v151 offset:35840
	ds_read_b128 v[204:207], v151 offset:36864
	ds_read_b128 v[208:211], v151 offset:37888
	ds_read_b128 v[212:215], v151 offset:38912
	ds_read_b128 v[216:219], v151 offset:39936
	global_load_lds_dwordx4 v128, s[40:41]
	s_mov_b32 m0, s61
	s_nop 0
	global_load_lds_dwordx4 v132, s[40:41]
	s_waitcnt vmcnt(8)
	s_waitcnt lgkmcnt(0)
	s_barrier
	s_setprio 1
	s_waitcnt lgkmcnt(0)
	v_mfma_f32_16x16x32_bf16 v[124:127], v[152:155], v[184:187], v[124:127]
	v_mfma_f32_16x16x32_bf16 v[120:123], v[160:163], v[184:187], v[120:123]
	v_mfma_f32_16x16x32_bf16 v[116:119], v[152:155], v[196:199], v[116:119]
	v_mfma_f32_16x16x32_bf16 v[108:111], v[160:163], v[196:199], v[108:111]
	v_mfma_f32_16x16x32_bf16 v[100:103], v[152:155], v[204:207], v[100:103]
	v_mfma_f32_16x16x32_bf16 v[92:95], v[160:163], v[204:207], v[92:95]
	v_mfma_f32_16x16x32_bf16 v[84:87], v[152:155], v[212:215], v[84:87]
	v_mfma_f32_16x16x32_bf16 v[76:79], v[160:163], v[212:215], v[76:79]
	v_mfma_f32_16x16x32_bf16 v[124:127], v[156:159], v[192:195], v[124:127]
	v_mfma_f32_16x16x32_bf16 v[120:123], v[164:167], v[192:195], v[120:123]
	v_mfma_f32_16x16x32_bf16 v[116:119], v[156:159], v[200:203], v[116:119]
	v_mfma_f32_16x16x32_bf16 v[108:111], v[164:167], v[200:203], v[108:111]
	v_mfma_f32_16x16x32_bf16 v[100:103], v[156:159], v[208:211], v[100:103]
	v_mfma_f32_16x16x32_bf16 v[92:95], v[164:167], v[208:211], v[92:95]
	v_mfma_f32_16x16x32_bf16 v[84:87], v[156:159], v[216:219], v[84:87]
	v_mfma_f32_16x16x32_bf16 v[76:79], v[164:167], v[216:219], v[76:79]
	s_setprio 0
	s_setprio 1
	v_mfma_f32_16x16x32_bf16 v[112:115], v[168:171], v[184:187], v[112:115]
	v_mfma_f32_16x16x32_bf16 v[104:107], v[176:179], v[184:187], v[104:107]
	v_mfma_f32_16x16x32_bf16 v[96:99], v[168:171], v[196:199], v[96:99]
	v_mfma_f32_16x16x32_bf16 v[88:91], v[176:179], v[196:199], v[88:91]
	v_mfma_f32_16x16x32_bf16 v[80:83], v[168:171], v[204:207], v[80:83]
	v_mfma_f32_16x16x32_bf16 v[72:75], v[176:179], v[204:207], v[72:75]
	v_mfma_f32_16x16x32_bf16 v[68:71], v[168:171], v[212:215], v[68:71]
	v_mfma_f32_16x16x32_bf16 v[64:67], v[176:179], v[212:215], v[64:67]
	v_mfma_f32_16x16x32_bf16 v[112:115], v[172:175], v[192:195], v[112:115]
	v_mfma_f32_16x16x32_bf16 v[104:107], v[180:183], v[192:195], v[104:107]
	v_mfma_f32_16x16x32_bf16 v[96:99], v[172:175], v[200:203], v[96:99]
	v_mfma_f32_16x16x32_bf16 v[88:91], v[180:183], v[200:203], v[88:91]
	v_mfma_f32_16x16x32_bf16 v[80:83], v[172:175], v[208:211], v[80:83]
	v_mfma_f32_16x16x32_bf16 v[72:75], v[180:183], v[208:211], v[72:75]
	v_mfma_f32_16x16x32_bf16 v[68:71], v[172:175], v[216:219], v[68:71]
	v_mfma_f32_16x16x32_bf16 v[64:67], v[180:183], v[216:219], v[64:67]
	s_setprio 0
	s_barrier
	s_add_i32 s40, s76, s53
	v_lshl_add_u64 v[144:145], v[144:145], 0, s[12:13]
	s_mov_b32 m0, s40
	ds_read_b128 v[184:187], v151 offset:49152
	ds_read_b128 v[192:195], v151 offset:50176
	ds_read_b128 v[196:199], v151 offset:51200
	ds_read_b128 v[200:203], v151 offset:52224
	ds_read_b128 v[204:207], v151 offset:53248
	ds_read_b128 v[208:211], v151 offset:54272
	ds_read_b128 v[212:215], v151 offset:55296
	ds_read_b128 v[216:219], v151 offset:56320
	global_load_lds_dwordx4 v[144:145], off
	s_add_i32 m0, s40, 0x2000
	s_add_u32 s38, s38, 0x40080
	v_lshl_add_u64 v[144:145], v[188:189], 0, s[12:13]
	s_addc_u32 s39, s39, 0
	s_add_i32 s40, s77, s53
	global_load_lds_dwordx4 v[144:145], off
	s_mov_b32 m0, s40
	s_nop 0
	global_load_lds_dwordx4 v130, s[38:39]
	s_add_i32 m0, s40, 0x2000
	s_nop 0
	global_load_lds_dwordx4 v134, s[38:39]
	v_lshl_add_u64 v[144:145], v[220:221], 0, s[12:13]
	s_mov_b32 m0, s63
	s_nop 0
	global_load_lds_dwordx4 v[144:145], off
	v_lshl_add_u64 v[144:145], v[222:223], 0, s[12:13]
	s_mov_b32 m0, s64
	s_nop 0
	global_load_lds_dwordx4 v[144:145], off
	s_waitcnt vmcnt(8)
	s_waitcnt lgkmcnt(0)
	s_barrier
	s_setprio 1
	s_waitcnt lgkmcnt(0)
	v_mfma_f32_16x16x32_bf16 v[60:63], v[152:155], v[184:187], v[60:63]
	v_mfma_f32_16x16x32_bf16 v[56:59], v[160:163], v[184:187], v[56:59]
	v_mfma_f32_16x16x32_bf16 v[52:55], v[152:155], v[196:199], v[52:55]
	v_mfma_f32_16x16x32_bf16 v[44:47], v[160:163], v[196:199], v[44:47]
	v_mfma_f32_16x16x32_bf16 v[36:39], v[152:155], v[204:207], v[36:39]
	v_mfma_f32_16x16x32_bf16 v[28:31], v[160:163], v[204:207], v[28:31]
	v_mfma_f32_16x16x32_bf16 v[20:23], v[152:155], v[212:215], v[20:23]
	v_mfma_f32_16x16x32_bf16 v[12:15], v[160:163], v[212:215], v[12:15]
	v_mfma_f32_16x16x32_bf16 v[60:63], v[156:159], v[192:195], v[60:63]
	v_mfma_f32_16x16x32_bf16 v[56:59], v[164:167], v[192:195], v[56:59]
	v_mfma_f32_16x16x32_bf16 v[52:55], v[156:159], v[200:203], v[52:55]
	v_mfma_f32_16x16x32_bf16 v[44:47], v[164:167], v[200:203], v[44:47]
	v_mfma_f32_16x16x32_bf16 v[36:39], v[156:159], v[208:211], v[36:39]
	v_mfma_f32_16x16x32_bf16 v[28:31], v[164:167], v[208:211], v[28:31]
	v_mfma_f32_16x16x32_bf16 v[20:23], v[156:159], v[216:219], v[20:23]
	v_mfma_f32_16x16x32_bf16 v[12:15], v[164:167], v[216:219], v[12:15]
	s_setprio 0
	s_setprio 1
	v_mfma_f32_16x16x32_bf16 v[48:51], v[168:171], v[184:187], v[48:51]
	v_mfma_f32_16x16x32_bf16 v[40:43], v[176:179], v[184:187], v[40:43]
	v_mfma_f32_16x16x32_bf16 v[32:35], v[168:171], v[196:199], v[32:35]
	v_mfma_f32_16x16x32_bf16 v[24:27], v[176:179], v[196:199], v[24:27]
	v_mfma_f32_16x16x32_bf16 v[16:19], v[168:171], v[204:207], v[16:19]
	v_mfma_f32_16x16x32_bf16 v[8:11], v[176:179], v[204:207], v[8:11]
	v_mfma_f32_16x16x32_bf16 v[4:7], v[168:171], v[212:215], v[4:7]
	v_mfma_f32_16x16x32_bf16 v[0:3], v[176:179], v[212:215], v[0:3]
	v_mfma_f32_16x16x32_bf16 v[48:51], v[172:175], v[192:195], v[48:51]
	v_mfma_f32_16x16x32_bf16 v[40:43], v[180:183], v[192:195], v[40:43]
	v_mfma_f32_16x16x32_bf16 v[32:35], v[172:175], v[200:203], v[32:35]
	v_mfma_f32_16x16x32_bf16 v[24:27], v[180:183], v[200:203], v[24:27]
	v_mfma_f32_16x16x32_bf16 v[16:19], v[172:175], v[208:211], v[16:19]
	v_mfma_f32_16x16x32_bf16 v[8:11], v[180:183], v[208:211], v[8:11]
	v_mfma_f32_16x16x32_bf16 v[4:7], v[172:175], v[216:219], v[4:7]
	v_mfma_f32_16x16x32_bf16 v[0:3], v[180:183], v[216:219], v[0:3]
	s_setprio 0
	s_barrier
	s_add_i32 s75, s75, 2
	s_add_u32 s34, s34, 0x100
	s_addc_u32 s35, s35, 0
	s_add_u32 s73, s73, 0x100
	s_addc_u32 s74, s74, 0
	s_cmp_gt_u32 s75, 13
	s_cbranch_scc0 .LBB0_700
	s_branch .Lpeel_exit2

.LBB0_836:
	s_ashr_i32 s25, s24, 31
	s_lshl_b64 s[26:27], s[24:25], 19
	s_add_u32 s26, s58, s26
	s_addc_u32 s27, s59, s27
	s_and_b64 s[28:29], s[4:5], exec
	s_cselect_b32 s25, s27, s35
	s_cselect_b32 s54, s26, s34
	s_ashr_i32 s23, s22, 31
	s_lshl_b64 s[28:29], s[22:23], 19
	s_add_u32 s28, s61, s28
	s_addc_u32 s29, s62, s29
	s_and_b64 s[42:43], s[4:5], exec
	s_cselect_b32 s23, s29, s41
	s_cselect_b32 s55, s28, s40
	s_add_u32 s34, s34, 0x40080
	s_addc_u32 s35, s35, 0
	s_add_u32 s75, s40, 0x100
	s_addc_u32 s76, s41, 0
	s_mov_b32 s77, -2
	ds_read_b128 v[152:155], v149
	ds_read_b128 v[156:159], v149 offset:1024
	ds_read_b128 v[160:163], v149 offset:2048
	ds_read_b128 v[164:167], v149 offset:3072
	ds_read_b128 v[168:171], v150
	ds_read_b128 v[172:175], v150 offset:1024
	ds_read_b128 v[176:179], v150 offset:2048
	ds_read_b128 v[180:183], v150 offset:3072
	s_add_u32 s40, s34, 0xfffc0080
	s_addc_u32 s41, s35, -1
	s_cmp_eq_u32 s77, 12
	s_cselect_b32 s43, s25, s41
	s_cselect_b32 s42, s54, s40
	s_cselect_b32 s41, s23, s76
	s_cselect_b32 s40, s55, s75
	s_add_i32 m0, s31, 0xc000
	ds_read_b128 v[184:187], v151
	ds_read_b128 v[192:195], v151 offset:1024
	ds_read_b128 v[196:199], v151 offset:2048
	ds_read_b128 v[200:203], v151 offset:3072
	ds_read_b128 v[204:207], v151 offset:4096
	ds_read_b128 v[208:211], v151 offset:5120
	ds_read_b128 v[212:215], v151 offset:6144
	ds_read_b128 v[216:219], v151 offset:7168
	global_load_lds_dwordx4 v136, s[34:35]
	s_add_i32 m0, s31, 0xe000
	s_nop 0
	global_load_lds_dwordx4 v138, s[34:35]
	s_waitcnt vmcnt(8)
	s_waitcnt lgkmcnt(0)
	s_barrier
	s_setprio 1
	s_waitcnt lgkmcnt(0)
	v_mfma_f32_16x16x32_bf16 v[124:127], v[152:155], v[184:187], 0
	v_mfma_f32_16x16x32_bf16 v[120:123], v[160:163], v[184:187], 0
	v_mfma_f32_16x16x32_bf16 v[108:111], v[152:155], v[196:199], 0
	v_mfma_f32_16x16x32_bf16 v[104:107], v[160:163], v[196:199], 0
	v_mfma_f32_16x16x32_bf16 v[92:95], v[152:155], v[204:207], 0
	v_mfma_f32_16x16x32_bf16 v[88:91], v[160:163], v[204:207], 0
	v_mfma_f32_16x16x32_bf16 v[76:79], v[152:155], v[212:215], 0
	v_mfma_f32_16x16x32_bf16 v[72:75], v[160:163], v[212:215], 0
	v_mfma_f32_16x16x32_bf16 v[124:127], v[156:159], v[192:195], v[124:127]
	v_mfma_f32_16x16x32_bf16 v[120:123], v[164:167], v[192:195], v[120:123]
	v_mfma_f32_16x16x32_bf16 v[108:111], v[156:159], v[200:203], v[108:111]
	v_mfma_f32_16x16x32_bf16 v[104:107], v[164:167], v[200:203], v[104:107]
	v_mfma_f32_16x16x32_bf16 v[92:95], v[156:159], v[208:211], v[92:95]
	v_mfma_f32_16x16x32_bf16 v[88:91], v[164:167], v[208:211], v[88:91]
	v_mfma_f32_16x16x32_bf16 v[76:79], v[156:159], v[216:219], v[76:79]
	v_mfma_f32_16x16x32_bf16 v[72:75], v[164:167], v[216:219], v[72:75]
	s_setprio 0
	s_setprio 1
	v_mfma_f32_16x16x32_bf16 v[116:119], v[168:171], v[184:187], 0
	v_mfma_f32_16x16x32_bf16 v[112:115], v[176:179], v[184:187], 0
	v_mfma_f32_16x16x32_bf16 v[100:103], v[168:171], v[196:199], 0
	v_mfma_f32_16x16x32_bf16 v[96:99], v[176:179], v[196:199], 0
	v_mfma_f32_16x16x32_bf16 v[84:87], v[168:171], v[204:207], 0
	v_mfma_f32_16x16x32_bf16 v[80:83], v[176:179], v[204:207], 0
	v_mfma_f32_16x16x32_bf16 v[68:71], v[168:171], v[212:215], 0
	v_mfma_f32_16x16x32_bf16 v[64:67], v[176:179], v[212:215], 0
	v_mfma_f32_16x16x32_bf16 v[116:119], v[172:175], v[192:195], v[116:119]
	v_mfma_f32_16x16x32_bf16 v[112:115], v[180:183], v[192:195], v[112:115]
	v_mfma_f32_16x16x32_bf16 v[100:103], v[172:175], v[200:203], v[100:103]
	v_mfma_f32_16x16x32_bf16 v[96:99], v[180:183], v[200:203], v[96:99]
	v_mfma_f32_16x16x32_bf16 v[84:87], v[172:175], v[208:211], v[84:87]
	v_mfma_f32_16x16x32_bf16 v[80:83], v[180:183], v[208:211], v[80:83]
	v_mfma_f32_16x16x32_bf16 v[68:71], v[172:175], v[216:219], v[68:71]
	v_mfma_f32_16x16x32_bf16 v[64:67], v[180:183], v[216:219], v[64:67]
	s_setprio 0
	s_barrier
	s_add_i32 s79, s69, s63
	v_lshl_add_u64 v[144:145], s[40:41], 0, v[130:131]
	s_mov_b32 m0, s79
	ds_read_b128 v[184:187], v151 offset:16384
	ds_read_b128 v[192:195], v151 offset:17408
	ds_read_b128 v[196:199], v151 offset:18432
	ds_read_b128 v[200:203], v151 offset:19456
	ds_read_b128 v[204:207], v151 offset:20480
	ds_read_b128 v[208:211], v151 offset:21504
	ds_read_b128 v[212:215], v151 offset:22528
	ds_read_b128 v[216:219], v151 offset:23552
	global_load_lds_dwordx4 v[144:145], off
	s_add_i32 m0, s79, 0x2000
	s_add_u32 s80, s40, 0x40000
	v_lshl_add_u64 v[188:189], s[40:41], 0, v[134:135]
	s_addc_u32 s81, s41, 0
	s_add_i32 s79, s70, s63
	global_load_lds_dwordx4 v[188:189], off
	s_mov_b32 m0, s79
	v_lshl_add_u64 v[222:223], s[42:43], 0, v[132:133]
	global_load_lds_dwordx4 v130, s[80:81]
	s_add_i32 m0, s79, 0x2000
	s_nop 0
	global_load_lds_dwordx4 v134, s[80:81]
	v_lshl_add_u64 v[220:221], s[42:43], 0, v[128:129]
	s_mov_b32 m0, s31
	s_nop 0
	global_load_lds_dwordx4 v[220:221], off
	s_mov_b32 m0, s64
	s_nop 0
	global_load_lds_dwordx4 v[222:223], off
	s_waitcnt vmcnt(8)
	s_waitcnt lgkmcnt(0)
	s_barrier
	s_setprio 1
	s_waitcnt lgkmcnt(0)
	v_mfma_f32_16x16x32_bf16 v[60:63], v[152:155], v[184:187], 0
	v_mfma_f32_16x16x32_bf16 v[56:59], v[160:163], v[184:187], 0
	v_mfma_f32_16x16x32_bf16 v[44:47], v[152:155], v[196:199], 0
	v_mfma_f32_16x16x32_bf16 v[40:43], v[160:163], v[196:199], 0
	v_mfma_f32_16x16x32_bf16 v[28:31], v[152:155], v[204:207], 0
	v_mfma_f32_16x16x32_bf16 v[24:27], v[160:163], v[204:207], 0
	v_mfma_f32_16x16x32_bf16 v[12:15], v[152:155], v[212:215], 0
	v_mfma_f32_16x16x32_bf16 v[8:11], v[160:163], v[212:215], 0
	v_mfma_f32_16x16x32_bf16 v[60:63], v[156:159], v[192:195], v[60:63]
	v_mfma_f32_16x16x32_bf16 v[56:59], v[164:167], v[192:195], v[56:59]
	v_mfma_f32_16x16x32_bf16 v[44:47], v[156:159], v[200:203], v[44:47]
	v_mfma_f32_16x16x32_bf16 v[40:43], v[164:167], v[200:203], v[40:43]
	v_mfma_f32_16x16x32_bf16 v[28:31], v[156:159], v[208:211], v[28:31]
	v_mfma_f32_16x16x32_bf16 v[24:27], v[164:167], v[208:211], v[24:27]
	v_mfma_f32_16x16x32_bf16 v[12:15], v[156:159], v[216:219], v[12:15]
	v_mfma_f32_16x16x32_bf16 v[8:11], v[164:167], v[216:219], v[8:11]
	s_setprio 0
	s_setprio 1
	v_mfma_f32_16x16x32_bf16 v[52:55], v[168:171], v[184:187], 0
	v_mfma_f32_16x16x32_bf16 v[48:51], v[176:179], v[184:187], 0
	v_mfma_f32_16x16x32_bf16 v[36:39], v[168:171], v[196:199], 0
	v_mfma_f32_16x16x32_bf16 v[32:35], v[176:179], v[196:199], 0
	v_mfma_f32_16x16x32_bf16 v[20:23], v[168:171], v[204:207], 0
	v_mfma_f32_16x16x32_bf16 v[16:19], v[176:179], v[204:207], 0
	v_mfma_f32_16x16x32_bf16 v[4:7], v[168:171], v[212:215], 0
	v_mfma_f32_16x16x32_bf16 v[0:3], v[176:179], v[212:215], 0
	v_mfma_f32_16x16x32_bf16 v[52:55], v[172:175], v[192:195], v[52:55]
	v_mfma_f32_16x16x32_bf16 v[48:51], v[180:183], v[192:195], v[48:51]
	v_mfma_f32_16x16x32_bf16 v[36:39], v[172:175], v[200:203], v[36:39]
	v_mfma_f32_16x16x32_bf16 v[32:35], v[180:183], v[200:203], v[32:35]
	v_mfma_f32_16x16x32_bf16 v[20:23], v[172:175], v[208:211], v[20:23]
	v_mfma_f32_16x16x32_bf16 v[16:19], v[180:183], v[208:211], v[16:19]
	v_mfma_f32_16x16x32_bf16 v[4:7], v[172:175], v[216:219], v[4:7]
	v_mfma_f32_16x16x32_bf16 v[0:3], v[180:183], v[216:219], v[0:3]
	s_setprio 0
	s_barrier
	s_add_i32 s79, 0, 0x18000
	s_add_i32 s80, 0, 0x1c000
	v_add_u32_e32 v164, s79, v147
	v_add_u32_e32 v180, s80, v147
	ds_read_b128 v[152:155], v164
	ds_read_b128 v[156:159], v164 offset:1024
	ds_read_b128 v[160:163], v164 offset:2048
	ds_read_b128 v[164:167], v164 offset:3072
	ds_read_b128 v[168:171], v180
	ds_read_b128 v[172:175], v180 offset:1024
	ds_read_b128 v[176:179], v180 offset:2048
	ds_read_b128 v[180:183], v180 offset:3072
	s_add_u32 s42, s42, 0x40000
	s_addc_u32 s43, s43, 0
	s_mov_b32 m0, s65
	ds_read_b128 v[184:187], v151 offset:32768
	ds_read_b128 v[192:195], v151 offset:33792
	ds_read_b128 v[196:199], v151 offset:34816
	ds_read_b128 v[200:203], v151 offset:35840
	ds_read_b128 v[204:207], v151 offset:36864
	ds_read_b128 v[208:211], v151 offset:37888
	ds_read_b128 v[212:215], v151 offset:38912
	ds_read_b128 v[216:219], v151 offset:39936
	global_load_lds_dwordx4 v128, s[42:43]
	s_mov_b32 m0, s66
	s_nop 0
	global_load_lds_dwordx4 v132, s[42:43]
	s_waitcnt vmcnt(8)
	s_waitcnt lgkmcnt(0)
	s_barrier
	s_setprio 1
	s_waitcnt lgkmcnt(0)
	v_mfma_f32_16x16x32_bf16 v[124:127], v[152:155], v[184:187], v[124:127]
	v_mfma_f32_16x16x32_bf16 v[120:123], v[160:163], v[184:187], v[120:123]
	v_mfma_f32_16x16x32_bf16 v[108:111], v[152:155], v[196:199], v[108:111]
	v_mfma_f32_16x16x32_bf16 v[104:107], v[160:163], v[196:199], v[104:107]
	v_mfma_f32_16x16x32_bf16 v[92:95], v[152:155], v[204:207], v[92:95]
	v_mfma_f32_16x16x32_bf16 v[88:91], v[160:163], v[204:207], v[88:91]
	v_mfma_f32_16x16x32_bf16 v[76:79], v[152:155], v[212:215], v[76:79]
	v_mfma_f32_16x16x32_bf16 v[72:75], v[160:163], v[212:215], v[72:75]
	v_mfma_f32_16x16x32_bf16 v[124:127], v[156:159], v[192:195], v[124:127]
	v_mfma_f32_16x16x32_bf16 v[120:123], v[164:167], v[192:195], v[120:123]
	v_mfma_f32_16x16x32_bf16 v[108:111], v[156:159], v[200:203], v[108:111]
	v_mfma_f32_16x16x32_bf16 v[104:107], v[164:167], v[200:203], v[104:107]
	v_mfma_f32_16x16x32_bf16 v[92:95], v[156:159], v[208:211], v[92:95]
	v_mfma_f32_16x16x32_bf16 v[88:91], v[164:167], v[208:211], v[88:91]
	v_mfma_f32_16x16x32_bf16 v[76:79], v[156:159], v[216:219], v[76:79]
	v_mfma_f32_16x16x32_bf16 v[72:75], v[164:167], v[216:219], v[72:75]
	s_setprio 0
	s_setprio 1
	v_mfma_f32_16x16x32_bf16 v[116:119], v[168:171], v[184:187], v[116:119]
	v_mfma_f32_16x16x32_bf16 v[112:115], v[176:179], v[184:187], v[112:115]
	v_mfma_f32_16x16x32_bf16 v[100:103], v[168:171], v[196:199], v[100:103]
	v_mfma_f32_16x16x32_bf16 v[96:99], v[176:179], v[196:199], v[96:99]
	v_mfma_f32_16x16x32_bf16 v[84:87], v[168:171], v[204:207], v[84:87]
	v_mfma_f32_16x16x32_bf16 v[80:83], v[176:179], v[204:207], v[80:83]
	v_mfma_f32_16x16x32_bf16 v[68:71], v[168:171], v[212:215], v[68:71]
	v_mfma_f32_16x16x32_bf16 v[64:67], v[176:179], v[212:215], v[64:67]
	v_mfma_f32_16x16x32_bf16 v[116:119], v[172:175], v[192:195], v[116:119]
	v_mfma_f32_16x16x32_bf16 v[112:115], v[180:183], v[192:195], v[112:115]
	v_mfma_f32_16x16x32_bf16 v[100:103], v[172:175], v[200:203], v[100:103]
	v_mfma_f32_16x16x32_bf16 v[96:99], v[180:183], v[200:203], v[96:99]
	v_mfma_f32_16x16x32_bf16 v[84:87], v[172:175], v[208:211], v[84:87]
	v_mfma_f32_16x16x32_bf16 v[80:83], v[180:183], v[208:211], v[80:83]
	v_mfma_f32_16x16x32_bf16 v[68:71], v[172:175], v[216:219], v[68:71]
	v_mfma_f32_16x16x32_bf16 v[64:67], v[180:183], v[216:219], v[64:67]
	s_setprio 0
	s_barrier
	s_add_i32 s42, s79, s63
	v_lshl_add_u64 v[144:145], v[144:145], 0, s[10:11]
	s_mov_b32 m0, s42
	ds_read_b128 v[184:187], v151 offset:49152
	ds_read_b128 v[192:195], v151 offset:50176
	ds_read_b128 v[196:199], v151 offset:51200
	ds_read_b128 v[200:203], v151 offset:52224
	ds_read_b128 v[204:207], v151 offset:53248
	ds_read_b128 v[208:211], v151 offset:54272
	ds_read_b128 v[212:215], v151 offset:55296
	ds_read_b128 v[216:219], v151 offset:56320
	global_load_lds_dwordx4 v[144:145], off
	s_add_i32 m0, s42, 0x2000
	s_add_u32 s40, s40, 0x40080
	v_lshl_add_u64 v[144:145], v[188:189], 0, s[10:11]
	s_addc_u32 s41, s41, 0
	s_add_i32 s42, s80, s63
	global_load_lds_dwordx4 v[144:145], off
	s_mov_b32 m0, s42
	s_nop 0
	global_load_lds_dwordx4 v130, s[40:41]
	s_add_i32 m0, s42, 0x2000
	s_nop 0
	global_load_lds_dwordx4 v134, s[40:41]
	v_lshl_add_u64 v[144:145], v[220:221], 0, s[10:11]
	s_mov_b32 m0, s52
	s_nop 0
	global_load_lds_dwordx4 v[144:145], off
	v_lshl_add_u64 v[144:145], v[222:223], 0, s[10:11]
	s_mov_b32 m0, s53
	s_nop 0
	global_load_lds_dwordx4 v[144:145], off
	s_waitcnt vmcnt(8)
	s_waitcnt lgkmcnt(0)
	s_barrier
	s_setprio 1
	s_waitcnt lgkmcnt(0)
	v_mfma_f32_16x16x32_bf16 v[60:63], v[152:155], v[184:187], v[60:63]
	v_mfma_f32_16x16x32_bf16 v[56:59], v[160:163], v[184:187], v[56:59]
	v_mfma_f32_16x16x32_bf16 v[44:47], v[152:155], v[196:199], v[44:47]
	v_mfma_f32_16x16x32_bf16 v[40:43], v[160:163], v[196:199], v[40:43]
	v_mfma_f32_16x16x32_bf16 v[28:31], v[152:155], v[204:207], v[28:31]
	v_mfma_f32_16x16x32_bf16 v[24:27], v[160:163], v[204:207], v[24:27]
	v_mfma_f32_16x16x32_bf16 v[12:15], v[152:155], v[212:215], v[12:15]
	v_mfma_f32_16x16x32_bf16 v[8:11], v[160:163], v[212:215], v[8:11]
	v_mfma_f32_16x16x32_bf16 v[60:63], v[156:159], v[192:195], v[60:63]
	v_mfma_f32_16x16x32_bf16 v[56:59], v[164:167], v[192:195], v[56:59]
	v_mfma_f32_16x16x32_bf16 v[44:47], v[156:159], v[200:203], v[44:47]
	v_mfma_f32_16x16x32_bf16 v[40:43], v[164:167], v[200:203], v[40:43]
	v_mfma_f32_16x16x32_bf16 v[28:31], v[156:159], v[208:211], v[28:31]
	v_mfma_f32_16x16x32_bf16 v[24:27], v[164:167], v[208:211], v[24:27]
	v_mfma_f32_16x16x32_bf16 v[12:15], v[156:159], v[216:219], v[12:15]
	v_mfma_f32_16x16x32_bf16 v[8:11], v[164:167], v[216:219], v[8:11]
	s_setprio 0
	s_setprio 1
	v_mfma_f32_16x16x32_bf16 v[52:55], v[168:171], v[184:187], v[52:55]
	v_mfma_f32_16x16x32_bf16 v[48:51], v[176:179], v[184:187], v[48:51]
	v_mfma_f32_16x16x32_bf16 v[36:39], v[168:171], v[196:199], v[36:39]
	v_mfma_f32_16x16x32_bf16 v[32:35], v[176:179], v[196:199], v[32:35]
	v_mfma_f32_16x16x32_bf16 v[20:23], v[168:171], v[204:207], v[20:23]
	v_mfma_f32_16x16x32_bf16 v[16:19], v[176:179], v[204:207], v[16:19]
	v_mfma_f32_16x16x32_bf16 v[4:7], v[168:171], v[212:215], v[4:7]
	v_mfma_f32_16x16x32_bf16 v[0:3], v[176:179], v[212:215], v[0:3]
	v_mfma_f32_16x16x32_bf16 v[52:55], v[172:175], v[192:195], v[52:55]
	v_mfma_f32_16x16x32_bf16 v[48:51], v[180:183], v[192:195], v[48:51]
	v_mfma_f32_16x16x32_bf16 v[36:39], v[172:175], v[200:203], v[36:39]
	v_mfma_f32_16x16x32_bf16 v[32:35], v[180:183], v[200:203], v[32:35]
	v_mfma_f32_16x16x32_bf16 v[20:23], v[172:175], v[208:211], v[20:23]
	v_mfma_f32_16x16x32_bf16 v[16:19], v[180:183], v[208:211], v[16:19]
	v_mfma_f32_16x16x32_bf16 v[4:7], v[172:175], v[216:219], v[4:7]
	v_mfma_f32_16x16x32_bf16 v[0:3], v[180:183], v[216:219], v[0:3]
	s_setprio 0
	s_barrier
	s_add_i32 s77, s77, 2
	s_add_u32 s34, s34, 0x100
	s_addc_u32 s35, s35, 0
	s_add_u32 s75, s75, 0x100
	s_addc_u32 s76, s76, 0
	s_cmp_gt_u32 s77, 13
	s_cbranch_scc0 .LBB0_837
	s_branch .Lpeel_exit3

.Lpeel_exit3:
	s_and_b64 vcc, exec, s[12:13]
	s_cbranch_vccz .LBB0_840
	s_barrier

.LBB0_915:
	s_ashr_i32 s25, s24, 31
	s_lshl_b64 s[26:27], s[24:25], 21
	s_add_u32 s26, s56, s26
	s_addc_u32 s27, s57, s27
	s_and_b64 s[28:29], s[4:5], exec
	s_cselect_b32 s25, s27, s35
	s_cselect_b32 s55, s26, s34
	s_ashr_i32 s23, s22, 31
	s_lshl_b64 s[28:29], s[22:23], 21
	s_add_u32 s28, s53, s28
	s_addc_u32 s29, s60, s29
	s_and_b64 s[42:43], s[4:5], exec
	s_cselect_b32 s23, s29, s41
	s_cselect_b32 s74, s28, s40
	s_add_u32 s34, s34, 0x100080
	s_addc_u32 s35, s35, 0
	s_add_u32 s75, s40, 0x100
	s_addc_u32 s76, s41, 0
	s_mov_b32 s77, -2
	ds_read_b128 v[152:155], v149
	ds_read_b128 v[156:159], v149 offset:1024
	ds_read_b128 v[160:163], v149 offset:2048
	ds_read_b128 v[164:167], v149 offset:3072
	ds_read_b128 v[168:171], v150
	ds_read_b128 v[172:175], v150 offset:1024
	ds_read_b128 v[176:179], v150 offset:2048
	ds_read_b128 v[180:183], v150 offset:3072
	s_add_u32 s40, s34, 0xfff00080
	s_addc_u32 s41, s35, -1
	s_cmp_eq_u32 s77, 60
	s_cselect_b32 s43, s25, s41
	s_cselect_b32 s42, s55, s40
	s_cselect_b32 s41, s23, s76
	s_cselect_b32 s40, s74, s75
	s_add_i32 m0, s31, 0xc000
	ds_read_b128 v[184:187], v151
	ds_read_b128 v[192:195], v151 offset:1024
	ds_read_b128 v[196:199], v151 offset:2048
	ds_read_b128 v[200:203], v151 offset:3072
	ds_read_b128 v[204:207], v151 offset:4096
	ds_read_b128 v[208:211], v151 offset:5120
	ds_read_b128 v[212:215], v151 offset:6144
	ds_read_b128 v[216:219], v151 offset:7168
	global_load_lds_dwordx4 v136, s[34:35]
	s_add_i32 m0, s31, 0xe000
	s_nop 0
	global_load_lds_dwordx4 v138, s[34:35]
	s_waitcnt vmcnt(8)
	s_waitcnt lgkmcnt(0)
	s_barrier
	s_setprio 1
	s_waitcnt lgkmcnt(0)
	v_mfma_f32_16x16x32_bf16 v[124:127], v[152:155], v[184:187], 0
	v_mfma_f32_16x16x32_bf16 v[120:123], v[160:163], v[184:187], 0
	v_mfma_f32_16x16x32_bf16 v[116:119], v[152:155], v[196:199], 0
	v_mfma_f32_16x16x32_bf16 v[108:111], v[160:163], v[196:199], 0
	v_mfma_f32_16x16x32_bf16 v[100:103], v[152:155], v[204:207], 0
	v_mfma_f32_16x16x32_bf16 v[92:95], v[160:163], v[204:207], 0
	v_mfma_f32_16x16x32_bf16 v[84:87], v[152:155], v[212:215], 0
	v_mfma_f32_16x16x32_bf16 v[76:79], v[160:163], v[212:215], 0
	v_mfma_f32_16x16x32_bf16 v[124:127], v[156:159], v[192:195], v[124:127]
	v_mfma_f32_16x16x32_bf16 v[120:123], v[164:167], v[192:195], v[120:123]
	v_mfma_f32_16x16x32_bf16 v[116:119], v[156:159], v[200:203], v[116:119]
	v_mfma_f32_16x16x32_bf16 v[108:111], v[164:167], v[200:203], v[108:111]
	v_mfma_f32_16x16x32_bf16 v[100:103], v[156:159], v[208:211], v[100:103]
	v_mfma_f32_16x16x32_bf16 v[92:95], v[164:167], v[208:211], v[92:95]
	v_mfma_f32_16x16x32_bf16 v[84:87], v[156:159], v[216:219], v[84:87]
	v_mfma_f32_16x16x32_bf16 v[76:79], v[164:167], v[216:219], v[76:79]
	s_setprio 0
	s_setprio 1
	v_mfma_f32_16x16x32_bf16 v[112:115], v[168:171], v[184:187], 0
	v_mfma_f32_16x16x32_bf16 v[104:107], v[176:179], v[184:187], 0
	v_mfma_f32_16x16x32_bf16 v[96:99], v[168:171], v[196:199], 0
	v_mfma_f32_16x16x32_bf16 v[88:91], v[176:179], v[196:199], 0
	v_mfma_f32_16x16x32_bf16 v[80:83], v[168:171], v[204:207], 0
	v_mfma_f32_16x16x32_bf16 v[72:75], v[176:179], v[204:207], 0
	v_mfma_f32_16x16x32_bf16 v[68:71], v[168:171], v[212:215], 0
	v_mfma_f32_16x16x32_bf16 v[64:67], v[176:179], v[212:215], 0
	v_mfma_f32_16x16x32_bf16 v[112:115], v[172:175], v[192:195], v[112:115]
	v_mfma_f32_16x16x32_bf16 v[104:107], v[180:183], v[192:195], v[104:107]
	v_mfma_f32_16x16x32_bf16 v[96:99], v[172:175], v[200:203], v[96:99]
	v_mfma_f32_16x16x32_bf16 v[88:91], v[180:183], v[200:203], v[88:91]
	v_mfma_f32_16x16x32_bf16 v[80:83], v[172:175], v[208:211], v[80:83]
	v_mfma_f32_16x16x32_bf16 v[72:75], v[180:183], v[208:211], v[72:75]
	v_mfma_f32_16x16x32_bf16 v[68:71], v[172:175], v[216:219], v[68:71]
	v_mfma_f32_16x16x32_bf16 v[64:67], v[180:183], v[216:219], v[64:67]
	s_setprio 0
	s_barrier
	s_add_i32 s79, s68, s61
	v_lshl_add_u64 v[144:145], s[40:41], 0, v[130:131]
	s_mov_b32 m0, s79
	ds_read_b128 v[184:187], v151 offset:16384
	ds_read_b128 v[192:195], v151 offset:17408
	ds_read_b128 v[196:199], v151 offset:18432
	ds_read_b128 v[200:203], v151 offset:19456
	ds_read_b128 v[204:207], v151 offset:20480
	ds_read_b128 v[208:211], v151 offset:21504
	ds_read_b128 v[212:215], v151 offset:22528
	ds_read_b128 v[216:219], v151 offset:23552
	global_load_lds_dwordx4 v[144:145], off
	s_add_i32 m0, s79, 0x2000
	s_add_u32 s80, s40, 0x100000
	v_lshl_add_u64 v[188:189], s[40:41], 0, v[134:135]
	s_addc_u32 s81, s41, 0
	s_add_i32 s79, s69, s61
	global_load_lds_dwordx4 v[188:189], off
	s_mov_b32 m0, s79
	v_lshl_add_u64 v[222:223], s[42:43], 0, v[132:133]
	global_load_lds_dwordx4 v130, s[80:81]
	s_add_i32 m0, s79, 0x2000
	s_nop 0
	global_load_lds_dwordx4 v134, s[80:81]
	v_lshl_add_u64 v[220:221], s[42:43], 0, v[128:129]
	s_mov_b32 m0, s31
	s_nop 0
	global_load_lds_dwordx4 v[220:221], off
	s_mov_b32 m0, s33
	s_nop 0
	global_load_lds_dwordx4 v[222:223], off
	s_waitcnt vmcnt(8)
	s_waitcnt lgkmcnt(0)
	s_barrier
	s_setprio 1
	s_waitcnt lgkmcnt(0)
	v_mfma_f32_16x16x32_bf16 v[60:63], v[152:155], v[184:187], 0
	v_mfma_f32_16x16x32_bf16 v[56:59], v[160:163], v[184:187], 0
	v_mfma_f32_16x16x32_bf16 v[52:55], v[152:155], v[196:199], 0
	v_mfma_f32_16x16x32_bf16 v[44:47], v[160:163], v[196:199], 0
	v_mfma_f32_16x16x32_bf16 v[36:39], v[152:155], v[204:207], 0
	v_mfma_f32_16x16x32_bf16 v[28:31], v[160:163], v[204:207], 0
	v_mfma_f32_16x16x32_bf16 v[20:23], v[152:155], v[212:215], 0
	v_mfma_f32_16x16x32_bf16 v[12:15], v[160:163], v[212:215], 0
	v_mfma_f32_16x16x32_bf16 v[60:63], v[156:159], v[192:195], v[60:63]
	v_mfma_f32_16x16x32_bf16 v[56:59], v[164:167], v[192:195], v[56:59]
	v_mfma_f32_16x16x32_bf16 v[52:55], v[156:159], v[200:203], v[52:55]
	v_mfma_f32_16x16x32_bf16 v[44:47], v[164:167], v[200:203], v[44:47]
	v_mfma_f32_16x16x32_bf16 v[36:39], v[156:159], v[208:211], v[36:39]
	v_mfma_f32_16x16x32_bf16 v[28:31], v[164:167], v[208:211], v[28:31]
	v_mfma_f32_16x16x32_bf16 v[20:23], v[156:159], v[216:219], v[20:23]
	v_mfma_f32_16x16x32_bf16 v[12:15], v[164:167], v[216:219], v[12:15]
	s_setprio 0
	s_setprio 1
	v_mfma_f32_16x16x32_bf16 v[48:51], v[168:171], v[184:187], 0
	v_mfma_f32_16x16x32_bf16 v[40:43], v[176:179], v[184:187], 0
	v_mfma_f32_16x16x32_bf16 v[32:35], v[168:171], v[196:199], 0
	v_mfma_f32_16x16x32_bf16 v[24:27], v[176:179], v[196:199], 0
	v_mfma_f32_16x16x32_bf16 v[16:19], v[168:171], v[204:207], 0
	v_mfma_f32_16x16x32_bf16 v[8:11], v[176:179], v[204:207], 0
	v_mfma_f32_16x16x32_bf16 v[4:7], v[168:171], v[212:215], 0
	v_mfma_f32_16x16x32_bf16 v[0:3], v[176:179], v[212:215], 0
	v_mfma_f32_16x16x32_bf16 v[48:51], v[172:175], v[192:195], v[48:51]
	v_mfma_f32_16x16x32_bf16 v[40:43], v[180:183], v[192:195], v[40:43]
	v_mfma_f32_16x16x32_bf16 v[32:35], v[172:175], v[200:203], v[32:35]
	v_mfma_f32_16x16x32_bf16 v[24:27], v[180:183], v[200:203], v[24:27]
	v_mfma_f32_16x16x32_bf16 v[16:19], v[172:175], v[208:211], v[16:19]
	v_mfma_f32_16x16x32_bf16 v[8:11], v[180:183], v[208:211], v[8:11]
	v_mfma_f32_16x16x32_bf16 v[4:7], v[172:175], v[216:219], v[4:7]
	v_mfma_f32_16x16x32_bf16 v[0:3], v[180:183], v[216:219], v[0:3]
	s_setprio 0
	s_barrier
	s_add_i32 s79, 0, 0x18000
	s_add_i32 s80, 0, 0x1c000
	v_add_u32_e32 v164, s79, v147
	v_add_u32_e32 v180, s80, v147
	ds_read_b128 v[152:155], v164
	ds_read_b128 v[156:159], v164 offset:1024
	ds_read_b128 v[160:163], v164 offset:2048
	ds_read_b128 v[164:167], v164 offset:3072
	ds_read_b128 v[168:171], v180
	ds_read_b128 v[172:175], v180 offset:1024
	ds_read_b128 v[176:179], v180 offset:2048
	ds_read_b128 v[180:183], v180 offset:3072
	s_add_u32 s42, s42, 0x100000
	s_addc_u32 s43, s43, 0
	s_mov_b32 m0, s62
	ds_read_b128 v[184:187], v151 offset:32768
	ds_read_b128 v[192:195], v151 offset:33792
	ds_read_b128 v[196:199], v151 offset:34816
	ds_read_b128 v[200:203], v151 offset:35840
	ds_read_b128 v[204:207], v151 offset:36864
	ds_read_b128 v[208:211], v151 offset:37888
	ds_read_b128 v[212:215], v151 offset:38912
	ds_read_b128 v[216:219], v151 offset:39936
	global_load_lds_dwordx4 v128, s[42:43]
	s_mov_b32 m0, s63
	s_nop 0
	global_load_lds_dwordx4 v132, s[42:43]
	s_waitcnt vmcnt(8)
	s_waitcnt lgkmcnt(0)
	s_barrier
	s_setprio 1
	s_waitcnt lgkmcnt(0)
	v_mfma_f32_16x16x32_bf16 v[124:127], v[152:155], v[184:187], v[124:127]
	v_mfma_f32_16x16x32_bf16 v[120:123], v[160:163], v[184:187], v[120:123]
	v_mfma_f32_16x16x32_bf16 v[116:119], v[152:155], v[196:199], v[116:119]
	v_mfma_f32_16x16x32_bf16 v[108:111], v[160:163], v[196:199], v[108:111]
	v_mfma_f32_16x16x32_bf16 v[100:103], v[152:155], v[204:207], v[100:103]
	v_mfma_f32_16x16x32_bf16 v[92:95], v[160:163], v[204:207], v[92:95]
	v_mfma_f32_16x16x32_bf16 v[84:87], v[152:155], v[212:215], v[84:87]
	v_mfma_f32_16x16x32_bf16 v[76:79], v[160:163], v[212:215], v[76:79]
	v_mfma_f32_16x16x32_bf16 v[124:127], v[156:159], v[192:195], v[124:127]
	v_mfma_f32_16x16x32_bf16 v[120:123], v[164:167], v[192:195], v[120:123]
	v_mfma_f32_16x16x32_bf16 v[116:119], v[156:159], v[200:203], v[116:119]
	v_mfma_f32_16x16x32_bf16 v[108:111], v[164:167], v[200:203], v[108:111]
	v_mfma_f32_16x16x32_bf16 v[100:103], v[156:159], v[208:211], v[100:103]
	v_mfma_f32_16x16x32_bf16 v[92:95], v[164:167], v[208:211], v[92:95]
	v_mfma_f32_16x16x32_bf16 v[84:87], v[156:159], v[216:219], v[84:87]
	v_mfma_f32_16x16x32_bf16 v[76:79], v[164:167], v[216:219], v[76:79]
	s_setprio 0
	s_setprio 1
	v_mfma_f32_16x16x32_bf16 v[112:115], v[168:171], v[184:187], v[112:115]
	v_mfma_f32_16x16x32_bf16 v[104:107], v[176:179], v[184:187], v[104:107]
	v_mfma_f32_16x16x32_bf16 v[96:99], v[168:171], v[196:199], v[96:99]
	v_mfma_f32_16x16x32_bf16 v[88:91], v[176:179], v[196:199], v[88:91]
	v_mfma_f32_16x16x32_bf16 v[80:83], v[168:171], v[204:207], v[80:83]
	v_mfma_f32_16x16x32_bf16 v[72:75], v[176:179], v[204:207], v[72:75]
	v_mfma_f32_16x16x32_bf16 v[68:71], v[168:171], v[212:215], v[68:71]
	v_mfma_f32_16x16x32_bf16 v[64:67], v[176:179], v[212:215], v[64:67]
	v_mfma_f32_16x16x32_bf16 v[112:115], v[172:175], v[192:195], v[112:115]
	v_mfma_f32_16x16x32_bf16 v[104:107], v[180:183], v[192:195], v[104:107]
	v_mfma_f32_16x16x32_bf16 v[96:99], v[172:175], v[200:203], v[96:99]
	v_mfma_f32_16x16x32_bf16 v[88:91], v[180:183], v[200:203], v[88:91]
	v_mfma_f32_16x16x32_bf16 v[80:83], v[172:175], v[208:211], v[80:83]
	v_mfma_f32_16x16x32_bf16 v[72:75], v[180:183], v[208:211], v[72:75]
	v_mfma_f32_16x16x32_bf16 v[68:71], v[172:175], v[216:219], v[68:71]
	v_mfma_f32_16x16x32_bf16 v[64:67], v[180:183], v[216:219], v[64:67]
	s_setprio 0
	s_barrier
	s_add_i32 s42, s79, s61
	v_lshl_add_u64 v[144:145], v[144:145], 0, s[10:11]
	s_mov_b32 m0, s42
	ds_read_b128 v[184:187], v151 offset:49152
	ds_read_b128 v[192:195], v151 offset:50176
	ds_read_b128 v[196:199], v151 offset:51200
	ds_read_b128 v[200:203], v151 offset:52224
	ds_read_b128 v[204:207], v151 offset:53248
	ds_read_b128 v[208:211], v151 offset:54272
	ds_read_b128 v[212:215], v151 offset:55296
	ds_read_b128 v[216:219], v151 offset:56320
	global_load_lds_dwordx4 v[144:145], off
	s_add_i32 m0, s42, 0x2000
	s_add_u32 s40, s40, 0x100080
	v_lshl_add_u64 v[144:145], v[188:189], 0, s[10:11]
	s_addc_u32 s41, s41, 0
	s_add_i32 s42, s80, s61
	global_load_lds_dwordx4 v[144:145], off
	s_mov_b32 m0, s42
	s_nop 0
	global_load_lds_dwordx4 v130, s[40:41]
	s_add_i32 m0, s42, 0x2000
	s_nop 0
	global_load_lds_dwordx4 v134, s[40:41]
	v_lshl_add_u64 v[144:145], v[220:221], 0, s[10:11]
	s_mov_b32 m0, s65
	s_nop 0
	global_load_lds_dwordx4 v[144:145], off
	v_lshl_add_u64 v[144:145], v[222:223], 0, s[10:11]
	s_mov_b32 m0, s66
	s_nop 0
	global_load_lds_dwordx4 v[144:145], off
	s_waitcnt vmcnt(8)
	s_waitcnt lgkmcnt(0)
	s_barrier
	s_setprio 1
	s_waitcnt lgkmcnt(0)
	v_mfma_f32_16x16x32_bf16 v[60:63], v[152:155], v[184:187], v[60:63]
	v_mfma_f32_16x16x32_bf16 v[56:59], v[160:163], v[184:187], v[56:59]
	v_mfma_f32_16x16x32_bf16 v[52:55], v[152:155], v[196:199], v[52:55]
	v_mfma_f32_16x16x32_bf16 v[44:47], v[160:163], v[196:199], v[44:47]
	v_mfma_f32_16x16x32_bf16 v[36:39], v[152:155], v[204:207], v[36:39]
	v_mfma_f32_16x16x32_bf16 v[28:31], v[160:163], v[204:207], v[28:31]
	v_mfma_f32_16x16x32_bf16 v[20:23], v[152:155], v[212:215], v[20:23]
	v_mfma_f32_16x16x32_bf16 v[12:15], v[160:163], v[212:215], v[12:15]
	v_mfma_f32_16x16x32_bf16 v[60:63], v[156:159], v[192:195], v[60:63]
	v_mfma_f32_16x16x32_bf16 v[56:59], v[164:167], v[192:195], v[56:59]
	v_mfma_f32_16x16x32_bf16 v[52:55], v[156:159], v[200:203], v[52:55]
	v_mfma_f32_16x16x32_bf16 v[44:47], v[164:167], v[200:203], v[44:47]
	v_mfma_f32_16x16x32_bf16 v[36:39], v[156:159], v[208:211], v[36:39]
	v_mfma_f32_16x16x32_bf16 v[28:31], v[164:167], v[208:211], v[28:31]
	v_mfma_f32_16x16x32_bf16 v[20:23], v[156:159], v[216:219], v[20:23]
	v_mfma_f32_16x16x32_bf16 v[12:15], v[164:167], v[216:219], v[12:15]
	s_setprio 0
	s_setprio 1
	v_mfma_f32_16x16x32_bf16 v[48:51], v[168:171], v[184:187], v[48:51]
	v_mfma_f32_16x16x32_bf16 v[40:43], v[176:179], v[184:187], v[40:43]
	v_mfma_f32_16x16x32_bf16 v[32:35], v[168:171], v[196:199], v[32:35]
	v_mfma_f32_16x16x32_bf16 v[24:27], v[176:179], v[196:199], v[24:27]
	v_mfma_f32_16x16x32_bf16 v[16:19], v[168:171], v[204:207], v[16:19]
	v_mfma_f32_16x16x32_bf16 v[8:11], v[176:179], v[204:207], v[8:11]
	v_mfma_f32_16x16x32_bf16 v[4:7], v[168:171], v[212:215], v[4:7]
	v_mfma_f32_16x16x32_bf16 v[0:3], v[176:179], v[212:215], v[0:3]
	v_mfma_f32_16x16x32_bf16 v[48:51], v[172:175], v[192:195], v[48:51]
	v_mfma_f32_16x16x32_bf16 v[40:43], v[180:183], v[192:195], v[40:43]
	v_mfma_f32_16x16x32_bf16 v[32:35], v[172:175], v[200:203], v[32:35]
	v_mfma_f32_16x16x32_bf16 v[24:27], v[180:183], v[200:203], v[24:27]
	v_mfma_f32_16x16x32_bf16 v[16:19], v[172:175], v[208:211], v[16:19]
	v_mfma_f32_16x16x32_bf16 v[8:11], v[180:183], v[208:211], v[8:11]
	v_mfma_f32_16x16x32_bf16 v[4:7], v[172:175], v[216:219], v[4:7]
	v_mfma_f32_16x16x32_bf16 v[0:3], v[180:183], v[216:219], v[0:3]
	s_setprio 0
	s_barrier
	s_add_i32 s77, s77, 2
	s_add_u32 s34, s34, 0x100
	s_addc_u32 s35, s35, 0
	s_add_u32 s75, s75, 0x100
	s_addc_u32 s76, s76, 0
	s_cmp_gt_u32 s77, 61
	s_cbranch_scc0 .LBB0_916
	s_branch .Lpeel_exit4

.LBB0_1052:
	s_ashr_i32 s27, s26, 31
	s_lshl_b64 s[28:29], s[26:27], 19
	s_add_u32 s28, s58, s28
	s_addc_u32 s29, s59, s29
	s_and_b64 s[30:31], s[4:5], exec
	s_cselect_b32 s27, s29, s43
	s_cselect_b32 s55, s28, s42
	s_ashr_i32 s25, s24, 31
	s_lshl_b64 s[30:31], s[24:25], 19
	s_add_u32 s30, s53, s30
	s_addc_u32 s31, s64, s31
	s_and_b64 s[62:63], s[4:5], exec
	s_cselect_b32 s25, s31, s61
	s_cselect_b32 s79, s30, s60
	s_add_u32 s42, s42, 0x40080
	s_addc_u32 s43, s43, 0
	s_add_u32 s80, s60, 0x100
	s_addc_u32 s81, s61, 0
	s_mov_b32 s82, -2
	ds_read_b128 v[152:155], v149
	ds_read_b128 v[156:159], v149 offset:1024
	ds_read_b128 v[160:163], v149 offset:2048
	ds_read_b128 v[164:167], v149 offset:3072
	ds_read_b128 v[168:171], v150
	ds_read_b128 v[172:175], v150 offset:1024
	ds_read_b128 v[176:179], v150 offset:2048
	ds_read_b128 v[180:183], v150 offset:3072
	s_add_u32 s60, s42, 0xfffc0080
	s_addc_u32 s61, s43, -1
	s_cmp_eq_u32 s82, 12
	s_cselect_b32 s63, s27, s61
	s_cselect_b32 s62, s55, s60
	s_cselect_b32 s61, s25, s81
	s_cselect_b32 s60, s79, s80
	s_add_i32 m0, s35, 0xc000
	ds_read_b128 v[184:187], v151
	ds_read_b128 v[192:195], v151 offset:1024
	ds_read_b128 v[196:199], v151 offset:2048
	ds_read_b128 v[200:203], v151 offset:3072
	ds_read_b128 v[204:207], v151 offset:4096
	ds_read_b128 v[208:211], v151 offset:5120
	ds_read_b128 v[212:215], v151 offset:6144
	ds_read_b128 v[216:219], v151 offset:7168
	global_load_lds_dwordx4 v136, s[42:43]
	s_add_i32 m0, s35, 0xe000
	s_nop 0
	global_load_lds_dwordx4 v138, s[42:43]
	s_waitcnt vmcnt(8)
	s_waitcnt lgkmcnt(0)
	s_barrier
	s_setprio 1
	s_waitcnt lgkmcnt(0)
	v_mfma_f32_16x16x32_bf16 v[124:127], v[152:155], v[184:187], 0
	v_mfma_f32_16x16x32_bf16 v[120:123], v[160:163], v[184:187], 0
	v_mfma_f32_16x16x32_bf16 v[116:119], v[152:155], v[196:199], 0
	v_mfma_f32_16x16x32_bf16 v[108:111], v[160:163], v[196:199], 0
	v_mfma_f32_16x16x32_bf16 v[100:103], v[152:155], v[204:207], 0
	v_mfma_f32_16x16x32_bf16 v[92:95], v[160:163], v[204:207], 0
	v_mfma_f32_16x16x32_bf16 v[84:87], v[152:155], v[212:215], 0
	v_mfma_f32_16x16x32_bf16 v[76:79], v[160:163], v[212:215], 0
	v_mfma_f32_16x16x32_bf16 v[124:127], v[156:159], v[192:195], v[124:127]
	v_mfma_f32_16x16x32_bf16 v[120:123], v[164:167], v[192:195], v[120:123]
	v_mfma_f32_16x16x32_bf16 v[116:119], v[156:159], v[200:203], v[116:119]
	v_mfma_f32_16x16x32_bf16 v[108:111], v[164:167], v[200:203], v[108:111]
	v_mfma_f32_16x16x32_bf16 v[100:103], v[156:159], v[208:211], v[100:103]
	v_mfma_f32_16x16x32_bf16 v[92:95], v[164:167], v[208:211], v[92:95]
	v_mfma_f32_16x16x32_bf16 v[84:87], v[156:159], v[216:219], v[84:87]
	v_mfma_f32_16x16x32_bf16 v[76:79], v[164:167], v[216:219], v[76:79]
	s_setprio 0
	s_setprio 1
	v_mfma_f32_16x16x32_bf16 v[112:115], v[168:171], v[184:187], 0
	v_mfma_f32_16x16x32_bf16 v[104:107], v[176:179], v[184:187], 0
	v_mfma_f32_16x16x32_bf16 v[96:99], v[168:171], v[196:199], 0
	v_mfma_f32_16x16x32_bf16 v[88:91], v[176:179], v[196:199], 0
	v_mfma_f32_16x16x32_bf16 v[80:83], v[168:171], v[204:207], 0
	v_mfma_f32_16x16x32_bf16 v[72:75], v[176:179], v[204:207], 0
	v_mfma_f32_16x16x32_bf16 v[68:71], v[168:171], v[212:215], 0
	v_mfma_f32_16x16x32_bf16 v[64:67], v[176:179], v[212:215], 0
	v_mfma_f32_16x16x32_bf16 v[112:115], v[172:175], v[192:195], v[112:115]
	v_mfma_f32_16x16x32_bf16 v[104:107], v[180:183], v[192:195], v[104:107]
	v_mfma_f32_16x16x32_bf16 v[96:99], v[172:175], v[200:203], v[96:99]
	v_mfma_f32_16x16x32_bf16 v[88:91], v[180:183], v[200:203], v[88:91]
	v_mfma_f32_16x16x32_bf16 v[80:83], v[172:175], v[208:211], v[80:83]
	v_mfma_f32_16x16x32_bf16 v[72:75], v[180:183], v[208:211], v[72:75]
	v_mfma_f32_16x16x32_bf16 v[68:71], v[172:175], v[216:219], v[68:71]
	v_mfma_f32_16x16x32_bf16 v[64:67], v[180:183], v[216:219], v[64:67]
	s_setprio 0
	s_barrier
	s_add_i32 s83, s72, s65
	v_lshl_add_u64 v[144:145], s[60:61], 0, v[130:131]
	s_mov_b32 m0, s83
	ds_read_b128 v[184:187], v151 offset:16384
	ds_read_b128 v[192:195], v151 offset:17408
	ds_read_b128 v[196:199], v151 offset:18432
	ds_read_b128 v[200:203], v151 offset:19456
	ds_read_b128 v[204:207], v151 offset:20480
	ds_read_b128 v[208:211], v151 offset:21504
	ds_read_b128 v[212:215], v151 offset:22528
	ds_read_b128 v[216:219], v151 offset:23552
	global_load_lds_dwordx4 v[144:145], off
	s_add_i32 m0, s83, 0x2000
	s_add_u32 s84, s60, 0x40000
	v_lshl_add_u64 v[188:189], s[60:61], 0, v[134:135]
	s_addc_u32 s85, s61, 0
	s_add_i32 s83, s73, s65
	global_load_lds_dwordx4 v[188:189], off
	s_mov_b32 m0, s83
	v_lshl_add_u64 v[222:223], s[62:63], 0, v[132:133]
	global_load_lds_dwordx4 v130, s[84:85]
	s_add_i32 m0, s83, 0x2000
	s_nop 0
	global_load_lds_dwordx4 v134, s[84:85]
	v_lshl_add_u64 v[220:221], s[62:63], 0, v[128:129]
	s_mov_b32 m0, s35
	s_nop 0
	global_load_lds_dwordx4 v[220:221], off
	s_mov_b32 m0, s33
	s_nop 0
	global_load_lds_dwordx4 v[222:223], off
	s_waitcnt vmcnt(8)
	s_waitcnt lgkmcnt(0)
	s_barrier
	s_setprio 1
	s_waitcnt lgkmcnt(0)
	v_mfma_f32_16x16x32_bf16 v[60:63], v[152:155], v[184:187], 0
	v_mfma_f32_16x16x32_bf16 v[56:59], v[160:163], v[184:187], 0
	v_mfma_f32_16x16x32_bf16 v[52:55], v[152:155], v[196:199], 0
	v_mfma_f32_16x16x32_bf16 v[44:47], v[160:163], v[196:199], 0
	v_mfma_f32_16x16x32_bf16 v[36:39], v[152:155], v[204:207], 0
	v_mfma_f32_16x16x32_bf16 v[28:31], v[160:163], v[204:207], 0
	v_mfma_f32_16x16x32_bf16 v[20:23], v[152:155], v[212:215], 0
	v_mfma_f32_16x16x32_bf16 v[12:15], v[160:163], v[212:215], 0
	v_mfma_f32_16x16x32_bf16 v[60:63], v[156:159], v[192:195], v[60:63]
	v_mfma_f32_16x16x32_bf16 v[56:59], v[164:167], v[192:195], v[56:59]
	v_mfma_f32_16x16x32_bf16 v[52:55], v[156:159], v[200:203], v[52:55]
	v_mfma_f32_16x16x32_bf16 v[44:47], v[164:167], v[200:203], v[44:47]
	v_mfma_f32_16x16x32_bf16 v[36:39], v[156:159], v[208:211], v[36:39]
	v_mfma_f32_16x16x32_bf16 v[28:31], v[164:167], v[208:211], v[28:31]
	v_mfma_f32_16x16x32_bf16 v[20:23], v[156:159], v[216:219], v[20:23]
	v_mfma_f32_16x16x32_bf16 v[12:15], v[164:167], v[216:219], v[12:15]
	s_setprio 0
	s_setprio 1
	v_mfma_f32_16x16x32_bf16 v[48:51], v[168:171], v[184:187], 0
	v_mfma_f32_16x16x32_bf16 v[40:43], v[176:179], v[184:187], 0
	v_mfma_f32_16x16x32_bf16 v[32:35], v[168:171], v[196:199], 0
	v_mfma_f32_16x16x32_bf16 v[24:27], v[176:179], v[196:199], 0
	v_mfma_f32_16x16x32_bf16 v[16:19], v[168:171], v[204:207], 0
	v_mfma_f32_16x16x32_bf16 v[8:11], v[176:179], v[204:207], 0
	v_mfma_f32_16x16x32_bf16 v[4:7], v[168:171], v[212:215], 0
	v_mfma_f32_16x16x32_bf16 v[0:3], v[176:179], v[212:215], 0
	v_mfma_f32_16x16x32_bf16 v[48:51], v[172:175], v[192:195], v[48:51]
	v_mfma_f32_16x16x32_bf16 v[40:43], v[180:183], v[192:195], v[40:43]
	v_mfma_f32_16x16x32_bf16 v[32:35], v[172:175], v[200:203], v[32:35]
	v_mfma_f32_16x16x32_bf16 v[24:27], v[180:183], v[200:203], v[24:27]
	v_mfma_f32_16x16x32_bf16 v[16:19], v[172:175], v[208:211], v[16:19]
	v_mfma_f32_16x16x32_bf16 v[8:11], v[180:183], v[208:211], v[8:11]
	v_mfma_f32_16x16x32_bf16 v[4:7], v[172:175], v[216:219], v[4:7]
	v_mfma_f32_16x16x32_bf16 v[0:3], v[180:183], v[216:219], v[0:3]
	s_setprio 0
	s_barrier
	s_add_i32 s83, 0, 0x18000
	s_add_i32 s84, 0, 0x1c000
	v_add_u32_e32 v164, s83, v147
	v_add_u32_e32 v180, s84, v147
	ds_read_b128 v[152:155], v164
	ds_read_b128 v[156:159], v164 offset:1024
	ds_read_b128 v[160:163], v164 offset:2048
	ds_read_b128 v[164:167], v164 offset:3072
	ds_read_b128 v[168:171], v180
	ds_read_b128 v[172:175], v180 offset:1024
	ds_read_b128 v[176:179], v180 offset:2048
	ds_read_b128 v[180:183], v180 offset:3072
	s_add_u32 s62, s62, 0x40000
	s_addc_u32 s63, s63, 0
	s_mov_b32 m0, s66
	ds_read_b128 v[184:187], v151 offset:32768
	ds_read_b128 v[192:195], v151 offset:33792
	ds_read_b128 v[196:199], v151 offset:34816
	ds_read_b128 v[200:203], v151 offset:35840
	ds_read_b128 v[204:207], v151 offset:36864
	ds_read_b128 v[208:211], v151 offset:37888
	ds_read_b128 v[212:215], v151 offset:38912
	ds_read_b128 v[216:219], v151 offset:39936
	global_load_lds_dwordx4 v128, s[62:63]
	s_mov_b32 m0, s67
	s_nop 0
	global_load_lds_dwordx4 v132, s[62:63]
	s_waitcnt vmcnt(8)
	s_waitcnt lgkmcnt(0)
	s_barrier
	s_setprio 1
	s_waitcnt lgkmcnt(0)
	v_mfma_f32_16x16x32_bf16 v[124:127], v[152:155], v[184:187], v[124:127]
	v_mfma_f32_16x16x32_bf16 v[120:123], v[160:163], v[184:187], v[120:123]
	v_mfma_f32_16x16x32_bf16 v[116:119], v[152:155], v[196:199], v[116:119]
	v_mfma_f32_16x16x32_bf16 v[108:111], v[160:163], v[196:199], v[108:111]
	v_mfma_f32_16x16x32_bf16 v[100:103], v[152:155], v[204:207], v[100:103]
	v_mfma_f32_16x16x32_bf16 v[92:95], v[160:163], v[204:207], v[92:95]
	v_mfma_f32_16x16x32_bf16 v[84:87], v[152:155], v[212:215], v[84:87]
	v_mfma_f32_16x16x32_bf16 v[76:79], v[160:163], v[212:215], v[76:79]
	v_mfma_f32_16x16x32_bf16 v[124:127], v[156:159], v[192:195], v[124:127]
	v_mfma_f32_16x16x32_bf16 v[120:123], v[164:167], v[192:195], v[120:123]
	v_mfma_f32_16x16x32_bf16 v[116:119], v[156:159], v[200:203], v[116:119]
	v_mfma_f32_16x16x32_bf16 v[108:111], v[164:167], v[200:203], v[108:111]
	v_mfma_f32_16x16x32_bf16 v[100:103], v[156:159], v[208:211], v[100:103]
	v_mfma_f32_16x16x32_bf16 v[92:95], v[164:167], v[208:211], v[92:95]
	v_mfma_f32_16x16x32_bf16 v[84:87], v[156:159], v[216:219], v[84:87]
	v_mfma_f32_16x16x32_bf16 v[76:79], v[164:167], v[216:219], v[76:79]
	s_setprio 0
	s_setprio 1
	v_mfma_f32_16x16x32_bf16 v[112:115], v[168:171], v[184:187], v[112:115]
	v_mfma_f32_16x16x32_bf16 v[104:107], v[176:179], v[184:187], v[104:107]
	v_mfma_f32_16x16x32_bf16 v[96:99], v[168:171], v[196:199], v[96:99]
	v_mfma_f32_16x16x32_bf16 v[88:91], v[176:179], v[196:199], v[88:91]
	v_mfma_f32_16x16x32_bf16 v[80:83], v[168:171], v[204:207], v[80:83]
	v_mfma_f32_16x16x32_bf16 v[72:75], v[176:179], v[204:207], v[72:75]
	v_mfma_f32_16x16x32_bf16 v[68:71], v[168:171], v[212:215], v[68:71]
	v_mfma_f32_16x16x32_bf16 v[64:67], v[176:179], v[212:215], v[64:67]
	v_mfma_f32_16x16x32_bf16 v[112:115], v[172:175], v[192:195], v[112:115]
	v_mfma_f32_16x16x32_bf16 v[104:107], v[180:183], v[192:195], v[104:107]
	v_mfma_f32_16x16x32_bf16 v[96:99], v[172:175], v[200:203], v[96:99]
	v_mfma_f32_16x16x32_bf16 v[88:91], v[180:183], v[200:203], v[88:91]
	v_mfma_f32_16x16x32_bf16 v[80:83], v[172:175], v[208:211], v[80:83]
	v_mfma_f32_16x16x32_bf16 v[72:75], v[180:183], v[208:211], v[72:75]
	v_mfma_f32_16x16x32_bf16 v[68:71], v[172:175], v[216:219], v[68:71]
	v_mfma_f32_16x16x32_bf16 v[64:67], v[180:183], v[216:219], v[64:67]
	s_setprio 0
	s_barrier
	s_add_i32 s62, s83, s65
	v_lshl_add_u64 v[144:145], v[144:145], 0, s[12:13]
	s_mov_b32 m0, s62
	ds_read_b128 v[184:187], v151 offset:49152
	ds_read_b128 v[192:195], v151 offset:50176
	ds_read_b128 v[196:199], v151 offset:51200
	ds_read_b128 v[200:203], v151 offset:52224
	ds_read_b128 v[204:207], v151 offset:53248
	ds_read_b128 v[208:211], v151 offset:54272
	ds_read_b128 v[212:215], v151 offset:55296
	ds_read_b128 v[216:219], v151 offset:56320
	global_load_lds_dwordx4 v[144:145], off
	s_add_i32 m0, s62, 0x2000
	s_add_u32 s60, s60, 0x40080
	v_lshl_add_u64 v[144:145], v[188:189], 0, s[12:13]
	s_addc_u32 s61, s61, 0
	s_add_i32 s62, s84, s65
	global_load_lds_dwordx4 v[144:145], off
	s_mov_b32 m0, s62
	s_nop 0
	global_load_lds_dwordx4 v130, s[60:61]
	s_add_i32 m0, s62, 0x2000
	s_nop 0
	global_load_lds_dwordx4 v134, s[60:61]
	v_lshl_add_u64 v[144:145], v[220:221], 0, s[12:13]
	s_mov_b32 m0, s69
	s_nop 0
	global_load_lds_dwordx4 v[144:145], off
	v_lshl_add_u64 v[144:145], v[222:223], 0, s[12:13]
	s_mov_b32 m0, s70
	s_nop 0
	global_load_lds_dwordx4 v[144:145], off
	s_waitcnt vmcnt(8)
	s_waitcnt lgkmcnt(0)
	s_barrier
	s_setprio 1
	s_waitcnt lgkmcnt(0)
	v_mfma_f32_16x16x32_bf16 v[60:63], v[152:155], v[184:187], v[60:63]
	v_mfma_f32_16x16x32_bf16 v[56:59], v[160:163], v[184:187], v[56:59]
	v_mfma_f32_16x16x32_bf16 v[52:55], v[152:155], v[196:199], v[52:55]
	v_mfma_f32_16x16x32_bf16 v[44:47], v[160:163], v[196:199], v[44:47]
	v_mfma_f32_16x16x32_bf16 v[36:39], v[152:155], v[204:207], v[36:39]
	v_mfma_f32_16x16x32_bf16 v[28:31], v[160:163], v[204:207], v[28:31]
	v_mfma_f32_16x16x32_bf16 v[20:23], v[152:155], v[212:215], v[20:23]
	v_mfma_f32_16x16x32_bf16 v[12:15], v[160:163], v[212:215], v[12:15]
	v_mfma_f32_16x16x32_bf16 v[60:63], v[156:159], v[192:195], v[60:63]
	v_mfma_f32_16x16x32_bf16 v[56:59], v[164:167], v[192:195], v[56:59]
	v_mfma_f32_16x16x32_bf16 v[52:55], v[156:159], v[200:203], v[52:55]
	v_mfma_f32_16x16x32_bf16 v[44:47], v[164:167], v[200:203], v[44:47]
	v_mfma_f32_16x16x32_bf16 v[36:39], v[156:159], v[208:211], v[36:39]
	v_mfma_f32_16x16x32_bf16 v[28:31], v[164:167], v[208:211], v[28:31]
	v_mfma_f32_16x16x32_bf16 v[20:23], v[156:159], v[216:219], v[20:23]
	v_mfma_f32_16x16x32_bf16 v[12:15], v[164:167], v[216:219], v[12:15]
	s_setprio 0
	s_setprio 1
	v_mfma_f32_16x16x32_bf16 v[48:51], v[168:171], v[184:187], v[48:51]
	v_mfma_f32_16x16x32_bf16 v[40:43], v[176:179], v[184:187], v[40:43]
	v_mfma_f32_16x16x32_bf16 v[32:35], v[168:171], v[196:199], v[32:35]
	v_mfma_f32_16x16x32_bf16 v[24:27], v[176:179], v[196:199], v[24:27]
	v_mfma_f32_16x16x32_bf16 v[16:19], v[168:171], v[204:207], v[16:19]
	v_mfma_f32_16x16x32_bf16 v[8:11], v[176:179], v[204:207], v[8:11]
	v_mfma_f32_16x16x32_bf16 v[4:7], v[168:171], v[212:215], v[4:7]
	v_mfma_f32_16x16x32_bf16 v[0:3], v[176:179], v[212:215], v[0:3]
	v_mfma_f32_16x16x32_bf16 v[48:51], v[172:175], v[192:195], v[48:51]
	v_mfma_f32_16x16x32_bf16 v[40:43], v[180:183], v[192:195], v[40:43]
	v_mfma_f32_16x16x32_bf16 v[32:35], v[172:175], v[200:203], v[32:35]
	v_mfma_f32_16x16x32_bf16 v[24:27], v[180:183], v[200:203], v[24:27]
	v_mfma_f32_16x16x32_bf16 v[16:19], v[172:175], v[208:211], v[16:19]
	v_mfma_f32_16x16x32_bf16 v[8:11], v[180:183], v[208:211], v[8:11]
	v_mfma_f32_16x16x32_bf16 v[4:7], v[172:175], v[216:219], v[4:7]
	v_mfma_f32_16x16x32_bf16 v[0:3], v[180:183], v[216:219], v[0:3]
	s_setprio 0
	s_barrier
	s_add_i32 s82, s82, 2
	s_add_u32 s42, s42, 0x100
	s_addc_u32 s43, s43, 0
	s_add_u32 s80, s80, 0x100
	s_addc_u32 s81, s81, 0
	s_cmp_gt_u32 s82, 13
	s_cbranch_scc0 .LBB0_1053
	s_branch .Lpeel_exit5

.LBB0_1076:
	s_ashr_i32 s27, s26, 31
	s_lshl_b64 s[28:29], s[26:27], 19
	s_add_u32 s28, s40, s28
	s_addc_u32 s29, s41, s29
	s_and_b64 s[30:31], s[4:5], exec
	s_cselect_b32 s27, s29, s43
	s_cselect_b32 s55, s28, s42
	s_ashr_i32 s25, s24, 31
	s_lshl_b64 s[30:31], s[24:25], 19
	s_add_u32 s30, s53, s30
	s_addc_u32 s31, s64, s31
	s_and_b64 s[62:63], s[4:5], exec
	s_cselect_b32 s25, s31, s61
	s_cselect_b32 s79, s30, s60
	s_add_u32 s42, s42, 0x40080
	s_addc_u32 s43, s43, 0
	s_add_u32 s80, s60, 0x100
	s_addc_u32 s81, s61, 0
	s_mov_b32 s82, -2
	ds_read_b128 v[152:155], v149
	ds_read_b128 v[156:159], v149 offset:1024
	ds_read_b128 v[160:163], v149 offset:2048
	ds_read_b128 v[164:167], v149 offset:3072
	ds_read_b128 v[168:171], v150
	ds_read_b128 v[172:175], v150 offset:1024
	ds_read_b128 v[176:179], v150 offset:2048
	ds_read_b128 v[180:183], v150 offset:3072
	s_add_u32 s60, s42, 0xfffc0080
	s_addc_u32 s61, s43, -1
	s_cmp_eq_u32 s82, 12
	s_cselect_b32 s63, s27, s61
	s_cselect_b32 s62, s55, s60
	s_cselect_b32 s61, s25, s81
	s_cselect_b32 s60, s79, s80
	s_add_i32 m0, s35, 0xc000
	ds_read_b128 v[184:187], v151
	ds_read_b128 v[192:195], v151 offset:1024
	ds_read_b128 v[196:199], v151 offset:2048
	ds_read_b128 v[200:203], v151 offset:3072
	ds_read_b128 v[204:207], v151 offset:4096
	ds_read_b128 v[208:211], v151 offset:5120
	ds_read_b128 v[212:215], v151 offset:6144
	ds_read_b128 v[216:219], v151 offset:7168
	global_load_lds_dwordx4 v136, s[42:43]
	s_add_i32 m0, s35, 0xe000
	s_nop 0
	global_load_lds_dwordx4 v138, s[42:43]
	s_waitcnt vmcnt(8)
	s_waitcnt lgkmcnt(0)
	s_barrier
	s_setprio 1
	s_waitcnt lgkmcnt(0)
	v_mfma_f32_16x16x32_bf16 v[124:127], v[152:155], v[184:187], 0
	v_mfma_f32_16x16x32_bf16 v[120:123], v[160:163], v[184:187], 0
	v_mfma_f32_16x16x32_bf16 v[116:119], v[152:155], v[196:199], 0
	v_mfma_f32_16x16x32_bf16 v[108:111], v[160:163], v[196:199], 0
	v_mfma_f32_16x16x32_bf16 v[100:103], v[152:155], v[204:207], 0
	v_mfma_f32_16x16x32_bf16 v[92:95], v[160:163], v[204:207], 0
	v_mfma_f32_16x16x32_bf16 v[84:87], v[152:155], v[212:215], 0
	v_mfma_f32_16x16x32_bf16 v[76:79], v[160:163], v[212:215], 0
	v_mfma_f32_16x16x32_bf16 v[124:127], v[156:159], v[192:195], v[124:127]
	v_mfma_f32_16x16x32_bf16 v[120:123], v[164:167], v[192:195], v[120:123]
	v_mfma_f32_16x16x32_bf16 v[116:119], v[156:159], v[200:203], v[116:119]
	v_mfma_f32_16x16x32_bf16 v[108:111], v[164:167], v[200:203], v[108:111]
	v_mfma_f32_16x16x32_bf16 v[100:103], v[156:159], v[208:211], v[100:103]
	v_mfma_f32_16x16x32_bf16 v[92:95], v[164:167], v[208:211], v[92:95]
	v_mfma_f32_16x16x32_bf16 v[84:87], v[156:159], v[216:219], v[84:87]
	v_mfma_f32_16x16x32_bf16 v[76:79], v[164:167], v[216:219], v[76:79]
	s_setprio 0
	s_setprio 1
	v_mfma_f32_16x16x32_bf16 v[112:115], v[168:171], v[184:187], 0
	v_mfma_f32_16x16x32_bf16 v[104:107], v[176:179], v[184:187], 0
	v_mfma_f32_16x16x32_bf16 v[96:99], v[168:171], v[196:199], 0
	v_mfma_f32_16x16x32_bf16 v[88:91], v[176:179], v[196:199], 0
	v_mfma_f32_16x16x32_bf16 v[80:83], v[168:171], v[204:207], 0
	v_mfma_f32_16x16x32_bf16 v[72:75], v[176:179], v[204:207], 0
	v_mfma_f32_16x16x32_bf16 v[68:71], v[168:171], v[212:215], 0
	v_mfma_f32_16x16x32_bf16 v[64:67], v[176:179], v[212:215], 0
	v_mfma_f32_16x16x32_bf16 v[112:115], v[172:175], v[192:195], v[112:115]
	v_mfma_f32_16x16x32_bf16 v[104:107], v[180:183], v[192:195], v[104:107]
	v_mfma_f32_16x16x32_bf16 v[96:99], v[172:175], v[200:203], v[96:99]
	v_mfma_f32_16x16x32_bf16 v[88:91], v[180:183], v[200:203], v[88:91]
	v_mfma_f32_16x16x32_bf16 v[80:83], v[172:175], v[208:211], v[80:83]
	v_mfma_f32_16x16x32_bf16 v[72:75], v[180:183], v[208:211], v[72:75]
	v_mfma_f32_16x16x32_bf16 v[68:71], v[172:175], v[216:219], v[68:71]
	v_mfma_f32_16x16x32_bf16 v[64:67], v[180:183], v[216:219], v[64:67]
	s_setprio 0
	s_barrier
	s_add_i32 s83, s72, s65
	v_lshl_add_u64 v[144:145], s[60:61], 0, v[130:131]
	s_mov_b32 m0, s83
	ds_read_b128 v[184:187], v151 offset:16384
	ds_read_b128 v[192:195], v151 offset:17408
	ds_read_b128 v[196:199], v151 offset:18432
	ds_read_b128 v[200:203], v151 offset:19456
	ds_read_b128 v[204:207], v151 offset:20480
	ds_read_b128 v[208:211], v151 offset:21504
	ds_read_b128 v[212:215], v151 offset:22528
	ds_read_b128 v[216:219], v151 offset:23552
	global_load_lds_dwordx4 v[144:145], off
	s_add_i32 m0, s83, 0x2000
	s_add_u32 s84, s60, 0x40000
	v_lshl_add_u64 v[188:189], s[60:61], 0, v[134:135]
	s_addc_u32 s85, s61, 0
	s_add_i32 s83, s73, s65
	global_load_lds_dwordx4 v[188:189], off
	s_mov_b32 m0, s83
	v_lshl_add_u64 v[222:223], s[62:63], 0, v[132:133]
	global_load_lds_dwordx4 v130, s[84:85]
	s_add_i32 m0, s83, 0x2000
	s_nop 0
	global_load_lds_dwordx4 v134, s[84:85]
	v_lshl_add_u64 v[220:221], s[62:63], 0, v[128:129]
	s_mov_b32 m0, s35
	s_nop 0
	global_load_lds_dwordx4 v[220:221], off
	s_mov_b32 m0, s33
	s_nop 0
	global_load_lds_dwordx4 v[222:223], off
	s_waitcnt vmcnt(8)
	s_waitcnt lgkmcnt(0)
	s_barrier
	s_setprio 1
	s_waitcnt lgkmcnt(0)
	v_mfma_f32_16x16x32_bf16 v[60:63], v[152:155], v[184:187], 0
	v_mfma_f32_16x16x32_bf16 v[56:59], v[160:163], v[184:187], 0
	v_mfma_f32_16x16x32_bf16 v[52:55], v[152:155], v[196:199], 0
	v_mfma_f32_16x16x32_bf16 v[44:47], v[160:163], v[196:199], 0
	v_mfma_f32_16x16x32_bf16 v[36:39], v[152:155], v[204:207], 0
	v_mfma_f32_16x16x32_bf16 v[28:31], v[160:163], v[204:207], 0
	v_mfma_f32_16x16x32_bf16 v[20:23], v[152:155], v[212:215], 0
	v_mfma_f32_16x16x32_bf16 v[12:15], v[160:163], v[212:215], 0
	v_mfma_f32_16x16x32_bf16 v[60:63], v[156:159], v[192:195], v[60:63]
	v_mfma_f32_16x16x32_bf16 v[56:59], v[164:167], v[192:195], v[56:59]
	v_mfma_f32_16x16x32_bf16 v[52:55], v[156:159], v[200:203], v[52:55]
	v_mfma_f32_16x16x32_bf16 v[44:47], v[164:167], v[200:203], v[44:47]
	v_mfma_f32_16x16x32_bf16 v[36:39], v[156:159], v[208:211], v[36:39]
	v_mfma_f32_16x16x32_bf16 v[28:31], v[164:167], v[208:211], v[28:31]
	v_mfma_f32_16x16x32_bf16 v[20:23], v[156:159], v[216:219], v[20:23]
	v_mfma_f32_16x16x32_bf16 v[12:15], v[164:167], v[216:219], v[12:15]
	s_setprio 0
	s_setprio 1
	v_mfma_f32_16x16x32_bf16 v[48:51], v[168:171], v[184:187], 0
	v_mfma_f32_16x16x32_bf16 v[40:43], v[176:179], v[184:187], 0
	v_mfma_f32_16x16x32_bf16 v[32:35], v[168:171], v[196:199], 0
	v_mfma_f32_16x16x32_bf16 v[24:27], v[176:179], v[196:199], 0
	v_mfma_f32_16x16x32_bf16 v[16:19], v[168:171], v[204:207], 0
	v_mfma_f32_16x16x32_bf16 v[8:11], v[176:179], v[204:207], 0
	v_mfma_f32_16x16x32_bf16 v[4:7], v[168:171], v[212:215], 0
	v_mfma_f32_16x16x32_bf16 v[0:3], v[176:179], v[212:215], 0
	v_mfma_f32_16x16x32_bf16 v[48:51], v[172:175], v[192:195], v[48:51]
	v_mfma_f32_16x16x32_bf16 v[40:43], v[180:183], v[192:195], v[40:43]
	v_mfma_f32_16x16x32_bf16 v[32:35], v[172:175], v[200:203], v[32:35]
	v_mfma_f32_16x16x32_bf16 v[24:27], v[180:183], v[200:203], v[24:27]
	v_mfma_f32_16x16x32_bf16 v[16:19], v[172:175], v[208:211], v[16:19]
	v_mfma_f32_16x16x32_bf16 v[8:11], v[180:183], v[208:211], v[8:11]
	v_mfma_f32_16x16x32_bf16 v[4:7], v[172:175], v[216:219], v[4:7]
	v_mfma_f32_16x16x32_bf16 v[0:3], v[180:183], v[216:219], v[0:3]
	s_setprio 0
	s_barrier
	s_add_i32 s83, 0, 0x18000
	s_add_i32 s84, 0, 0x1c000
	v_add_u32_e32 v164, s83, v147
	v_add_u32_e32 v180, s84, v147
	ds_read_b128 v[152:155], v164
	ds_read_b128 v[156:159], v164 offset:1024
	ds_read_b128 v[160:163], v164 offset:2048
	ds_read_b128 v[164:167], v164 offset:3072
	ds_read_b128 v[168:171], v180
	ds_read_b128 v[172:175], v180 offset:1024
	ds_read_b128 v[176:179], v180 offset:2048
	ds_read_b128 v[180:183], v180 offset:3072
	s_add_u32 s62, s62, 0x40000
	s_addc_u32 s63, s63, 0
	s_mov_b32 m0, s66
	ds_read_b128 v[184:187], v151 offset:32768
	ds_read_b128 v[192:195], v151 offset:33792
	ds_read_b128 v[196:199], v151 offset:34816
	ds_read_b128 v[200:203], v151 offset:35840
	ds_read_b128 v[204:207], v151 offset:36864
	ds_read_b128 v[208:211], v151 offset:37888
	ds_read_b128 v[212:215], v151 offset:38912
	ds_read_b128 v[216:219], v151 offset:39936
	global_load_lds_dwordx4 v128, s[62:63]
	s_mov_b32 m0, s67
	s_nop 0
	global_load_lds_dwordx4 v132, s[62:63]
	s_waitcnt vmcnt(8)
	s_waitcnt lgkmcnt(0)
	s_barrier
	s_setprio 1
	s_waitcnt lgkmcnt(0)
	v_mfma_f32_16x16x32_bf16 v[124:127], v[152:155], v[184:187], v[124:127]
	v_mfma_f32_16x16x32_bf16 v[120:123], v[160:163], v[184:187], v[120:123]
	v_mfma_f32_16x16x32_bf16 v[116:119], v[152:155], v[196:199], v[116:119]
	v_mfma_f32_16x16x32_bf16 v[108:111], v[160:163], v[196:199], v[108:111]
	v_mfma_f32_16x16x32_bf16 v[100:103], v[152:155], v[204:207], v[100:103]
	v_mfma_f32_16x16x32_bf16 v[92:95], v[160:163], v[204:207], v[92:95]
	v_mfma_f32_16x16x32_bf16 v[84:87], v[152:155], v[212:215], v[84:87]
	v_mfma_f32_16x16x32_bf16 v[76:79], v[160:163], v[212:215], v[76:79]
	v_mfma_f32_16x16x32_bf16 v[124:127], v[156:159], v[192:195], v[124:127]
	v_mfma_f32_16x16x32_bf16 v[120:123], v[164:167], v[192:195], v[120:123]
	v_mfma_f32_16x16x32_bf16 v[116:119], v[156:159], v[200:203], v[116:119]
	v_mfma_f32_16x16x32_bf16 v[108:111], v[164:167], v[200:203], v[108:111]
	v_mfma_f32_16x16x32_bf16 v[100:103], v[156:159], v[208:211], v[100:103]
	v_mfma_f32_16x16x32_bf16 v[92:95], v[164:167], v[208:211], v[92:95]
	v_mfma_f32_16x16x32_bf16 v[84:87], v[156:159], v[216:219], v[84:87]
	v_mfma_f32_16x16x32_bf16 v[76:79], v[164:167], v[216:219], v[76:79]
	s_setprio 0
	s_setprio 1
	v_mfma_f32_16x16x32_bf16 v[112:115], v[168:171], v[184:187], v[112:115]
	v_mfma_f32_16x16x32_bf16 v[104:107], v[176:179], v[184:187], v[104:107]
	v_mfma_f32_16x16x32_bf16 v[96:99], v[168:171], v[196:199], v[96:99]
	v_mfma_f32_16x16x32_bf16 v[88:91], v[176:179], v[196:199], v[88:91]
	v_mfma_f32_16x16x32_bf16 v[80:83], v[168:171], v[204:207], v[80:83]
	v_mfma_f32_16x16x32_bf16 v[72:75], v[176:179], v[204:207], v[72:75]
	v_mfma_f32_16x16x32_bf16 v[68:71], v[168:171], v[212:215], v[68:71]
	v_mfma_f32_16x16x32_bf16 v[64:67], v[176:179], v[212:215], v[64:67]
	v_mfma_f32_16x16x32_bf16 v[112:115], v[172:175], v[192:195], v[112:115]
	v_mfma_f32_16x16x32_bf16 v[104:107], v[180:183], v[192:195], v[104:107]
	v_mfma_f32_16x16x32_bf16 v[96:99], v[172:175], v[200:203], v[96:99]
	v_mfma_f32_16x16x32_bf16 v[88:91], v[180:183], v[200:203], v[88:91]
	v_mfma_f32_16x16x32_bf16 v[80:83], v[172:175], v[208:211], v[80:83]
	v_mfma_f32_16x16x32_bf16 v[72:75], v[180:183], v[208:211], v[72:75]
	v_mfma_f32_16x16x32_bf16 v[68:71], v[172:175], v[216:219], v[68:71]
	v_mfma_f32_16x16x32_bf16 v[64:67], v[180:183], v[216:219], v[64:67]
	s_setprio 0
	s_barrier
	s_add_i32 s62, s83, s65
	v_lshl_add_u64 v[144:145], v[144:145], 0, s[12:13]
	s_mov_b32 m0, s62
	ds_read_b128 v[184:187], v151 offset:49152
	ds_read_b128 v[192:195], v151 offset:50176
	ds_read_b128 v[196:199], v151 offset:51200
	ds_read_b128 v[200:203], v151 offset:52224
	ds_read_b128 v[204:207], v151 offset:53248
	ds_read_b128 v[208:211], v151 offset:54272
	ds_read_b128 v[212:215], v151 offset:55296
	ds_read_b128 v[216:219], v151 offset:56320
	global_load_lds_dwordx4 v[144:145], off
	s_add_i32 m0, s62, 0x2000
	s_add_u32 s60, s60, 0x40080
	v_lshl_add_u64 v[144:145], v[188:189], 0, s[12:13]
	s_addc_u32 s61, s61, 0
	s_add_i32 s62, s84, s65
	global_load_lds_dwordx4 v[144:145], off
	s_mov_b32 m0, s62
	s_nop 0
	global_load_lds_dwordx4 v130, s[60:61]
	s_add_i32 m0, s62, 0x2000
	s_nop 0
	global_load_lds_dwordx4 v134, s[60:61]
	v_lshl_add_u64 v[144:145], v[220:221], 0, s[12:13]
	s_mov_b32 m0, s69
	s_nop 0
	global_load_lds_dwordx4 v[144:145], off
	v_lshl_add_u64 v[144:145], v[222:223], 0, s[12:13]
	s_mov_b32 m0, s70
	s_nop 0
	global_load_lds_dwordx4 v[144:145], off
	s_waitcnt vmcnt(8)
	s_waitcnt lgkmcnt(0)
	s_barrier
	s_setprio 1
	s_waitcnt lgkmcnt(0)
	v_mfma_f32_16x16x32_bf16 v[60:63], v[152:155], v[184:187], v[60:63]
	v_mfma_f32_16x16x32_bf16 v[56:59], v[160:163], v[184:187], v[56:59]
	v_mfma_f32_16x16x32_bf16 v[52:55], v[152:155], v[196:199], v[52:55]
	v_mfma_f32_16x16x32_bf16 v[44:47], v[160:163], v[196:199], v[44:47]
	v_mfma_f32_16x16x32_bf16 v[36:39], v[152:155], v[204:207], v[36:39]
	v_mfma_f32_16x16x32_bf16 v[28:31], v[160:163], v[204:207], v[28:31]
	v_mfma_f32_16x16x32_bf16 v[20:23], v[152:155], v[212:215], v[20:23]
	v_mfma_f32_16x16x32_bf16 v[12:15], v[160:163], v[212:215], v[12:15]
	v_mfma_f32_16x16x32_bf16 v[60:63], v[156:159], v[192:195], v[60:63]
	v_mfma_f32_16x16x32_bf16 v[56:59], v[164:167], v[192:195], v[56:59]
	v_mfma_f32_16x16x32_bf16 v[52:55], v[156:159], v[200:203], v[52:55]
	v_mfma_f32_16x16x32_bf16 v[44:47], v[164:167], v[200:203], v[44:47]
	v_mfma_f32_16x16x32_bf16 v[36:39], v[156:159], v[208:211], v[36:39]
	v_mfma_f32_16x16x32_bf16 v[28:31], v[164:167], v[208:211], v[28:31]
	v_mfma_f32_16x16x32_bf16 v[20:23], v[156:159], v[216:219], v[20:23]
	v_mfma_f32_16x16x32_bf16 v[12:15], v[164:167], v[216:219], v[12:15]
	s_setprio 0
	s_setprio 1
	v_mfma_f32_16x16x32_bf16 v[48:51], v[168:171], v[184:187], v[48:51]
	v_mfma_f32_16x16x32_bf16 v[40:43], v[176:179], v[184:187], v[40:43]
	v_mfma_f32_16x16x32_bf16 v[32:35], v[168:171], v[196:199], v[32:35]
	v_mfma_f32_16x16x32_bf16 v[24:27], v[176:179], v[196:199], v[24:27]
	v_mfma_f32_16x16x32_bf16 v[16:19], v[168:171], v[204:207], v[16:19]
	v_mfma_f32_16x16x32_bf16 v[8:11], v[176:179], v[204:207], v[8:11]
	v_mfma_f32_16x16x32_bf16 v[4:7], v[168:171], v[212:215], v[4:7]
	v_mfma_f32_16x16x32_bf16 v[0:3], v[176:179], v[212:215], v[0:3]
	v_mfma_f32_16x16x32_bf16 v[48:51], v[172:175], v[192:195], v[48:51]
	v_mfma_f32_16x16x32_bf16 v[40:43], v[180:183], v[192:195], v[40:43]
	v_mfma_f32_16x16x32_bf16 v[32:35], v[172:175], v[200:203], v[32:35]
	v_mfma_f32_16x16x32_bf16 v[24:27], v[180:183], v[200:203], v[24:27]
	v_mfma_f32_16x16x32_bf16 v[16:19], v[172:175], v[208:211], v[16:19]
	v_mfma_f32_16x16x32_bf16 v[8:11], v[180:183], v[208:211], v[8:11]
	v_mfma_f32_16x16x32_bf16 v[4:7], v[172:175], v[216:219], v[4:7]
	v_mfma_f32_16x16x32_bf16 v[0:3], v[180:183], v[216:219], v[0:3]
	s_setprio 0
	s_barrier
	s_add_i32 s82, s82, 2
	s_add_u32 s42, s42, 0x100
	s_addc_u32 s43, s43, 0
	s_add_u32 s80, s80, 0x100
	s_addc_u32 s81, s81, 0
	s_cmp_gt_u32 s82, 13
	s_cbranch_scc0 .LBB0_1077
	s_branch .Lpeel_exit6

.LBB0_1221:
	s_ashr_i32 s21, s20, 31
	s_lshl_b64 s[22:23], s[20:21], 17
	s_add_u32 s22, s70, s22
	s_addc_u32 s23, s71, s23
	s_and_b64 s[24:25], s[0:1], exec
	s_cselect_b32 s21, s23, s31
	s_cselect_b32 s55, s22, s30
	s_ashr_i32 s19, s18, 31
	s_lshl_b64 s[24:25], s[18:19], 17
	s_add_u32 s24, s53, s24
	s_addc_u32 s25, s72, s25
	s_and_b64 s[34:35], s[0:1], exec
	s_cselect_b32 s19, s25, s29
	s_cselect_b32 s85, s24, s28
	s_mov_b32 s60, 0
	s_mov_b64 s[34:35], -1
	s_mov_b64 s[42:43], 0
	s_add_u32 s61, s30, s60
	s_addc_u32 s66, s31, 0
	s_add_u32 s64, s61, 0x100
	s_addc_u32 s65, s66, 0
	s_and_b64 s[62:63], s[42:43], exec
	s_cselect_b32 s63, s21, s65
	s_cselect_b32 s62, s55, s64
	s_add_u32 s60, s28, s60
	s_addc_u32 s64, s29, 0
	s_add_u32 s60, s60, 0x100
	s_addc_u32 s64, s64, 0
	s_and_b64 s[42:43], s[42:43], exec
	s_cselect_b32 s65, s19, s64
	s_cselect_b32 s64, s85, s60
	s_add_u32 s68, s61, 0x10080
	ds_read_b128 v[148:151], v145
	ds_read_b128 v[152:155], v145 offset:1024
	ds_read_b128 v[156:159], v145 offset:2048
	ds_read_b128 v[160:163], v145 offset:3072
	ds_read_b128 v[164:167], v146
	ds_read_b128 v[168:171], v146 offset:1024
	ds_read_b128 v[172:175], v146 offset:2048
	ds_read_b128 v[176:179], v146 offset:3072
	s_addc_u32 s69, s66, 0
	s_add_i32 s95, s81, s73
	s_add_i32 m0, s27, 0xc000
	s_add_i32 s96, s27, 0xe000
	s_add_i32 s92, s95, 0x2000
	s_add_u32 s66, s64, 0x10000
	s_addc_u32 s67, s65, 0
	s_add_i32 s94, s82, s73
	s_add_i32 s93, s94, 0x2000
	s_add_i32 s91, 0, 0x18000
	s_add_i32 s90, 0, 0x1c000
	s_add_u32 s60, s62, 0x10000
	s_addc_u32 s61, s63, 0
	s_add_i32 s89, s91, s73
	s_add_i32 s87, s89, 0x2000
	s_add_u32 s42, s64, 0x10080
	s_addc_u32 s43, s65, 0
	s_add_i32 s88, s90, s73
	s_add_i32 s86, s88, 0x2000
	ds_read_b128 v[180:183], v147
	ds_read_b128 v[184:187], v147 offset:1024
	ds_read_b128 v[192:195], v147 offset:2048
	ds_read_b128 v[196:199], v147 offset:3072
	ds_read_b128 v[200:203], v147 offset:4096
	ds_read_b128 v[204:207], v147 offset:5120
	ds_read_b128 v[208:211], v147 offset:6144
	ds_read_b128 v[212:215], v147 offset:7168
	global_load_lds_dwordx4 v128, s[68:69]
	s_mov_b32 m0, s96
	s_nop 0
	global_load_lds_dwordx4 v132, s[68:69]
	s_waitcnt vmcnt(8)
	s_waitcnt lgkmcnt(0)
	s_barrier
	s_setprio 1
	s_waitcnt lgkmcnt(0)
	v_mfma_f32_16x16x32_bf16 v[124:127], v[148:151], v[180:183], 0
	v_mfma_f32_16x16x32_bf16 v[120:123], v[156:159], v[180:183], 0
	v_mfma_f32_16x16x32_bf16 v[116:119], v[148:151], v[192:195], 0
	v_mfma_f32_16x16x32_bf16 v[108:111], v[156:159], v[192:195], 0
	v_mfma_f32_16x16x32_bf16 v[100:103], v[148:151], v[200:203], 0
	v_mfma_f32_16x16x32_bf16 v[92:95], v[156:159], v[200:203], 0
	v_mfma_f32_16x16x32_bf16 v[84:87], v[148:151], v[208:211], 0
	v_mfma_f32_16x16x32_bf16 v[76:79], v[156:159], v[208:211], 0
	v_mfma_f32_16x16x32_bf16 v[124:127], v[152:155], v[184:187], v[124:127]
	v_mfma_f32_16x16x32_bf16 v[120:123], v[160:163], v[184:187], v[120:123]
	v_mfma_f32_16x16x32_bf16 v[116:119], v[152:155], v[196:199], v[116:119]
	v_mfma_f32_16x16x32_bf16 v[108:111], v[160:163], v[196:199], v[108:111]
	v_mfma_f32_16x16x32_bf16 v[100:103], v[152:155], v[204:207], v[100:103]
	v_mfma_f32_16x16x32_bf16 v[92:95], v[160:163], v[204:207], v[92:95]
	v_mfma_f32_16x16x32_bf16 v[84:87], v[152:155], v[212:215], v[84:87]
	v_mfma_f32_16x16x32_bf16 v[76:79], v[160:163], v[212:215], v[76:79]
	s_setprio 0
	s_setprio 1
	v_mfma_f32_16x16x32_bf16 v[112:115], v[164:167], v[180:183], 0
	v_mfma_f32_16x16x32_bf16 v[104:107], v[172:175], v[180:183], 0
	v_mfma_f32_16x16x32_bf16 v[96:99], v[164:167], v[192:195], 0
	v_mfma_f32_16x16x32_bf16 v[88:91], v[172:175], v[192:195], 0
	v_mfma_f32_16x16x32_bf16 v[80:83], v[164:167], v[200:203], 0
	v_mfma_f32_16x16x32_bf16 v[72:75], v[172:175], v[200:203], 0
	v_mfma_f32_16x16x32_bf16 v[68:71], v[164:167], v[208:211], 0
	v_mfma_f32_16x16x32_bf16 v[64:67], v[172:175], v[208:211], 0
	v_mfma_f32_16x16x32_bf16 v[112:115], v[168:171], v[184:187], v[112:115]
	v_mfma_f32_16x16x32_bf16 v[104:107], v[176:179], v[184:187], v[104:107]
	v_mfma_f32_16x16x32_bf16 v[96:99], v[168:171], v[196:199], v[96:99]
	v_mfma_f32_16x16x32_bf16 v[88:91], v[176:179], v[196:199], v[88:91]
	v_mfma_f32_16x16x32_bf16 v[80:83], v[168:171], v[204:207], v[80:83]
	v_mfma_f32_16x16x32_bf16 v[72:75], v[176:179], v[204:207], v[72:75]
	v_mfma_f32_16x16x32_bf16 v[68:71], v[168:171], v[212:215], v[68:71]
	v_mfma_f32_16x16x32_bf16 v[64:67], v[176:179], v[212:215], v[64:67]
	s_setprio 0
	s_barrier
	s_mov_b32 m0, s95
	v_lshl_add_u64 v[140:141], s[64:65], 0, v[130:131]
	ds_read_b128 v[180:183], v147 offset:16384
	ds_read_b128 v[184:187], v147 offset:17408
	ds_read_b128 v[192:195], v147 offset:18432
	ds_read_b128 v[196:199], v147 offset:19456
	ds_read_b128 v[200:203], v147 offset:20480
	ds_read_b128 v[204:207], v147 offset:21504
	ds_read_b128 v[208:211], v147 offset:22528
	ds_read_b128 v[212:215], v147 offset:23552
	global_load_lds_dwordx4 v[140:141], off
	v_lshl_add_u64 v[188:189], s[64:65], 0, v[134:135]
	s_mov_b32 m0, s92
	s_nop 0
	global_load_lds_dwordx4 v[188:189], off
	s_mov_b32 m0, s94
	v_lshl_add_u64 v[218:219], s[62:63], 0, v[132:133]
	global_load_lds_dwordx4 v130, s[66:67]
	s_mov_b32 m0, s93
	s_nop 0
	global_load_lds_dwordx4 v134, s[66:67]
	v_lshl_add_u64 v[216:217], s[62:63], 0, v[128:129]
	s_mov_b32 m0, s27
	s_nop 0
	global_load_lds_dwordx4 v[216:217], off
	s_mov_b32 m0, s33
	s_nop 0
	global_load_lds_dwordx4 v[218:219], off
	s_waitcnt vmcnt(8)
	s_waitcnt lgkmcnt(0)
	s_barrier
	s_setprio 1
	s_waitcnt lgkmcnt(0)
	v_mfma_f32_16x16x32_bf16 v[60:63], v[148:151], v[180:183], 0
	v_mfma_f32_16x16x32_bf16 v[56:59], v[156:159], v[180:183], 0
	v_mfma_f32_16x16x32_bf16 v[52:55], v[148:151], v[192:195], 0
	v_mfma_f32_16x16x32_bf16 v[44:47], v[156:159], v[192:195], 0
	v_mfma_f32_16x16x32_bf16 v[36:39], v[148:151], v[200:203], 0
	v_mfma_f32_16x16x32_bf16 v[28:31], v[156:159], v[200:203], 0
	v_mfma_f32_16x16x32_bf16 v[20:23], v[148:151], v[208:211], 0
	v_mfma_f32_16x16x32_bf16 v[12:15], v[156:159], v[208:211], 0
	v_mfma_f32_16x16x32_bf16 v[60:63], v[152:155], v[184:187], v[60:63]
	v_mfma_f32_16x16x32_bf16 v[56:59], v[160:163], v[184:187], v[56:59]
	v_mfma_f32_16x16x32_bf16 v[52:55], v[152:155], v[196:199], v[52:55]
	v_mfma_f32_16x16x32_bf16 v[44:47], v[160:163], v[196:199], v[44:47]
	v_mfma_f32_16x16x32_bf16 v[36:39], v[152:155], v[204:207], v[36:39]
	v_mfma_f32_16x16x32_bf16 v[28:31], v[160:163], v[204:207], v[28:31]
	v_mfma_f32_16x16x32_bf16 v[20:23], v[152:155], v[212:215], v[20:23]
	v_mfma_f32_16x16x32_bf16 v[12:15], v[160:163], v[212:215], v[12:15]
	s_setprio 0
	s_setprio 1
	v_mfma_f32_16x16x32_bf16 v[48:51], v[164:167], v[180:183], 0
	v_mfma_f32_16x16x32_bf16 v[40:43], v[172:175], v[180:183], 0
	v_mfma_f32_16x16x32_bf16 v[32:35], v[164:167], v[192:195], 0
	v_mfma_f32_16x16x32_bf16 v[24:27], v[172:175], v[192:195], 0
	v_mfma_f32_16x16x32_bf16 v[16:19], v[164:167], v[200:203], 0
	v_mfma_f32_16x16x32_bf16 v[8:11], v[172:175], v[200:203], 0
	v_mfma_f32_16x16x32_bf16 v[4:7], v[164:167], v[208:211], 0
	v_mfma_f32_16x16x32_bf16 v[0:3], v[172:175], v[208:211], 0
	v_mfma_f32_16x16x32_bf16 v[48:51], v[168:171], v[184:187], v[48:51]
	v_mfma_f32_16x16x32_bf16 v[40:43], v[176:179], v[184:187], v[40:43]
	v_mfma_f32_16x16x32_bf16 v[32:35], v[168:171], v[196:199], v[32:35]
	v_mfma_f32_16x16x32_bf16 v[24:27], v[176:179], v[196:199], v[24:27]
	v_mfma_f32_16x16x32_bf16 v[16:19], v[168:171], v[204:207], v[16:19]
	v_mfma_f32_16x16x32_bf16 v[8:11], v[176:179], v[204:207], v[8:11]
	v_mfma_f32_16x16x32_bf16 v[4:7], v[168:171], v[212:215], v[4:7]
	v_mfma_f32_16x16x32_bf16 v[0:3], v[176:179], v[212:215], v[0:3]
	s_setprio 0
	s_barrier
	v_add_u32_e32 v160, s91, v143
	v_add_u32_e32 v176, s90, v143
	ds_read_b128 v[148:151], v160
	ds_read_b128 v[152:155], v160 offset:1024
	ds_read_b128 v[156:159], v160 offset:2048
	ds_read_b128 v[160:163], v160 offset:3072
	ds_read_b128 v[164:167], v176
	ds_read_b128 v[168:171], v176 offset:1024
	ds_read_b128 v[172:175], v176 offset:2048
	ds_read_b128 v[176:179], v176 offset:3072
	s_mov_b32 m0, s74
	ds_read_b128 v[180:183], v147 offset:32768
	ds_read_b128 v[184:187], v147 offset:33792
	ds_read_b128 v[192:195], v147 offset:34816
	ds_read_b128 v[196:199], v147 offset:35840
	ds_read_b128 v[200:203], v147 offset:36864
	ds_read_b128 v[204:207], v147 offset:37888
	ds_read_b128 v[208:211], v147 offset:38912
	ds_read_b128 v[212:215], v147 offset:39936
	global_load_lds_dwordx4 v128, s[60:61]
	s_mov_b32 m0, s75
	s_nop 0
	global_load_lds_dwordx4 v132, s[60:61]
	s_waitcnt vmcnt(8)
	s_waitcnt lgkmcnt(0)
	s_barrier
	s_setprio 1
	s_waitcnt lgkmcnt(0)
	v_mfma_f32_16x16x32_bf16 v[124:127], v[148:151], v[180:183], v[124:127]
	v_mfma_f32_16x16x32_bf16 v[120:123], v[156:159], v[180:183], v[120:123]
	v_mfma_f32_16x16x32_bf16 v[116:119], v[148:151], v[192:195], v[116:119]
	v_mfma_f32_16x16x32_bf16 v[108:111], v[156:159], v[192:195], v[108:111]
	v_mfma_f32_16x16x32_bf16 v[100:103], v[148:151], v[200:203], v[100:103]
	v_mfma_f32_16x16x32_bf16 v[92:95], v[156:159], v[200:203], v[92:95]
	v_mfma_f32_16x16x32_bf16 v[84:87], v[148:151], v[208:211], v[84:87]
	v_mfma_f32_16x16x32_bf16 v[76:79], v[156:159], v[208:211], v[76:79]
	v_mfma_f32_16x16x32_bf16 v[124:127], v[152:155], v[184:187], v[124:127]
	v_mfma_f32_16x16x32_bf16 v[120:123], v[160:163], v[184:187], v[120:123]
	v_mfma_f32_16x16x32_bf16 v[116:119], v[152:155], v[196:199], v[116:119]
	v_mfma_f32_16x16x32_bf16 v[108:111], v[160:163], v[196:199], v[108:111]
	v_mfma_f32_16x16x32_bf16 v[100:103], v[152:155], v[204:207], v[100:103]
	v_mfma_f32_16x16x32_bf16 v[92:95], v[160:163], v[204:207], v[92:95]
	v_mfma_f32_16x16x32_bf16 v[84:87], v[152:155], v[212:215], v[84:87]
	v_mfma_f32_16x16x32_bf16 v[76:79], v[160:163], v[212:215], v[76:79]
	s_setprio 0
	s_setprio 1
	v_mfma_f32_16x16x32_bf16 v[112:115], v[164:167], v[180:183], v[112:115]
	v_mfma_f32_16x16x32_bf16 v[104:107], v[172:175], v[180:183], v[104:107]
	v_mfma_f32_16x16x32_bf16 v[96:99], v[164:167], v[192:195], v[96:99]
	v_mfma_f32_16x16x32_bf16 v[88:91], v[172:175], v[192:195], v[88:91]
	v_mfma_f32_16x16x32_bf16 v[80:83], v[164:167], v[200:203], v[80:83]
	v_mfma_f32_16x16x32_bf16 v[72:75], v[172:175], v[200:203], v[72:75]
	v_mfma_f32_16x16x32_bf16 v[68:71], v[164:167], v[208:211], v[68:71]
	v_mfma_f32_16x16x32_bf16 v[64:67], v[172:175], v[208:211], v[64:67]
	v_mfma_f32_16x16x32_bf16 v[112:115], v[168:171], v[184:187], v[112:115]
	v_mfma_f32_16x16x32_bf16 v[104:107], v[176:179], v[184:187], v[104:107]
	v_mfma_f32_16x16x32_bf16 v[96:99], v[168:171], v[196:199], v[96:99]
	v_mfma_f32_16x16x32_bf16 v[88:91], v[176:179], v[196:199], v[88:91]
	v_mfma_f32_16x16x32_bf16 v[80:83], v[168:171], v[204:207], v[80:83]
	v_mfma_f32_16x16x32_bf16 v[72:75], v[176:179], v[204:207], v[72:75]
	v_mfma_f32_16x16x32_bf16 v[68:71], v[168:171], v[212:215], v[68:71]
	v_mfma_f32_16x16x32_bf16 v[64:67], v[176:179], v[212:215], v[64:67]
	s_setprio 0
	s_barrier
	s_mov_b32 m0, s89
	v_lshl_add_u64 v[140:141], v[140:141], 0, s[12:13]
	ds_read_b128 v[180:183], v147 offset:49152
	ds_read_b128 v[184:187], v147 offset:50176
	ds_read_b128 v[192:195], v147 offset:51200
	ds_read_b128 v[196:199], v147 offset:52224
	ds_read_b128 v[200:203], v147 offset:53248
	ds_read_b128 v[204:207], v147 offset:54272
	ds_read_b128 v[208:211], v147 offset:55296
	ds_read_b128 v[212:215], v147 offset:56320
	global_load_lds_dwordx4 v[140:141], off
	v_lshl_add_u64 v[140:141], v[188:189], 0, s[12:13]
	s_mov_b32 m0, s87
	s_nop 0
	global_load_lds_dwordx4 v[140:141], off
	s_mov_b32 m0, s88
	s_nop 0
	global_load_lds_dwordx4 v130, s[42:43]
	s_mov_b32 m0, s86
	s_nop 0
	global_load_lds_dwordx4 v134, s[42:43]
	v_lshl_add_u64 v[140:141], v[216:217], 0, s[12:13]
	s_mov_b32 m0, s77
	s_nop 0
	global_load_lds_dwordx4 v[140:141], off
	v_lshl_add_u64 v[140:141], v[218:219], 0, s[12:13]
	s_mov_b32 m0, s79
	s_nop 0
	global_load_lds_dwordx4 v[140:141], off
	s_waitcnt vmcnt(8)
	s_waitcnt lgkmcnt(0)
	s_barrier
	s_setprio 1
	s_waitcnt lgkmcnt(0)
	v_mfma_f32_16x16x32_bf16 v[60:63], v[148:151], v[180:183], v[60:63]
	v_mfma_f32_16x16x32_bf16 v[56:59], v[156:159], v[180:183], v[56:59]
	v_mfma_f32_16x16x32_bf16 v[52:55], v[148:151], v[192:195], v[52:55]
	v_mfma_f32_16x16x32_bf16 v[44:47], v[156:159], v[192:195], v[44:47]
	v_mfma_f32_16x16x32_bf16 v[36:39], v[148:151], v[200:203], v[36:39]
	v_mfma_f32_16x16x32_bf16 v[28:31], v[156:159], v[200:203], v[28:31]
	v_mfma_f32_16x16x32_bf16 v[20:23], v[148:151], v[208:211], v[20:23]
	v_mfma_f32_16x16x32_bf16 v[12:15], v[156:159], v[208:211], v[12:15]
	v_mfma_f32_16x16x32_bf16 v[60:63], v[152:155], v[184:187], v[60:63]
	v_mfma_f32_16x16x32_bf16 v[56:59], v[160:163], v[184:187], v[56:59]
	v_mfma_f32_16x16x32_bf16 v[52:55], v[152:155], v[196:199], v[52:55]
	v_mfma_f32_16x16x32_bf16 v[44:47], v[160:163], v[196:199], v[44:47]
	v_mfma_f32_16x16x32_bf16 v[36:39], v[152:155], v[204:207], v[36:39]
	v_mfma_f32_16x16x32_bf16 v[28:31], v[160:163], v[204:207], v[28:31]
	v_mfma_f32_16x16x32_bf16 v[20:23], v[152:155], v[212:215], v[20:23]
	v_mfma_f32_16x16x32_bf16 v[12:15], v[160:163], v[212:215], v[12:15]
	s_setprio 0
	s_setprio 1
	v_mfma_f32_16x16x32_bf16 v[48:51], v[164:167], v[180:183], v[48:51]
	v_mfma_f32_16x16x32_bf16 v[40:43], v[172:175], v[180:183], v[40:43]
	v_mfma_f32_16x16x32_bf16 v[32:35], v[164:167], v[192:195], v[32:35]
	v_mfma_f32_16x16x32_bf16 v[24:27], v[172:175], v[192:195], v[24:27]
	v_mfma_f32_16x16x32_bf16 v[16:19], v[164:167], v[200:203], v[16:19]
	v_mfma_f32_16x16x32_bf16 v[8:11], v[172:175], v[200:203], v[8:11]
	v_mfma_f32_16x16x32_bf16 v[4:7], v[164:167], v[208:211], v[4:7]
	v_mfma_f32_16x16x32_bf16 v[0:3], v[172:175], v[208:211], v[0:3]
	v_mfma_f32_16x16x32_bf16 v[48:51], v[168:171], v[184:187], v[48:51]
	v_mfma_f32_16x16x32_bf16 v[40:43], v[176:179], v[184:187], v[40:43]
	v_mfma_f32_16x16x32_bf16 v[32:35], v[168:171], v[196:199], v[32:35]
	v_mfma_f32_16x16x32_bf16 v[24:27], v[176:179], v[196:199], v[24:27]
	v_mfma_f32_16x16x32_bf16 v[16:19], v[168:171], v[204:207], v[16:19]
	v_mfma_f32_16x16x32_bf16 v[8:11], v[176:179], v[204:207], v[8:11]
	v_mfma_f32_16x16x32_bf16 v[4:7], v[168:171], v[212:215], v[4:7]
	v_mfma_f32_16x16x32_bf16 v[0:3], v[176:179], v[212:215], v[0:3]
	s_setprio 0
	s_barrier
	s_movk_i32 s60, 0x100
	s_andn2_b64 vcc, exec, s[34:35]
	s_mov_b64 s[42:43], -1
	s_mov_b64 s[34:35], 0
	s_cbranch_vccz .LBB0_1222
	s_branch .Lpeel_exit7

.LBB0_1245:
	s_ashr_i32 s21, s20, 31
	s_lshl_b64 s[22:23], s[20:21], 17
	s_add_u32 s22, s52, s22
	s_addc_u32 s23, s53, s23
	s_and_b64 s[24:25], s[0:1], exec
	s_cselect_b32 s21, s23, s31
	s_cselect_b32 s55, s22, s30
	s_ashr_i32 s19, s18, 31
	s_lshl_b64 s[24:25], s[18:19], 17
	s_add_u32 s24, s70, s24
	s_addc_u32 s25, s71, s25
	s_and_b64 s[34:35], s[0:1], exec
	s_cselect_b32 s19, s25, s29
	s_cselect_b32 s86, s24, s28
	s_mov_b32 s60, 0
	s_mov_b64 s[34:35], -1
	s_mov_b64 s[42:43], 0
	s_add_u32 s61, s30, s60
	s_addc_u32 s66, s31, 0
	s_add_u32 s64, s61, 0x100
	s_addc_u32 s65, s66, 0
	s_and_b64 s[62:63], s[42:43], exec
	s_cselect_b32 s63, s21, s65
	s_cselect_b32 s62, s55, s64
	s_add_u32 s60, s28, s60
	s_addc_u32 s64, s29, 0
	s_add_u32 s60, s60, 0x100
	s_addc_u32 s64, s64, 0
	s_and_b64 s[42:43], s[42:43], exec
	s_cselect_b32 s65, s19, s64
	s_cselect_b32 s64, s86, s60
	s_add_u32 s68, s61, 0x10080
	ds_read_b128 v[148:151], v145
	ds_read_b128 v[152:155], v145 offset:1024
	ds_read_b128 v[156:159], v145 offset:2048
	ds_read_b128 v[160:163], v145 offset:3072
	ds_read_b128 v[164:167], v146
	ds_read_b128 v[168:171], v146 offset:1024
	ds_read_b128 v[172:175], v146 offset:2048
	ds_read_b128 v[176:179], v146 offset:3072
	s_addc_u32 s69, s66, 0
	s_add_i32 s96, s81, s73
	s_add_i32 m0, s27, 0xc000
	s_add_i32 s97, s27, 0xe000
	s_add_i32 s93, s96, 0x2000
	s_add_u32 s66, s64, 0x10000
	s_addc_u32 s67, s65, 0
	s_add_i32 s95, s82, s73
	s_add_i32 s94, s95, 0x2000
	s_add_i32 s92, 0, 0x18000
	s_add_i32 s91, 0, 0x1c000
	s_add_u32 s60, s62, 0x10000
	s_addc_u32 s61, s63, 0
	s_add_i32 s90, s92, s73
	s_add_i32 s88, s90, 0x2000
	s_add_u32 s42, s64, 0x10080
	s_addc_u32 s43, s65, 0
	s_add_i32 s89, s91, s73
	s_add_i32 s87, s89, 0x2000
	ds_read_b128 v[180:183], v147
	ds_read_b128 v[184:187], v147 offset:1024
	ds_read_b128 v[192:195], v147 offset:2048
	ds_read_b128 v[196:199], v147 offset:3072
	ds_read_b128 v[200:203], v147 offset:4096
	ds_read_b128 v[204:207], v147 offset:5120
	ds_read_b128 v[208:211], v147 offset:6144
	ds_read_b128 v[212:215], v147 offset:7168
	global_load_lds_dwordx4 v128, s[68:69]
	s_mov_b32 m0, s97
	s_nop 0
	global_load_lds_dwordx4 v132, s[68:69]
	s_waitcnt vmcnt(8)
	s_waitcnt lgkmcnt(0)
	s_barrier
	s_setprio 1
	s_waitcnt lgkmcnt(0)
	v_mfma_f32_16x16x32_bf16 v[124:127], v[148:151], v[180:183], 0
	v_mfma_f32_16x16x32_bf16 v[120:123], v[156:159], v[180:183], 0
	v_mfma_f32_16x16x32_bf16 v[116:119], v[148:151], v[192:195], 0
	v_mfma_f32_16x16x32_bf16 v[108:111], v[156:159], v[192:195], 0
	v_mfma_f32_16x16x32_bf16 v[100:103], v[148:151], v[200:203], 0
	v_mfma_f32_16x16x32_bf16 v[92:95], v[156:159], v[200:203], 0
	v_mfma_f32_16x16x32_bf16 v[84:87], v[148:151], v[208:211], 0
	v_mfma_f32_16x16x32_bf16 v[76:79], v[156:159], v[208:211], 0
	v_mfma_f32_16x16x32_bf16 v[124:127], v[152:155], v[184:187], v[124:127]
	v_mfma_f32_16x16x32_bf16 v[120:123], v[160:163], v[184:187], v[120:123]
	v_mfma_f32_16x16x32_bf16 v[116:119], v[152:155], v[196:199], v[116:119]
	v_mfma_f32_16x16x32_bf16 v[108:111], v[160:163], v[196:199], v[108:111]
	v_mfma_f32_16x16x32_bf16 v[100:103], v[152:155], v[204:207], v[100:103]
	v_mfma_f32_16x16x32_bf16 v[92:95], v[160:163], v[204:207], v[92:95]
	v_mfma_f32_16x16x32_bf16 v[84:87], v[152:155], v[212:215], v[84:87]
	v_mfma_f32_16x16x32_bf16 v[76:79], v[160:163], v[212:215], v[76:79]
	s_setprio 0
	s_setprio 1
	v_mfma_f32_16x16x32_bf16 v[112:115], v[164:167], v[180:183], 0
	v_mfma_f32_16x16x32_bf16 v[104:107], v[172:175], v[180:183], 0
	v_mfma_f32_16x16x32_bf16 v[96:99], v[164:167], v[192:195], 0
	v_mfma_f32_16x16x32_bf16 v[88:91], v[172:175], v[192:195], 0
	v_mfma_f32_16x16x32_bf16 v[80:83], v[164:167], v[200:203], 0
	v_mfma_f32_16x16x32_bf16 v[72:75], v[172:175], v[200:203], 0
	v_mfma_f32_16x16x32_bf16 v[68:71], v[164:167], v[208:211], 0
	v_mfma_f32_16x16x32_bf16 v[64:67], v[172:175], v[208:211], 0
	v_mfma_f32_16x16x32_bf16 v[112:115], v[168:171], v[184:187], v[112:115]
	v_mfma_f32_16x16x32_bf16 v[104:107], v[176:179], v[184:187], v[104:107]
	v_mfma_f32_16x16x32_bf16 v[96:99], v[168:171], v[196:199], v[96:99]
	v_mfma_f32_16x16x32_bf16 v[88:91], v[176:179], v[196:199], v[88:91]
	v_mfma_f32_16x16x32_bf16 v[80:83], v[168:171], v[204:207], v[80:83]
	v_mfma_f32_16x16x32_bf16 v[72:75], v[176:179], v[204:207], v[72:75]
	v_mfma_f32_16x16x32_bf16 v[68:71], v[168:171], v[212:215], v[68:71]
	v_mfma_f32_16x16x32_bf16 v[64:67], v[176:179], v[212:215], v[64:67]
	s_setprio 0
	s_barrier
	s_mov_b32 m0, s96
	v_lshl_add_u64 v[140:141], s[64:65], 0, v[130:131]
	ds_read_b128 v[180:183], v147 offset:16384
	ds_read_b128 v[184:187], v147 offset:17408
	ds_read_b128 v[192:195], v147 offset:18432
	ds_read_b128 v[196:199], v147 offset:19456
	ds_read_b128 v[200:203], v147 offset:20480
	ds_read_b128 v[204:207], v147 offset:21504
	ds_read_b128 v[208:211], v147 offset:22528
	ds_read_b128 v[212:215], v147 offset:23552
	global_load_lds_dwordx4 v[140:141], off
	v_lshl_add_u64 v[188:189], s[64:65], 0, v[134:135]
	s_mov_b32 m0, s93
	s_nop 0
	global_load_lds_dwordx4 v[188:189], off
	s_mov_b32 m0, s95
	v_lshl_add_u64 v[218:219], s[62:63], 0, v[132:133]
	global_load_lds_dwordx4 v130, s[66:67]
	s_mov_b32 m0, s94
	s_nop 0
	global_load_lds_dwordx4 v134, s[66:67]
	v_lshl_add_u64 v[216:217], s[62:63], 0, v[128:129]
	s_mov_b32 m0, s27
	s_nop 0
	global_load_lds_dwordx4 v[216:217], off
	s_mov_b32 m0, s33
	s_nop 0
	global_load_lds_dwordx4 v[218:219], off
	s_waitcnt vmcnt(8)
	s_waitcnt lgkmcnt(0)
	s_barrier
	s_setprio 1
	s_waitcnt lgkmcnt(0)
	v_mfma_f32_16x16x32_bf16 v[60:63], v[148:151], v[180:183], 0
	v_mfma_f32_16x16x32_bf16 v[56:59], v[156:159], v[180:183], 0
	v_mfma_f32_16x16x32_bf16 v[52:55], v[148:151], v[192:195], 0
	v_mfma_f32_16x16x32_bf16 v[44:47], v[156:159], v[192:195], 0
	v_mfma_f32_16x16x32_bf16 v[36:39], v[148:151], v[200:203], 0
	v_mfma_f32_16x16x32_bf16 v[28:31], v[156:159], v[200:203], 0
	v_mfma_f32_16x16x32_bf16 v[20:23], v[148:151], v[208:211], 0
	v_mfma_f32_16x16x32_bf16 v[12:15], v[156:159], v[208:211], 0
	v_mfma_f32_16x16x32_bf16 v[60:63], v[152:155], v[184:187], v[60:63]
	v_mfma_f32_16x16x32_bf16 v[56:59], v[160:163], v[184:187], v[56:59]
	v_mfma_f32_16x16x32_bf16 v[52:55], v[152:155], v[196:199], v[52:55]
	v_mfma_f32_16x16x32_bf16 v[44:47], v[160:163], v[196:199], v[44:47]
	v_mfma_f32_16x16x32_bf16 v[36:39], v[152:155], v[204:207], v[36:39]
	v_mfma_f32_16x16x32_bf16 v[28:31], v[160:163], v[204:207], v[28:31]
	v_mfma_f32_16x16x32_bf16 v[20:23], v[152:155], v[212:215], v[20:23]
	v_mfma_f32_16x16x32_bf16 v[12:15], v[160:163], v[212:215], v[12:15]
	s_setprio 0
	s_setprio 1
	v_mfma_f32_16x16x32_bf16 v[48:51], v[164:167], v[180:183], 0
	v_mfma_f32_16x16x32_bf16 v[40:43], v[172:175], v[180:183], 0
	v_mfma_f32_16x16x32_bf16 v[32:35], v[164:167], v[192:195], 0
	v_mfma_f32_16x16x32_bf16 v[24:27], v[172:175], v[192:195], 0
	v_mfma_f32_16x16x32_bf16 v[16:19], v[164:167], v[200:203], 0
	v_mfma_f32_16x16x32_bf16 v[8:11], v[172:175], v[200:203], 0
	v_mfma_f32_16x16x32_bf16 v[4:7], v[164:167], v[208:211], 0
	v_mfma_f32_16x16x32_bf16 v[0:3], v[172:175], v[208:211], 0
	v_mfma_f32_16x16x32_bf16 v[48:51], v[168:171], v[184:187], v[48:51]
	v_mfma_f32_16x16x32_bf16 v[40:43], v[176:179], v[184:187], v[40:43]
	v_mfma_f32_16x16x32_bf16 v[32:35], v[168:171], v[196:199], v[32:35]
	v_mfma_f32_16x16x32_bf16 v[24:27], v[176:179], v[196:199], v[24:27]
	v_mfma_f32_16x16x32_bf16 v[16:19], v[168:171], v[204:207], v[16:19]
	v_mfma_f32_16x16x32_bf16 v[8:11], v[176:179], v[204:207], v[8:11]
	v_mfma_f32_16x16x32_bf16 v[4:7], v[168:171], v[212:215], v[4:7]
	v_mfma_f32_16x16x32_bf16 v[0:3], v[176:179], v[212:215], v[0:3]
	s_setprio 0
	s_barrier
	v_add_u32_e32 v160, s92, v143
	v_add_u32_e32 v176, s91, v143
	ds_read_b128 v[148:151], v160
	ds_read_b128 v[152:155], v160 offset:1024
	ds_read_b128 v[156:159], v160 offset:2048
	ds_read_b128 v[160:163], v160 offset:3072
	ds_read_b128 v[164:167], v176
	ds_read_b128 v[168:171], v176 offset:1024
	ds_read_b128 v[172:175], v176 offset:2048
	ds_read_b128 v[176:179], v176 offset:3072
	s_mov_b32 m0, s74
	ds_read_b128 v[180:183], v147 offset:32768
	ds_read_b128 v[184:187], v147 offset:33792
	ds_read_b128 v[192:195], v147 offset:34816
	ds_read_b128 v[196:199], v147 offset:35840
	ds_read_b128 v[200:203], v147 offset:36864
	ds_read_b128 v[204:207], v147 offset:37888
	ds_read_b128 v[208:211], v147 offset:38912
	ds_read_b128 v[212:215], v147 offset:39936
	global_load_lds_dwordx4 v128, s[60:61]
	s_mov_b32 m0, s75
	s_nop 0
	global_load_lds_dwordx4 v132, s[60:61]
	s_waitcnt vmcnt(8)
	s_waitcnt lgkmcnt(0)
	s_barrier
	s_setprio 1
	s_waitcnt lgkmcnt(0)
	v_mfma_f32_16x16x32_bf16 v[124:127], v[148:151], v[180:183], v[124:127]
	v_mfma_f32_16x16x32_bf16 v[120:123], v[156:159], v[180:183], v[120:123]
	v_mfma_f32_16x16x32_bf16 v[116:119], v[148:151], v[192:195], v[116:119]
	v_mfma_f32_16x16x32_bf16 v[108:111], v[156:159], v[192:195], v[108:111]
	v_mfma_f32_16x16x32_bf16 v[100:103], v[148:151], v[200:203], v[100:103]
	v_mfma_f32_16x16x32_bf16 v[92:95], v[156:159], v[200:203], v[92:95]
	v_mfma_f32_16x16x32_bf16 v[84:87], v[148:151], v[208:211], v[84:87]
	v_mfma_f32_16x16x32_bf16 v[76:79], v[156:159], v[208:211], v[76:79]
	v_mfma_f32_16x16x32_bf16 v[124:127], v[152:155], v[184:187], v[124:127]
	v_mfma_f32_16x16x32_bf16 v[120:123], v[160:163], v[184:187], v[120:123]
	v_mfma_f32_16x16x32_bf16 v[116:119], v[152:155], v[196:199], v[116:119]
	v_mfma_f32_16x16x32_bf16 v[108:111], v[160:163], v[196:199], v[108:111]
	v_mfma_f32_16x16x32_bf16 v[100:103], v[152:155], v[204:207], v[100:103]
	v_mfma_f32_16x16x32_bf16 v[92:95], v[160:163], v[204:207], v[92:95]
	v_mfma_f32_16x16x32_bf16 v[84:87], v[152:155], v[212:215], v[84:87]
	v_mfma_f32_16x16x32_bf16 v[76:79], v[160:163], v[212:215], v[76:79]
	s_setprio 0
	s_setprio 1
	v_mfma_f32_16x16x32_bf16 v[112:115], v[164:167], v[180:183], v[112:115]
	v_mfma_f32_16x16x32_bf16 v[104:107], v[172:175], v[180:183], v[104:107]
	v_mfma_f32_16x16x32_bf16 v[96:99], v[164:167], v[192:195], v[96:99]
	v_mfma_f32_16x16x32_bf16 v[88:91], v[172:175], v[192:195], v[88:91]
	v_mfma_f32_16x16x32_bf16 v[80:83], v[164:167], v[200:203], v[80:83]
	v_mfma_f32_16x16x32_bf16 v[72:75], v[172:175], v[200:203], v[72:75]
	v_mfma_f32_16x16x32_bf16 v[68:71], v[164:167], v[208:211], v[68:71]
	v_mfma_f32_16x16x32_bf16 v[64:67], v[172:175], v[208:211], v[64:67]
	v_mfma_f32_16x16x32_bf16 v[112:115], v[168:171], v[184:187], v[112:115]
	v_mfma_f32_16x16x32_bf16 v[104:107], v[176:179], v[184:187], v[104:107]
	v_mfma_f32_16x16x32_bf16 v[96:99], v[168:171], v[196:199], v[96:99]
	v_mfma_f32_16x16x32_bf16 v[88:91], v[176:179], v[196:199], v[88:91]
	v_mfma_f32_16x16x32_bf16 v[80:83], v[168:171], v[204:207], v[80:83]
	v_mfma_f32_16x16x32_bf16 v[72:75], v[176:179], v[204:207], v[72:75]
	v_mfma_f32_16x16x32_bf16 v[68:71], v[168:171], v[212:215], v[68:71]
	v_mfma_f32_16x16x32_bf16 v[64:67], v[176:179], v[212:215], v[64:67]
	s_setprio 0
	s_barrier
	s_mov_b32 m0, s90
	v_lshl_add_u64 v[140:141], v[140:141], 0, s[10:11]
	ds_read_b128 v[180:183], v147 offset:49152
	ds_read_b128 v[184:187], v147 offset:50176
	ds_read_b128 v[192:195], v147 offset:51200
	ds_read_b128 v[196:199], v147 offset:52224
	ds_read_b128 v[200:203], v147 offset:53248
	ds_read_b128 v[204:207], v147 offset:54272
	ds_read_b128 v[208:211], v147 offset:55296
	ds_read_b128 v[212:215], v147 offset:56320
	global_load_lds_dwordx4 v[140:141], off
	v_lshl_add_u64 v[140:141], v[188:189], 0, s[10:11]
	s_mov_b32 m0, s88
	s_nop 0
	global_load_lds_dwordx4 v[140:141], off
	s_mov_b32 m0, s89
	s_nop 0
	global_load_lds_dwordx4 v130, s[42:43]
	s_mov_b32 m0, s87
	s_nop 0
	global_load_lds_dwordx4 v134, s[42:43]
	v_lshl_add_u64 v[140:141], v[216:217], 0, s[10:11]
	s_mov_b32 m0, s77
	s_nop 0
	global_load_lds_dwordx4 v[140:141], off
	v_lshl_add_u64 v[140:141], v[218:219], 0, s[10:11]
	s_mov_b32 m0, s79
	s_nop 0
	global_load_lds_dwordx4 v[140:141], off
	s_waitcnt vmcnt(8)
	s_waitcnt lgkmcnt(0)
	s_barrier
	s_setprio 1
	s_waitcnt lgkmcnt(0)
	v_mfma_f32_16x16x32_bf16 v[60:63], v[148:151], v[180:183], v[60:63]
	v_mfma_f32_16x16x32_bf16 v[56:59], v[156:159], v[180:183], v[56:59]
	v_mfma_f32_16x16x32_bf16 v[52:55], v[148:151], v[192:195], v[52:55]
	v_mfma_f32_16x16x32_bf16 v[44:47], v[156:159], v[192:195], v[44:47]
	v_mfma_f32_16x16x32_bf16 v[36:39], v[148:151], v[200:203], v[36:39]
	v_mfma_f32_16x16x32_bf16 v[28:31], v[156:159], v[200:203], v[28:31]
	v_mfma_f32_16x16x32_bf16 v[20:23], v[148:151], v[208:211], v[20:23]
	v_mfma_f32_16x16x32_bf16 v[12:15], v[156:159], v[208:211], v[12:15]
	v_mfma_f32_16x16x32_bf16 v[60:63], v[152:155], v[184:187], v[60:63]
	v_mfma_f32_16x16x32_bf16 v[56:59], v[160:163], v[184:187], v[56:59]
	v_mfma_f32_16x16x32_bf16 v[52:55], v[152:155], v[196:199], v[52:55]
	v_mfma_f32_16x16x32_bf16 v[44:47], v[160:163], v[196:199], v[44:47]
	v_mfma_f32_16x16x32_bf16 v[36:39], v[152:155], v[204:207], v[36:39]
	v_mfma_f32_16x16x32_bf16 v[28:31], v[160:163], v[204:207], v[28:31]
	v_mfma_f32_16x16x32_bf16 v[20:23], v[152:155], v[212:215], v[20:23]
	v_mfma_f32_16x16x32_bf16 v[12:15], v[160:163], v[212:215], v[12:15]
	s_setprio 0
	s_setprio 1
	v_mfma_f32_16x16x32_bf16 v[48:51], v[164:167], v[180:183], v[48:51]
	v_mfma_f32_16x16x32_bf16 v[40:43], v[172:175], v[180:183], v[40:43]
	v_mfma_f32_16x16x32_bf16 v[32:35], v[164:167], v[192:195], v[32:35]
	v_mfma_f32_16x16x32_bf16 v[24:27], v[172:175], v[192:195], v[24:27]
	v_mfma_f32_16x16x32_bf16 v[16:19], v[164:167], v[200:203], v[16:19]
	v_mfma_f32_16x16x32_bf16 v[8:11], v[172:175], v[200:203], v[8:11]
	v_mfma_f32_16x16x32_bf16 v[4:7], v[164:167], v[208:211], v[4:7]
	v_mfma_f32_16x16x32_bf16 v[0:3], v[172:175], v[208:211], v[0:3]
	v_mfma_f32_16x16x32_bf16 v[48:51], v[168:171], v[184:187], v[48:51]
	v_mfma_f32_16x16x32_bf16 v[40:43], v[176:179], v[184:187], v[40:43]
	v_mfma_f32_16x16x32_bf16 v[32:35], v[168:171], v[196:199], v[32:35]
	v_mfma_f32_16x16x32_bf16 v[24:27], v[176:179], v[196:199], v[24:27]
	v_mfma_f32_16x16x32_bf16 v[16:19], v[168:171], v[204:207], v[16:19]
	v_mfma_f32_16x16x32_bf16 v[8:11], v[176:179], v[204:207], v[8:11]
	v_mfma_f32_16x16x32_bf16 v[4:7], v[168:171], v[212:215], v[4:7]
	v_mfma_f32_16x16x32_bf16 v[0:3], v[176:179], v[212:215], v[0:3]
	s_setprio 0
	s_barrier
	s_movk_i32 s60, 0x100
	s_andn2_b64 vcc, exec, s[34:35]
	s_mov_b64 s[42:43], -1
	s_mov_b64 s[34:35], 0
	s_cbranch_vccz .LBB0_1246
	s_branch .Lpeel_exit8

.LBB0_1265:
	s_add_u32 s65, s18, 0x100
	s_addc_u32 s66, s19, 0
	s_mov_b32 s67, -2
	ds_read_b128 v[144:147], v151
	ds_read_b128 v[154:157], v151 offset:1024
	ds_read_b128 v[158:161], v151 offset:2048
	ds_read_b128 v[162:165], v151 offset:3072
	ds_read_b128 v[166:169], v152
	ds_read_b128 v[170:173], v152 offset:1024
	ds_read_b128 v[174:177], v152 offset:2048
	ds_read_b128 v[178:181], v152 offset:3072
	s_add_u32 s18, s16, 0x100
	s_addc_u32 s19, s17, 0
	s_cmp_eq_u32 s67, 2
	s_cselect_b32 s23, s5, s19
	s_cselect_b32 s22, s4, s18
	s_cselect_b32 s21, s15, s66
	s_cselect_b32 s20, s14, s65
	v_lshl_add_u64 v[216:217], s[16:17], 0, v[136:137]
	s_add_i32 m0, s31, 0xc000
	ds_read_b128 v[182:185], v153
	ds_read_b128 v[186:189], v153 offset:1024
	ds_read_b128 v[192:195], v153 offset:2048
	ds_read_b128 v[196:199], v153 offset:3072
	ds_read_b128 v[200:203], v153 offset:4096
	ds_read_b128 v[204:207], v153 offset:5120
	ds_read_b128 v[208:211], v153 offset:6144
	ds_read_b128 v[212:215], v153 offset:7168
	global_load_lds_dwordx4 v[216:217], off
	v_lshl_add_u64 v[216:217], s[16:17], 0, v[138:139]
	s_add_i32 m0, s31, 0xe000
	s_nop 0
	global_load_lds_dwordx4 v[216:217], off
	s_waitcnt vmcnt(8)
	s_waitcnt lgkmcnt(0)
	s_barrier
	s_setprio 1
	s_waitcnt lgkmcnt(0)
	v_mfma_f32_16x16x32_bf16 v[124:127], v[144:147], v[182:185], 0
	v_mfma_f32_16x16x32_bf16 v[120:123], v[158:161], v[182:185], 0
	v_mfma_f32_16x16x32_bf16 v[116:119], v[144:147], v[192:195], 0
	v_mfma_f32_16x16x32_bf16 v[108:111], v[158:161], v[192:195], 0
	v_mfma_f32_16x16x32_bf16 v[100:103], v[144:147], v[200:203], 0
	v_mfma_f32_16x16x32_bf16 v[92:95], v[158:161], v[200:203], 0
	v_mfma_f32_16x16x32_bf16 v[84:87], v[144:147], v[208:211], 0
	v_mfma_f32_16x16x32_bf16 v[76:79], v[158:161], v[208:211], 0
	v_mfma_f32_16x16x32_bf16 v[124:127], v[154:157], v[186:189], v[124:127]
	v_mfma_f32_16x16x32_bf16 v[120:123], v[162:165], v[186:189], v[120:123]
	v_mfma_f32_16x16x32_bf16 v[116:119], v[154:157], v[196:199], v[116:119]
	v_mfma_f32_16x16x32_bf16 v[108:111], v[162:165], v[196:199], v[108:111]
	v_mfma_f32_16x16x32_bf16 v[100:103], v[154:157], v[204:207], v[100:103]
	v_mfma_f32_16x16x32_bf16 v[92:95], v[162:165], v[204:207], v[92:95]
	v_mfma_f32_16x16x32_bf16 v[84:87], v[154:157], v[212:215], v[84:87]
	v_mfma_f32_16x16x32_bf16 v[76:79], v[162:165], v[212:215], v[76:79]
	s_setprio 0
	s_setprio 1
	v_mfma_f32_16x16x32_bf16 v[112:115], v[166:169], v[182:185], 0
	v_mfma_f32_16x16x32_bf16 v[104:107], v[174:177], v[182:185], 0
	v_mfma_f32_16x16x32_bf16 v[96:99], v[166:169], v[192:195], 0
	v_mfma_f32_16x16x32_bf16 v[88:91], v[174:177], v[192:195], 0
	v_mfma_f32_16x16x32_bf16 v[80:83], v[166:169], v[200:203], 0
	v_mfma_f32_16x16x32_bf16 v[72:75], v[174:177], v[200:203], 0
	v_mfma_f32_16x16x32_bf16 v[68:71], v[166:169], v[208:211], 0
	v_mfma_f32_16x16x32_bf16 v[64:67], v[174:177], v[208:211], 0
	v_mfma_f32_16x16x32_bf16 v[112:115], v[170:173], v[186:189], v[112:115]
	v_mfma_f32_16x16x32_bf16 v[104:107], v[178:181], v[186:189], v[104:107]
	v_mfma_f32_16x16x32_bf16 v[96:99], v[170:173], v[196:199], v[96:99]
	v_mfma_f32_16x16x32_bf16 v[88:91], v[178:181], v[196:199], v[88:91]
	v_mfma_f32_16x16x32_bf16 v[80:83], v[170:173], v[204:207], v[80:83]
	v_mfma_f32_16x16x32_bf16 v[72:75], v[178:181], v[204:207], v[72:75]
	v_mfma_f32_16x16x32_bf16 v[68:71], v[170:173], v[212:215], v[68:71]
	v_mfma_f32_16x16x32_bf16 v[64:67], v[178:181], v[212:215], v[64:67]
	s_setprio 0
	s_barrier
	s_add_i32 s16, s60, s28
	v_lshl_add_u64 v[216:217], s[20:21], 0, v[132:133]
	s_mov_b32 m0, s16
	ds_read_b128 v[182:185], v153 offset:16384
	ds_read_b128 v[186:189], v153 offset:17408
	ds_read_b128 v[192:195], v153 offset:18432
	ds_read_b128 v[196:199], v153 offset:19456
	ds_read_b128 v[200:203], v153 offset:20480
	ds_read_b128 v[204:207], v153 offset:21504
	ds_read_b128 v[208:211], v153 offset:22528
	ds_read_b128 v[212:215], v153 offset:23552
	global_load_lds_dwordx4 v[216:217], off
	s_add_i32 m0, s16, 0x2000
	s_add_u32 s16, s20, 0x18000
	v_lshl_add_u64 v[218:219], s[20:21], 0, v[128:129]
	s_addc_u32 s17, s21, 0
	s_add_i32 s68, s61, s28
	global_load_lds_dwordx4 v[218:219], off
	s_mov_b32 m0, s68
	v_lshl_add_u64 v[222:223], s[22:23], 0, v[130:131]
	global_load_lds_dwordx4 v132, s[16:17]
	s_add_i32 m0, s68, 0x2000
	s_nop 0
	global_load_lds_dwordx4 v128, s[16:17]
	v_lshl_add_u64 v[220:221], s[22:23], 0, v[134:135]
	s_mov_b32 m0, s31
	s_nop 0
	global_load_lds_dwordx4 v[220:221], off
	s_mov_b32 m0, s33
	s_nop 0
	global_load_lds_dwordx4 v[222:223], off
	s_waitcnt vmcnt(8)
	s_waitcnt lgkmcnt(0)
	s_barrier
	s_setprio 1
	s_waitcnt lgkmcnt(0)
	v_mfma_f32_16x16x32_bf16 v[60:63], v[144:147], v[182:185], 0
	v_mfma_f32_16x16x32_bf16 v[56:59], v[158:161], v[182:185], 0
	v_mfma_f32_16x16x32_bf16 v[52:55], v[144:147], v[192:195], 0
	v_mfma_f32_16x16x32_bf16 v[44:47], v[158:161], v[192:195], 0
	v_mfma_f32_16x16x32_bf16 v[36:39], v[144:147], v[200:203], 0
	v_mfma_f32_16x16x32_bf16 v[28:31], v[158:161], v[200:203], 0
	v_mfma_f32_16x16x32_bf16 v[20:23], v[144:147], v[208:211], 0
	v_mfma_f32_16x16x32_bf16 v[12:15], v[158:161], v[208:211], 0
	v_mfma_f32_16x16x32_bf16 v[60:63], v[154:157], v[186:189], v[60:63]
	v_mfma_f32_16x16x32_bf16 v[56:59], v[162:165], v[186:189], v[56:59]
	v_mfma_f32_16x16x32_bf16 v[52:55], v[154:157], v[196:199], v[52:55]
	v_mfma_f32_16x16x32_bf16 v[44:47], v[162:165], v[196:199], v[44:47]
	v_mfma_f32_16x16x32_bf16 v[36:39], v[154:157], v[204:207], v[36:39]
	v_mfma_f32_16x16x32_bf16 v[28:31], v[162:165], v[204:207], v[28:31]
	v_mfma_f32_16x16x32_bf16 v[20:23], v[154:157], v[212:215], v[20:23]
	v_mfma_f32_16x16x32_bf16 v[12:15], v[162:165], v[212:215], v[12:15]
	s_setprio 0
	s_setprio 1
	v_mfma_f32_16x16x32_bf16 v[48:51], v[166:169], v[182:185], 0
	v_mfma_f32_16x16x32_bf16 v[40:43], v[174:177], v[182:185], 0
	v_mfma_f32_16x16x32_bf16 v[32:35], v[166:169], v[192:195], 0
	v_mfma_f32_16x16x32_bf16 v[24:27], v[174:177], v[192:195], 0
	v_mfma_f32_16x16x32_bf16 v[16:19], v[166:169], v[200:203], 0
	v_mfma_f32_16x16x32_bf16 v[8:11], v[174:177], v[200:203], 0
	v_mfma_f32_16x16x32_bf16 v[4:7], v[166:169], v[208:211], 0
	v_mfma_f32_16x16x32_bf16 v[0:3], v[174:177], v[208:211], 0
	v_mfma_f32_16x16x32_bf16 v[48:51], v[170:173], v[186:189], v[48:51]
	v_mfma_f32_16x16x32_bf16 v[40:43], v[178:181], v[186:189], v[40:43]
	v_mfma_f32_16x16x32_bf16 v[32:35], v[170:173], v[196:199], v[32:35]
	v_mfma_f32_16x16x32_bf16 v[24:27], v[178:181], v[196:199], v[24:27]
	v_mfma_f32_16x16x32_bf16 v[16:19], v[170:173], v[204:207], v[16:19]
	v_mfma_f32_16x16x32_bf16 v[8:11], v[178:181], v[204:207], v[8:11]
	v_mfma_f32_16x16x32_bf16 v[4:7], v[170:173], v[212:215], v[4:7]
	v_mfma_f32_16x16x32_bf16 v[0:3], v[178:181], v[212:215], v[0:3]
	s_setprio 0
	s_barrier
	s_add_i32 s68, 0, 0x18000
	s_add_i32 s69, 0, 0x1c000
	v_add_u32_e32 v162, s68, v149
	v_add_u32_e32 v178, s69, v149
	ds_read_b128 v[144:147], v162
	ds_read_b128 v[154:157], v162 offset:1024
	ds_read_b128 v[158:161], v162 offset:2048
	ds_read_b128 v[162:165], v162 offset:3072
	ds_read_b128 v[166:169], v178
	ds_read_b128 v[170:173], v178 offset:1024
	ds_read_b128 v[174:177], v178 offset:2048
	ds_read_b128 v[178:181], v178 offset:3072
	s_add_u32 s16, s22, 0x18000
	s_addc_u32 s17, s23, 0
	s_mov_b32 m0, s34
	ds_read_b128 v[182:185], v153 offset:32768
	ds_read_b128 v[186:189], v153 offset:33792
	ds_read_b128 v[192:195], v153 offset:34816
	ds_read_b128 v[196:199], v153 offset:35840
	ds_read_b128 v[200:203], v153 offset:36864
	ds_read_b128 v[204:207], v153 offset:37888
	ds_read_b128 v[208:211], v153 offset:38912
	ds_read_b128 v[212:215], v153 offset:39936
	global_load_lds_dwordx4 v134, s[16:17]
	s_mov_b32 m0, s35
	s_nop 0
	global_load_lds_dwordx4 v130, s[16:17]
	s_waitcnt vmcnt(8)
	s_waitcnt lgkmcnt(0)
	s_barrier
	s_setprio 1
	s_waitcnt lgkmcnt(0)
	v_mfma_f32_16x16x32_bf16 v[124:127], v[144:147], v[182:185], v[124:127]
	v_mfma_f32_16x16x32_bf16 v[120:123], v[158:161], v[182:185], v[120:123]
	v_mfma_f32_16x16x32_bf16 v[116:119], v[144:147], v[192:195], v[116:119]
	v_mfma_f32_16x16x32_bf16 v[108:111], v[158:161], v[192:195], v[108:111]
	v_mfma_f32_16x16x32_bf16 v[100:103], v[144:147], v[200:203], v[100:103]
	v_mfma_f32_16x16x32_bf16 v[92:95], v[158:161], v[200:203], v[92:95]
	v_mfma_f32_16x16x32_bf16 v[84:87], v[144:147], v[208:211], v[84:87]
	v_mfma_f32_16x16x32_bf16 v[76:79], v[158:161], v[208:211], v[76:79]
	v_mfma_f32_16x16x32_bf16 v[124:127], v[154:157], v[186:189], v[124:127]
	v_mfma_f32_16x16x32_bf16 v[120:123], v[162:165], v[186:189], v[120:123]
	v_mfma_f32_16x16x32_bf16 v[116:119], v[154:157], v[196:199], v[116:119]
	v_mfma_f32_16x16x32_bf16 v[108:111], v[162:165], v[196:199], v[108:111]
	v_mfma_f32_16x16x32_bf16 v[100:103], v[154:157], v[204:207], v[100:103]
	v_mfma_f32_16x16x32_bf16 v[92:95], v[162:165], v[204:207], v[92:95]
	v_mfma_f32_16x16x32_bf16 v[84:87], v[154:157], v[212:215], v[84:87]
	v_mfma_f32_16x16x32_bf16 v[76:79], v[162:165], v[212:215], v[76:79]
	s_setprio 0
	s_setprio 1
	v_mfma_f32_16x16x32_bf16 v[112:115], v[166:169], v[182:185], v[112:115]
	v_mfma_f32_16x16x32_bf16 v[104:107], v[174:177], v[182:185], v[104:107]
	v_mfma_f32_16x16x32_bf16 v[96:99], v[166:169], v[192:195], v[96:99]
	v_mfma_f32_16x16x32_bf16 v[88:91], v[174:177], v[192:195], v[88:91]
	v_mfma_f32_16x16x32_bf16 v[80:83], v[166:169], v[200:203], v[80:83]
	v_mfma_f32_16x16x32_bf16 v[72:75], v[174:177], v[200:203], v[72:75]
	v_mfma_f32_16x16x32_bf16 v[68:71], v[166:169], v[208:211], v[68:71]
	v_mfma_f32_16x16x32_bf16 v[64:67], v[174:177], v[208:211], v[64:67]
	v_mfma_f32_16x16x32_bf16 v[112:115], v[170:173], v[186:189], v[112:115]
	v_mfma_f32_16x16x32_bf16 v[104:107], v[178:181], v[186:189], v[104:107]
	v_mfma_f32_16x16x32_bf16 v[96:99], v[170:173], v[196:199], v[96:99]
	v_mfma_f32_16x16x32_bf16 v[88:91], v[178:181], v[196:199], v[88:91]
	v_mfma_f32_16x16x32_bf16 v[80:83], v[170:173], v[204:207], v[80:83]
	v_mfma_f32_16x16x32_bf16 v[72:75], v[178:181], v[204:207], v[72:75]
	v_mfma_f32_16x16x32_bf16 v[68:71], v[170:173], v[212:215], v[68:71]
	v_mfma_f32_16x16x32_bf16 v[64:67], v[178:181], v[212:215], v[64:67]
	s_setprio 0
	s_barrier
	s_add_i32 s16, s68, s28
	v_lshl_add_u64 v[216:217], v[216:217], 0, s[10:11]
	s_mov_b32 m0, s16
	ds_read_b128 v[182:185], v153 offset:49152
	ds_read_b128 v[186:189], v153 offset:50176
	ds_read_b128 v[192:195], v153 offset:51200
	ds_read_b128 v[196:199], v153 offset:52224
	ds_read_b128 v[200:203], v153 offset:53248
	ds_read_b128 v[204:207], v153 offset:54272
	ds_read_b128 v[208:211], v153 offset:55296
	ds_read_b128 v[212:215], v153 offset:56320
	global_load_lds_dwordx4 v[216:217], off
	s_add_i32 m0, s16, 0x2000
	s_add_u32 s16, s20, 0x18080
	v_lshl_add_u64 v[216:217], v[218:219], 0, s[10:11]
	s_addc_u32 s17, s21, 0
	s_add_i32 s20, s69, s28
	global_load_lds_dwordx4 v[216:217], off
	s_mov_b32 m0, s20
	s_nop 0
	global_load_lds_dwordx4 v132, s[16:17]
	s_add_i32 m0, s20, 0x2000
	s_nop 0
	global_load_lds_dwordx4 v128, s[16:17]
	v_lshl_add_u64 v[216:217], v[220:221], 0, s[10:11]
	s_mov_b32 m0, s43
	s_nop 0
	global_load_lds_dwordx4 v[216:217], off
	v_lshl_add_u64 v[216:217], v[222:223], 0, s[10:11]
	s_mov_b32 m0, s52
	s_nop 0
	global_load_lds_dwordx4 v[216:217], off
	s_waitcnt vmcnt(8)
	s_waitcnt lgkmcnt(0)
	s_barrier
	s_setprio 1
	s_waitcnt lgkmcnt(0)
	v_mfma_f32_16x16x32_bf16 v[60:63], v[144:147], v[182:185], v[60:63]
	v_mfma_f32_16x16x32_bf16 v[56:59], v[158:161], v[182:185], v[56:59]
	v_mfma_f32_16x16x32_bf16 v[52:55], v[144:147], v[192:195], v[52:55]
	v_mfma_f32_16x16x32_bf16 v[44:47], v[158:161], v[192:195], v[44:47]
	v_mfma_f32_16x16x32_bf16 v[36:39], v[144:147], v[200:203], v[36:39]
	v_mfma_f32_16x16x32_bf16 v[28:31], v[158:161], v[200:203], v[28:31]
	v_mfma_f32_16x16x32_bf16 v[20:23], v[144:147], v[208:211], v[20:23]
	v_mfma_f32_16x16x32_bf16 v[12:15], v[158:161], v[208:211], v[12:15]
	v_mfma_f32_16x16x32_bf16 v[60:63], v[154:157], v[186:189], v[60:63]
	v_mfma_f32_16x16x32_bf16 v[56:59], v[162:165], v[186:189], v[56:59]
	v_mfma_f32_16x16x32_bf16 v[52:55], v[154:157], v[196:199], v[52:55]
	v_mfma_f32_16x16x32_bf16 v[44:47], v[162:165], v[196:199], v[44:47]
	v_mfma_f32_16x16x32_bf16 v[36:39], v[154:157], v[204:207], v[36:39]
	v_mfma_f32_16x16x32_bf16 v[28:31], v[162:165], v[204:207], v[28:31]
	v_mfma_f32_16x16x32_bf16 v[20:23], v[154:157], v[212:215], v[20:23]
	v_mfma_f32_16x16x32_bf16 v[12:15], v[162:165], v[212:215], v[12:15]
	s_setprio 0
	s_setprio 1
	v_mfma_f32_16x16x32_bf16 v[48:51], v[166:169], v[182:185], v[48:51]
	v_mfma_f32_16x16x32_bf16 v[40:43], v[174:177], v[182:185], v[40:43]
	v_mfma_f32_16x16x32_bf16 v[32:35], v[166:169], v[192:195], v[32:35]
	v_mfma_f32_16x16x32_bf16 v[24:27], v[174:177], v[192:195], v[24:27]
	v_mfma_f32_16x16x32_bf16 v[16:19], v[166:169], v[200:203], v[16:19]
	v_mfma_f32_16x16x32_bf16 v[8:11], v[174:177], v[200:203], v[8:11]
	v_mfma_f32_16x16x32_bf16 v[4:7], v[166:169], v[208:211], v[4:7]
	v_mfma_f32_16x16x32_bf16 v[0:3], v[174:177], v[208:211], v[0:3]
	v_mfma_f32_16x16x32_bf16 v[48:51], v[170:173], v[186:189], v[48:51]
	v_mfma_f32_16x16x32_bf16 v[40:43], v[178:181], v[186:189], v[40:43]
	v_mfma_f32_16x16x32_bf16 v[32:35], v[170:173], v[196:199], v[32:35]
	v_mfma_f32_16x16x32_bf16 v[24:27], v[178:181], v[196:199], v[24:27]
	v_mfma_f32_16x16x32_bf16 v[16:19], v[170:173], v[204:207], v[16:19]
	v_mfma_f32_16x16x32_bf16 v[8:11], v[178:181], v[204:207], v[8:11]
	v_mfma_f32_16x16x32_bf16 v[4:7], v[170:173], v[212:215], v[4:7]
	v_mfma_f32_16x16x32_bf16 v[0:3], v[178:181], v[212:215], v[0:3]
	s_setprio 0
	s_barrier
	s_add_i32 s67, s67, 2
	s_add_u32 s65, s65, 0x100
	s_addc_u32 s66, s66, 0
	s_cmp_gt_u32 s67, 3
	s_mov_b64 s[16:17], s[18:19]
	s_cbranch_scc0 .LBB0_1266
	s_branch .Lpeel_exit9

.LBB0_1433:
	s_ashr_i32 s23, s22, 31
	s_lshl_b64 s[24:25], s[22:23], 19
	s_add_u32 s24, s56, s24
	s_addc_u32 s25, s57, s25
	s_and_b64 s[26:27], s[0:1], exec
	s_cselect_b32 s23, s25, s31
	s_cselect_b32 s55, s24, s30
	s_ashr_i32 s21, s20, 31
	s_lshl_b64 s[26:27], s[20:21], 19
	s_add_u32 s26, s53, s26
	s_addc_u32 s27, s60, s27
	s_and_b64 s[42:43], s[0:1], exec
	s_cselect_b32 s21, s27, s35
	s_cselect_b32 s74, s26, s34
	s_add_u32 s30, s30, 0x40080
	s_addc_u32 s31, s31, 0
	s_add_u32 s75, s34, 0x100
	s_addc_u32 s76, s35, 0
	s_mov_b32 s77, -2
	ds_read_b128 v[152:155], v149
	ds_read_b128 v[156:159], v149 offset:1024
	ds_read_b128 v[160:163], v149 offset:2048
	ds_read_b128 v[164:167], v149 offset:3072
	ds_read_b128 v[168:171], v150
	ds_read_b128 v[172:175], v150 offset:1024
	ds_read_b128 v[176:179], v150 offset:2048
	ds_read_b128 v[180:183], v150 offset:3072
	s_add_u32 s34, s30, 0xfffc0080
	s_addc_u32 s35, s31, -1
	s_cmp_eq_u32 s77, 12
	s_cselect_b32 s43, s23, s35
	s_cselect_b32 s42, s55, s34
	s_cselect_b32 s35, s21, s76
	s_cselect_b32 s34, s74, s75
	s_add_i32 m0, s29, 0xc000
	ds_read_b128 v[184:187], v151
	ds_read_b128 v[192:195], v151 offset:1024
	ds_read_b128 v[196:199], v151 offset:2048
	ds_read_b128 v[200:203], v151 offset:3072
	ds_read_b128 v[204:207], v151 offset:4096
	ds_read_b128 v[208:211], v151 offset:5120
	ds_read_b128 v[212:215], v151 offset:6144
	ds_read_b128 v[216:219], v151 offset:7168
	global_load_lds_dwordx4 v136, s[30:31]
	s_add_i32 m0, s29, 0xe000
	s_nop 0
	global_load_lds_dwordx4 v138, s[30:31]
	s_waitcnt vmcnt(8)
	s_waitcnt lgkmcnt(0)
	s_barrier
	s_setprio 1
	s_waitcnt lgkmcnt(0)
	v_mfma_f32_16x16x32_bf16 v[124:127], v[152:155], v[184:187], 0
	v_mfma_f32_16x16x32_bf16 v[120:123], v[160:163], v[184:187], 0
	v_mfma_f32_16x16x32_bf16 v[116:119], v[152:155], v[196:199], 0
	v_mfma_f32_16x16x32_bf16 v[108:111], v[160:163], v[196:199], 0
	v_mfma_f32_16x16x32_bf16 v[100:103], v[152:155], v[204:207], 0
	v_mfma_f32_16x16x32_bf16 v[92:95], v[160:163], v[204:207], 0
	v_mfma_f32_16x16x32_bf16 v[84:87], v[152:155], v[212:215], 0
	v_mfma_f32_16x16x32_bf16 v[76:79], v[160:163], v[212:215], 0
	v_mfma_f32_16x16x32_bf16 v[124:127], v[156:159], v[192:195], v[124:127]
	v_mfma_f32_16x16x32_bf16 v[120:123], v[164:167], v[192:195], v[120:123]
	v_mfma_f32_16x16x32_bf16 v[116:119], v[156:159], v[200:203], v[116:119]
	v_mfma_f32_16x16x32_bf16 v[108:111], v[164:167], v[200:203], v[108:111]
	v_mfma_f32_16x16x32_bf16 v[100:103], v[156:159], v[208:211], v[100:103]
	v_mfma_f32_16x16x32_bf16 v[92:95], v[164:167], v[208:211], v[92:95]
	v_mfma_f32_16x16x32_bf16 v[84:87], v[156:159], v[216:219], v[84:87]
	v_mfma_f32_16x16x32_bf16 v[76:79], v[164:167], v[216:219], v[76:79]
	s_setprio 0
	s_setprio 1
	v_mfma_f32_16x16x32_bf16 v[112:115], v[168:171], v[184:187], 0
	v_mfma_f32_16x16x32_bf16 v[104:107], v[176:179], v[184:187], 0
	v_mfma_f32_16x16x32_bf16 v[96:99], v[168:171], v[196:199], 0
	v_mfma_f32_16x16x32_bf16 v[88:91], v[176:179], v[196:199], 0
	v_mfma_f32_16x16x32_bf16 v[80:83], v[168:171], v[204:207], 0
	v_mfma_f32_16x16x32_bf16 v[72:75], v[176:179], v[204:207], 0
	v_mfma_f32_16x16x32_bf16 v[68:71], v[168:171], v[212:215], 0
	v_mfma_f32_16x16x32_bf16 v[64:67], v[176:179], v[212:215], 0
	v_mfma_f32_16x16x32_bf16 v[112:115], v[172:175], v[192:195], v[112:115]
	v_mfma_f32_16x16x32_bf16 v[104:107], v[180:183], v[192:195], v[104:107]
	v_mfma_f32_16x16x32_bf16 v[96:99], v[172:175], v[200:203], v[96:99]
	v_mfma_f32_16x16x32_bf16 v[88:91], v[180:183], v[200:203], v[88:91]
	v_mfma_f32_16x16x32_bf16 v[80:83], v[172:175], v[208:211], v[80:83]
	v_mfma_f32_16x16x32_bf16 v[72:75], v[180:183], v[208:211], v[72:75]
	v_mfma_f32_16x16x32_bf16 v[68:71], v[172:175], v[216:219], v[68:71]
	v_mfma_f32_16x16x32_bf16 v[64:67], v[180:183], v[216:219], v[64:67]
	s_setprio 0
	s_barrier
	s_add_i32 s79, s68, s61
	v_lshl_add_u64 v[144:145], s[34:35], 0, v[130:131]
	s_mov_b32 m0, s79
	ds_read_b128 v[184:187], v151 offset:16384
	ds_read_b128 v[192:195], v151 offset:17408
	ds_read_b128 v[196:199], v151 offset:18432
	ds_read_b128 v[200:203], v151 offset:19456
	ds_read_b128 v[204:207], v151 offset:20480
	ds_read_b128 v[208:211], v151 offset:21504
	ds_read_b128 v[212:215], v151 offset:22528
	ds_read_b128 v[216:219], v151 offset:23552
	global_load_lds_dwordx4 v[144:145], off
	s_add_i32 m0, s79, 0x2000
	s_add_u32 s80, s34, 0x40000
	v_lshl_add_u64 v[188:189], s[34:35], 0, v[134:135]
	s_addc_u32 s81, s35, 0
	s_add_i32 s79, s69, s61
	global_load_lds_dwordx4 v[188:189], off
	s_mov_b32 m0, s79
	v_lshl_add_u64 v[222:223], s[42:43], 0, v[132:133]
	global_load_lds_dwordx4 v130, s[80:81]
	s_add_i32 m0, s79, 0x2000
	s_nop 0
	global_load_lds_dwordx4 v134, s[80:81]
	v_lshl_add_u64 v[220:221], s[42:43], 0, v[128:129]
	s_mov_b32 m0, s29
	s_nop 0
	global_load_lds_dwordx4 v[220:221], off
	s_mov_b32 m0, s33
	s_nop 0
	global_load_lds_dwordx4 v[222:223], off
	s_waitcnt vmcnt(8)
	s_waitcnt lgkmcnt(0)
	s_barrier
	s_setprio 1
	s_waitcnt lgkmcnt(0)
	v_mfma_f32_16x16x32_bf16 v[60:63], v[152:155], v[184:187], 0
	v_mfma_f32_16x16x32_bf16 v[56:59], v[160:163], v[184:187], 0
	v_mfma_f32_16x16x32_bf16 v[52:55], v[152:155], v[196:199], 0
	v_mfma_f32_16x16x32_bf16 v[44:47], v[160:163], v[196:199], 0
	v_mfma_f32_16x16x32_bf16 v[36:39], v[152:155], v[204:207], 0
	v_mfma_f32_16x16x32_bf16 v[28:31], v[160:163], v[204:207], 0
	v_mfma_f32_16x16x32_bf16 v[20:23], v[152:155], v[212:215], 0
	v_mfma_f32_16x16x32_bf16 v[12:15], v[160:163], v[212:215], 0
	v_mfma_f32_16x16x32_bf16 v[60:63], v[156:159], v[192:195], v[60:63]
	v_mfma_f32_16x16x32_bf16 v[56:59], v[164:167], v[192:195], v[56:59]
	v_mfma_f32_16x16x32_bf16 v[52:55], v[156:159], v[200:203], v[52:55]
	v_mfma_f32_16x16x32_bf16 v[44:47], v[164:167], v[200:203], v[44:47]
	v_mfma_f32_16x16x32_bf16 v[36:39], v[156:159], v[208:211], v[36:39]
	v_mfma_f32_16x16x32_bf16 v[28:31], v[164:167], v[208:211], v[28:31]
	v_mfma_f32_16x16x32_bf16 v[20:23], v[156:159], v[216:219], v[20:23]
	v_mfma_f32_16x16x32_bf16 v[12:15], v[164:167], v[216:219], v[12:15]
	s_setprio 0
	s_setprio 1
	v_mfma_f32_16x16x32_bf16 v[48:51], v[168:171], v[184:187], 0
	v_mfma_f32_16x16x32_bf16 v[40:43], v[176:179], v[184:187], 0
	v_mfma_f32_16x16x32_bf16 v[32:35], v[168:171], v[196:199], 0
	v_mfma_f32_16x16x32_bf16 v[24:27], v[176:179], v[196:199], 0
	v_mfma_f32_16x16x32_bf16 v[16:19], v[168:171], v[204:207], 0
	v_mfma_f32_16x16x32_bf16 v[8:11], v[176:179], v[204:207], 0
	v_mfma_f32_16x16x32_bf16 v[4:7], v[168:171], v[212:215], 0
	v_mfma_f32_16x16x32_bf16 v[0:3], v[176:179], v[212:215], 0
	v_mfma_f32_16x16x32_bf16 v[48:51], v[172:175], v[192:195], v[48:51]
	v_mfma_f32_16x16x32_bf16 v[40:43], v[180:183], v[192:195], v[40:43]
	v_mfma_f32_16x16x32_bf16 v[32:35], v[172:175], v[200:203], v[32:35]
	v_mfma_f32_16x16x32_bf16 v[24:27], v[180:183], v[200:203], v[24:27]
	v_mfma_f32_16x16x32_bf16 v[16:19], v[172:175], v[208:211], v[16:19]
	v_mfma_f32_16x16x32_bf16 v[8:11], v[180:183], v[208:211], v[8:11]
	v_mfma_f32_16x16x32_bf16 v[4:7], v[172:175], v[216:219], v[4:7]
	v_mfma_f32_16x16x32_bf16 v[0:3], v[180:183], v[216:219], v[0:3]
	s_setprio 0
	s_barrier
	s_add_i32 s79, 0, 0x18000
	s_add_i32 s80, 0, 0x1c000
	v_add_u32_e32 v164, s79, v147
	v_add_u32_e32 v180, s80, v147
	ds_read_b128 v[152:155], v164
	ds_read_b128 v[156:159], v164 offset:1024
	ds_read_b128 v[160:163], v164 offset:2048
	ds_read_b128 v[164:167], v164 offset:3072
	ds_read_b128 v[168:171], v180
	ds_read_b128 v[172:175], v180 offset:1024
	ds_read_b128 v[176:179], v180 offset:2048
	ds_read_b128 v[180:183], v180 offset:3072
	s_add_u32 s42, s42, 0x40000
	s_addc_u32 s43, s43, 0
	s_mov_b32 m0, s62
	ds_read_b128 v[184:187], v151 offset:32768
	ds_read_b128 v[192:195], v151 offset:33792
	ds_read_b128 v[196:199], v151 offset:34816
	ds_read_b128 v[200:203], v151 offset:35840
	ds_read_b128 v[204:207], v151 offset:36864
	ds_read_b128 v[208:211], v151 offset:37888
	ds_read_b128 v[212:215], v151 offset:38912
	ds_read_b128 v[216:219], v151 offset:39936
	global_load_lds_dwordx4 v128, s[42:43]
	s_mov_b32 m0, s63
	s_nop 0
	global_load_lds_dwordx4 v132, s[42:43]
	s_waitcnt vmcnt(8)
	s_waitcnt lgkmcnt(0)
	s_barrier
	s_setprio 1
	s_waitcnt lgkmcnt(0)
	v_mfma_f32_16x16x32_bf16 v[124:127], v[152:155], v[184:187], v[124:127]
	v_mfma_f32_16x16x32_bf16 v[120:123], v[160:163], v[184:187], v[120:123]
	v_mfma_f32_16x16x32_bf16 v[116:119], v[152:155], v[196:199], v[116:119]
	v_mfma_f32_16x16x32_bf16 v[108:111], v[160:163], v[196:199], v[108:111]
	v_mfma_f32_16x16x32_bf16 v[100:103], v[152:155], v[204:207], v[100:103]
	v_mfma_f32_16x16x32_bf16 v[92:95], v[160:163], v[204:207], v[92:95]
	v_mfma_f32_16x16x32_bf16 v[84:87], v[152:155], v[212:215], v[84:87]
	v_mfma_f32_16x16x32_bf16 v[76:79], v[160:163], v[212:215], v[76:79]
	v_mfma_f32_16x16x32_bf16 v[124:127], v[156:159], v[192:195], v[124:127]
	v_mfma_f32_16x16x32_bf16 v[120:123], v[164:167], v[192:195], v[120:123]
	v_mfma_f32_16x16x32_bf16 v[116:119], v[156:159], v[200:203], v[116:119]
	v_mfma_f32_16x16x32_bf16 v[108:111], v[164:167], v[200:203], v[108:111]
	v_mfma_f32_16x16x32_bf16 v[100:103], v[156:159], v[208:211], v[100:103]
	v_mfma_f32_16x16x32_bf16 v[92:95], v[164:167], v[208:211], v[92:95]
	v_mfma_f32_16x16x32_bf16 v[84:87], v[156:159], v[216:219], v[84:87]
	v_mfma_f32_16x16x32_bf16 v[76:79], v[164:167], v[216:219], v[76:79]
	s_setprio 0
	s_setprio 1
	v_mfma_f32_16x16x32_bf16 v[112:115], v[168:171], v[184:187], v[112:115]
	v_mfma_f32_16x16x32_bf16 v[104:107], v[176:179], v[184:187], v[104:107]
	v_mfma_f32_16x16x32_bf16 v[96:99], v[168:171], v[196:199], v[96:99]
	v_mfma_f32_16x16x32_bf16 v[88:91], v[176:179], v[196:199], v[88:91]
	v_mfma_f32_16x16x32_bf16 v[80:83], v[168:171], v[204:207], v[80:83]
	v_mfma_f32_16x16x32_bf16 v[72:75], v[176:179], v[204:207], v[72:75]
	v_mfma_f32_16x16x32_bf16 v[68:71], v[168:171], v[212:215], v[68:71]
	v_mfma_f32_16x16x32_bf16 v[64:67], v[176:179], v[212:215], v[64:67]
	v_mfma_f32_16x16x32_bf16 v[112:115], v[172:175], v[192:195], v[112:115]
	v_mfma_f32_16x16x32_bf16 v[104:107], v[180:183], v[192:195], v[104:107]
	v_mfma_f32_16x16x32_bf16 v[96:99], v[172:175], v[200:203], v[96:99]
	v_mfma_f32_16x16x32_bf16 v[88:91], v[180:183], v[200:203], v[88:91]
	v_mfma_f32_16x16x32_bf16 v[80:83], v[172:175], v[208:211], v[80:83]
	v_mfma_f32_16x16x32_bf16 v[72:75], v[180:183], v[208:211], v[72:75]
	v_mfma_f32_16x16x32_bf16 v[68:71], v[172:175], v[216:219], v[68:71]
	v_mfma_f32_16x16x32_bf16 v[64:67], v[180:183], v[216:219], v[64:67]
	s_setprio 0
	s_barrier
	s_add_i32 s42, s79, s61
	v_lshl_add_u64 v[144:145], v[144:145], 0, s[10:11]
	s_mov_b32 m0, s42
	ds_read_b128 v[184:187], v151 offset:49152
	ds_read_b128 v[192:195], v151 offset:50176
	ds_read_b128 v[196:199], v151 offset:51200
	ds_read_b128 v[200:203], v151 offset:52224
	ds_read_b128 v[204:207], v151 offset:53248
	ds_read_b128 v[208:211], v151 offset:54272
	ds_read_b128 v[212:215], v151 offset:55296
	ds_read_b128 v[216:219], v151 offset:56320
	global_load_lds_dwordx4 v[144:145], off
	s_add_i32 m0, s42, 0x2000
	s_add_u32 s34, s34, 0x40080
	v_lshl_add_u64 v[144:145], v[188:189], 0, s[10:11]
	s_addc_u32 s35, s35, 0
	s_add_i32 s42, s80, s61
	global_load_lds_dwordx4 v[144:145], off
	s_mov_b32 m0, s42
	s_nop 0
	global_load_lds_dwordx4 v130, s[34:35]
	s_add_i32 m0, s42, 0x2000
	s_nop 0
	global_load_lds_dwordx4 v134, s[34:35]
	v_lshl_add_u64 v[144:145], v[220:221], 0, s[10:11]
	s_mov_b32 m0, s65
	s_nop 0
	global_load_lds_dwordx4 v[144:145], off
	v_lshl_add_u64 v[144:145], v[222:223], 0, s[10:11]
	s_mov_b32 m0, s66
	s_nop 0
	global_load_lds_dwordx4 v[144:145], off
	s_waitcnt vmcnt(8)
	s_waitcnt lgkmcnt(0)
	s_barrier
	s_setprio 1
	s_waitcnt lgkmcnt(0)
	v_mfma_f32_16x16x32_bf16 v[60:63], v[152:155], v[184:187], v[60:63]
	v_mfma_f32_16x16x32_bf16 v[56:59], v[160:163], v[184:187], v[56:59]
	v_mfma_f32_16x16x32_bf16 v[52:55], v[152:155], v[196:199], v[52:55]
	v_mfma_f32_16x16x32_bf16 v[44:47], v[160:163], v[196:199], v[44:47]
	v_mfma_f32_16x16x32_bf16 v[36:39], v[152:155], v[204:207], v[36:39]
	v_mfma_f32_16x16x32_bf16 v[28:31], v[160:163], v[204:207], v[28:31]
	v_mfma_f32_16x16x32_bf16 v[20:23], v[152:155], v[212:215], v[20:23]
	v_mfma_f32_16x16x32_bf16 v[12:15], v[160:163], v[212:215], v[12:15]
	v_mfma_f32_16x16x32_bf16 v[60:63], v[156:159], v[192:195], v[60:63]
	v_mfma_f32_16x16x32_bf16 v[56:59], v[164:167], v[192:195], v[56:59]
	v_mfma_f32_16x16x32_bf16 v[52:55], v[156:159], v[200:203], v[52:55]
	v_mfma_f32_16x16x32_bf16 v[44:47], v[164:167], v[200:203], v[44:47]
	v_mfma_f32_16x16x32_bf16 v[36:39], v[156:159], v[208:211], v[36:39]
	v_mfma_f32_16x16x32_bf16 v[28:31], v[164:167], v[208:211], v[28:31]
	v_mfma_f32_16x16x32_bf16 v[20:23], v[156:159], v[216:219], v[20:23]
	v_mfma_f32_16x16x32_bf16 v[12:15], v[164:167], v[216:219], v[12:15]
	s_setprio 0
	s_setprio 1
	v_mfma_f32_16x16x32_bf16 v[48:51], v[168:171], v[184:187], v[48:51]
	v_mfma_f32_16x16x32_bf16 v[40:43], v[176:179], v[184:187], v[40:43]
	v_mfma_f32_16x16x32_bf16 v[32:35], v[168:171], v[196:199], v[32:35]
	v_mfma_f32_16x16x32_bf16 v[24:27], v[176:179], v[196:199], v[24:27]
	v_mfma_f32_16x16x32_bf16 v[16:19], v[168:171], v[204:207], v[16:19]
	v_mfma_f32_16x16x32_bf16 v[8:11], v[176:179], v[204:207], v[8:11]
	v_mfma_f32_16x16x32_bf16 v[4:7], v[168:171], v[212:215], v[4:7]
	v_mfma_f32_16x16x32_bf16 v[0:3], v[176:179], v[212:215], v[0:3]
	v_mfma_f32_16x16x32_bf16 v[48:51], v[172:175], v[192:195], v[48:51]
	v_mfma_f32_16x16x32_bf16 v[40:43], v[180:183], v[192:195], v[40:43]
	v_mfma_f32_16x16x32_bf16 v[32:35], v[172:175], v[200:203], v[32:35]
	v_mfma_f32_16x16x32_bf16 v[24:27], v[180:183], v[200:203], v[24:27]
	v_mfma_f32_16x16x32_bf16 v[16:19], v[172:175], v[208:211], v[16:19]
	v_mfma_f32_16x16x32_bf16 v[8:11], v[180:183], v[208:211], v[8:11]
	v_mfma_f32_16x16x32_bf16 v[4:7], v[172:175], v[216:219], v[4:7]
	v_mfma_f32_16x16x32_bf16 v[0:3], v[180:183], v[216:219], v[0:3]
	s_setprio 0
	s_barrier
	s_add_i32 s77, s77, 2
	s_add_u32 s30, s30, 0x100
	s_addc_u32 s31, s31, 0
	s_add_u32 s75, s75, 0x100
	s_addc_u32 s76, s76, 0
	s_cmp_gt_u32 s77, 13
	s_cbranch_scc0 .LBB0_1434
	s_branch .Lpeel_exit10

.LBB0_1570:
	s_ashr_i32 s23, s22, 31
	s_lshl_b64 s[24:25], s[22:23], 19
	s_add_u32 s24, s58, s24
	s_addc_u32 s25, s59, s25
	s_and_b64 s[26:27], s[0:1], exec
	s_cselect_b32 s23, s25, s31
	s_cselect_b32 s54, s24, s30
	s_ashr_i32 s21, s20, 31
	s_lshl_b64 s[26:27], s[20:21], 19
	s_add_u32 s26, s61, s26
	s_addc_u32 s27, s62, s27
	s_and_b64 s[42:43], s[0:1], exec
	s_cselect_b32 s21, s27, s35
	s_cselect_b32 s55, s26, s34
	s_add_u32 s30, s30, 0x40080
	s_addc_u32 s31, s31, 0
	s_add_u32 s75, s34, 0x100
	s_addc_u32 s76, s35, 0
	s_mov_b32 s77, -2
	ds_read_b128 v[152:155], v149
	ds_read_b128 v[156:159], v149 offset:1024
	ds_read_b128 v[160:163], v149 offset:2048
	ds_read_b128 v[164:167], v149 offset:3072
	ds_read_b128 v[168:171], v150
	ds_read_b128 v[172:175], v150 offset:1024
	ds_read_b128 v[176:179], v150 offset:2048
	ds_read_b128 v[180:183], v150 offset:3072
	s_add_u32 s34, s30, 0xfffc0080
	s_addc_u32 s35, s31, -1
	s_cmp_eq_u32 s77, 12
	s_cselect_b32 s43, s23, s35
	s_cselect_b32 s42, s54, s34
	s_cselect_b32 s35, s21, s76
	s_cselect_b32 s34, s55, s75
	s_add_i32 m0, s29, 0xc000
	ds_read_b128 v[184:187], v151
	ds_read_b128 v[192:195], v151 offset:1024
	ds_read_b128 v[196:199], v151 offset:2048
	ds_read_b128 v[200:203], v151 offset:3072
	ds_read_b128 v[204:207], v151 offset:4096
	ds_read_b128 v[208:211], v151 offset:5120
	ds_read_b128 v[212:215], v151 offset:6144
	ds_read_b128 v[216:219], v151 offset:7168
	global_load_lds_dwordx4 v136, s[30:31]
	s_add_i32 m0, s29, 0xe000
	s_nop 0
	global_load_lds_dwordx4 v138, s[30:31]
	s_waitcnt vmcnt(8)
	s_waitcnt lgkmcnt(0)
	s_barrier
	s_setprio 1
	s_waitcnt lgkmcnt(0)
	v_mfma_f32_16x16x32_bf16 v[124:127], v[152:155], v[184:187], 0
	v_mfma_f32_16x16x32_bf16 v[120:123], v[160:163], v[184:187], 0
	v_mfma_f32_16x16x32_bf16 v[108:111], v[152:155], v[196:199], 0
	v_mfma_f32_16x16x32_bf16 v[104:107], v[160:163], v[196:199], 0
	v_mfma_f32_16x16x32_bf16 v[92:95], v[152:155], v[204:207], 0
	v_mfma_f32_16x16x32_bf16 v[88:91], v[160:163], v[204:207], 0
	v_mfma_f32_16x16x32_bf16 v[76:79], v[152:155], v[212:215], 0
	v_mfma_f32_16x16x32_bf16 v[72:75], v[160:163], v[212:215], 0
	v_mfma_f32_16x16x32_bf16 v[124:127], v[156:159], v[192:195], v[124:127]
	v_mfma_f32_16x16x32_bf16 v[120:123], v[164:167], v[192:195], v[120:123]
	v_mfma_f32_16x16x32_bf16 v[108:111], v[156:159], v[200:203], v[108:111]
	v_mfma_f32_16x16x32_bf16 v[104:107], v[164:167], v[200:203], v[104:107]
	v_mfma_f32_16x16x32_bf16 v[92:95], v[156:159], v[208:211], v[92:95]
	v_mfma_f32_16x16x32_bf16 v[88:91], v[164:167], v[208:211], v[88:91]
	v_mfma_f32_16x16x32_bf16 v[76:79], v[156:159], v[216:219], v[76:79]
	v_mfma_f32_16x16x32_bf16 v[72:75], v[164:167], v[216:219], v[72:75]
	s_setprio 0
	s_setprio 1
	v_mfma_f32_16x16x32_bf16 v[116:119], v[168:171], v[184:187], 0
	v_mfma_f32_16x16x32_bf16 v[112:115], v[176:179], v[184:187], 0
	v_mfma_f32_16x16x32_bf16 v[100:103], v[168:171], v[196:199], 0
	v_mfma_f32_16x16x32_bf16 v[96:99], v[176:179], v[196:199], 0
	v_mfma_f32_16x16x32_bf16 v[84:87], v[168:171], v[204:207], 0
	v_mfma_f32_16x16x32_bf16 v[80:83], v[176:179], v[204:207], 0
	v_mfma_f32_16x16x32_bf16 v[68:71], v[168:171], v[212:215], 0
	v_mfma_f32_16x16x32_bf16 v[64:67], v[176:179], v[212:215], 0
	v_mfma_f32_16x16x32_bf16 v[116:119], v[172:175], v[192:195], v[116:119]
	v_mfma_f32_16x16x32_bf16 v[112:115], v[180:183], v[192:195], v[112:115]
	v_mfma_f32_16x16x32_bf16 v[100:103], v[172:175], v[200:203], v[100:103]
	v_mfma_f32_16x16x32_bf16 v[96:99], v[180:183], v[200:203], v[96:99]
	v_mfma_f32_16x16x32_bf16 v[84:87], v[172:175], v[208:211], v[84:87]
	v_mfma_f32_16x16x32_bf16 v[80:83], v[180:183], v[208:211], v[80:83]
	v_mfma_f32_16x16x32_bf16 v[68:71], v[172:175], v[216:219], v[68:71]
	v_mfma_f32_16x16x32_bf16 v[64:67], v[180:183], v[216:219], v[64:67]
	s_setprio 0
	s_barrier
	s_add_i32 s79, s69, s63
	v_lshl_add_u64 v[144:145], s[34:35], 0, v[130:131]
	s_mov_b32 m0, s79
	ds_read_b128 v[184:187], v151 offset:16384
	ds_read_b128 v[192:195], v151 offset:17408
	ds_read_b128 v[196:199], v151 offset:18432
	ds_read_b128 v[200:203], v151 offset:19456
	ds_read_b128 v[204:207], v151 offset:20480
	ds_read_b128 v[208:211], v151 offset:21504
	ds_read_b128 v[212:215], v151 offset:22528
	ds_read_b128 v[216:219], v151 offset:23552
	global_load_lds_dwordx4 v[144:145], off
	s_add_i32 m0, s79, 0x2000
	s_add_u32 s80, s34, 0x40000
	v_lshl_add_u64 v[188:189], s[34:35], 0, v[134:135]
	s_addc_u32 s81, s35, 0
	s_add_i32 s79, s70, s63
	global_load_lds_dwordx4 v[188:189], off
	s_mov_b32 m0, s79
	v_lshl_add_u64 v[222:223], s[42:43], 0, v[132:133]
	global_load_lds_dwordx4 v130, s[80:81]
	s_add_i32 m0, s79, 0x2000
	s_nop 0
	global_load_lds_dwordx4 v134, s[80:81]
	v_lshl_add_u64 v[220:221], s[42:43], 0, v[128:129]
	s_mov_b32 m0, s29
	s_nop 0
	global_load_lds_dwordx4 v[220:221], off
	s_mov_b32 m0, s64
	s_nop 0
	global_load_lds_dwordx4 v[222:223], off
	s_waitcnt vmcnt(8)
	s_waitcnt lgkmcnt(0)
	s_barrier
	s_setprio 1
	s_waitcnt lgkmcnt(0)
	v_mfma_f32_16x16x32_bf16 v[60:63], v[152:155], v[184:187], 0
	v_mfma_f32_16x16x32_bf16 v[56:59], v[160:163], v[184:187], 0
	v_mfma_f32_16x16x32_bf16 v[44:47], v[152:155], v[196:199], 0
	v_mfma_f32_16x16x32_bf16 v[40:43], v[160:163], v[196:199], 0
	v_mfma_f32_16x16x32_bf16 v[28:31], v[152:155], v[204:207], 0
	v_mfma_f32_16x16x32_bf16 v[24:27], v[160:163], v[204:207], 0
	v_mfma_f32_16x16x32_bf16 v[12:15], v[152:155], v[212:215], 0
	v_mfma_f32_16x16x32_bf16 v[8:11], v[160:163], v[212:215], 0
	v_mfma_f32_16x16x32_bf16 v[60:63], v[156:159], v[192:195], v[60:63]
	v_mfma_f32_16x16x32_bf16 v[56:59], v[164:167], v[192:195], v[56:59]
	v_mfma_f32_16x16x32_bf16 v[44:47], v[156:159], v[200:203], v[44:47]
	v_mfma_f32_16x16x32_bf16 v[40:43], v[164:167], v[200:203], v[40:43]
	v_mfma_f32_16x16x32_bf16 v[28:31], v[156:159], v[208:211], v[28:31]
	v_mfma_f32_16x16x32_bf16 v[24:27], v[164:167], v[208:211], v[24:27]
	v_mfma_f32_16x16x32_bf16 v[12:15], v[156:159], v[216:219], v[12:15]
	v_mfma_f32_16x16x32_bf16 v[8:11], v[164:167], v[216:219], v[8:11]
	s_setprio 0
	s_setprio 1
	v_mfma_f32_16x16x32_bf16 v[52:55], v[168:171], v[184:187], 0
	v_mfma_f32_16x16x32_bf16 v[48:51], v[176:179], v[184:187], 0
	v_mfma_f32_16x16x32_bf16 v[36:39], v[168:171], v[196:199], 0
	v_mfma_f32_16x16x32_bf16 v[32:35], v[176:179], v[196:199], 0
	v_mfma_f32_16x16x32_bf16 v[20:23], v[168:171], v[204:207], 0
	v_mfma_f32_16x16x32_bf16 v[16:19], v[176:179], v[204:207], 0
	v_mfma_f32_16x16x32_bf16 v[4:7], v[168:171], v[212:215], 0
	v_mfma_f32_16x16x32_bf16 v[0:3], v[176:179], v[212:215], 0
	v_mfma_f32_16x16x32_bf16 v[52:55], v[172:175], v[192:195], v[52:55]
	v_mfma_f32_16x16x32_bf16 v[48:51], v[180:183], v[192:195], v[48:51]
	v_mfma_f32_16x16x32_bf16 v[36:39], v[172:175], v[200:203], v[36:39]
	v_mfma_f32_16x16x32_bf16 v[32:35], v[180:183], v[200:203], v[32:35]
	v_mfma_f32_16x16x32_bf16 v[20:23], v[172:175], v[208:211], v[20:23]
	v_mfma_f32_16x16x32_bf16 v[16:19], v[180:183], v[208:211], v[16:19]
	v_mfma_f32_16x16x32_bf16 v[4:7], v[172:175], v[216:219], v[4:7]
	v_mfma_f32_16x16x32_bf16 v[0:3], v[180:183], v[216:219], v[0:3]
	s_setprio 0
	s_barrier
	s_add_i32 s79, 0, 0x18000
	s_add_i32 s80, 0, 0x1c000
	v_add_u32_e32 v164, s79, v147
	v_add_u32_e32 v180, s80, v147
	ds_read_b128 v[152:155], v164
	ds_read_b128 v[156:159], v164 offset:1024
	ds_read_b128 v[160:163], v164 offset:2048
	ds_read_b128 v[164:167], v164 offset:3072
	ds_read_b128 v[168:171], v180
	ds_read_b128 v[172:175], v180 offset:1024
	ds_read_b128 v[176:179], v180 offset:2048
	ds_read_b128 v[180:183], v180 offset:3072
	s_add_u32 s42, s42, 0x40000
	s_addc_u32 s43, s43, 0
	s_mov_b32 m0, s65
	ds_read_b128 v[184:187], v151 offset:32768
	ds_read_b128 v[192:195], v151 offset:33792
	ds_read_b128 v[196:199], v151 offset:34816
	ds_read_b128 v[200:203], v151 offset:35840
	ds_read_b128 v[204:207], v151 offset:36864
	ds_read_b128 v[208:211], v151 offset:37888
	ds_read_b128 v[212:215], v151 offset:38912
	ds_read_b128 v[216:219], v151 offset:39936
	global_load_lds_dwordx4 v128, s[42:43]
	s_mov_b32 m0, s66
	s_nop 0
	global_load_lds_dwordx4 v132, s[42:43]
	s_waitcnt vmcnt(8)
	s_waitcnt lgkmcnt(0)
	s_barrier
	s_setprio 1
	s_waitcnt lgkmcnt(0)
	v_mfma_f32_16x16x32_bf16 v[124:127], v[152:155], v[184:187], v[124:127]
	v_mfma_f32_16x16x32_bf16 v[120:123], v[160:163], v[184:187], v[120:123]
	v_mfma_f32_16x16x32_bf16 v[108:111], v[152:155], v[196:199], v[108:111]
	v_mfma_f32_16x16x32_bf16 v[104:107], v[160:163], v[196:199], v[104:107]
	v_mfma_f32_16x16x32_bf16 v[92:95], v[152:155], v[204:207], v[92:95]
	v_mfma_f32_16x16x32_bf16 v[88:91], v[160:163], v[204:207], v[88:91]
	v_mfma_f32_16x16x32_bf16 v[76:79], v[152:155], v[212:215], v[76:79]
	v_mfma_f32_16x16x32_bf16 v[72:75], v[160:163], v[212:215], v[72:75]
	v_mfma_f32_16x16x32_bf16 v[124:127], v[156:159], v[192:195], v[124:127]
	v_mfma_f32_16x16x32_bf16 v[120:123], v[164:167], v[192:195], v[120:123]
	v_mfma_f32_16x16x32_bf16 v[108:111], v[156:159], v[200:203], v[108:111]
	v_mfma_f32_16x16x32_bf16 v[104:107], v[164:167], v[200:203], v[104:107]
	v_mfma_f32_16x16x32_bf16 v[92:95], v[156:159], v[208:211], v[92:95]
	v_mfma_f32_16x16x32_bf16 v[88:91], v[164:167], v[208:211], v[88:91]
	v_mfma_f32_16x16x32_bf16 v[76:79], v[156:159], v[216:219], v[76:79]
	v_mfma_f32_16x16x32_bf16 v[72:75], v[164:167], v[216:219], v[72:75]
	s_setprio 0
	s_setprio 1
	v_mfma_f32_16x16x32_bf16 v[116:119], v[168:171], v[184:187], v[116:119]
	v_mfma_f32_16x16x32_bf16 v[112:115], v[176:179], v[184:187], v[112:115]
	v_mfma_f32_16x16x32_bf16 v[100:103], v[168:171], v[196:199], v[100:103]
	v_mfma_f32_16x16x32_bf16 v[96:99], v[176:179], v[196:199], v[96:99]
	v_mfma_f32_16x16x32_bf16 v[84:87], v[168:171], v[204:207], v[84:87]
	v_mfma_f32_16x16x32_bf16 v[80:83], v[176:179], v[204:207], v[80:83]
	v_mfma_f32_16x16x32_bf16 v[68:71], v[168:171], v[212:215], v[68:71]
	v_mfma_f32_16x16x32_bf16 v[64:67], v[176:179], v[212:215], v[64:67]
	v_mfma_f32_16x16x32_bf16 v[116:119], v[172:175], v[192:195], v[116:119]
	v_mfma_f32_16x16x32_bf16 v[112:115], v[180:183], v[192:195], v[112:115]
	v_mfma_f32_16x16x32_bf16 v[100:103], v[172:175], v[200:203], v[100:103]
	v_mfma_f32_16x16x32_bf16 v[96:99], v[180:183], v[200:203], v[96:99]
	v_mfma_f32_16x16x32_bf16 v[84:87], v[172:175], v[208:211], v[84:87]
	v_mfma_f32_16x16x32_bf16 v[80:83], v[180:183], v[208:211], v[80:83]
	v_mfma_f32_16x16x32_bf16 v[68:71], v[172:175], v[216:219], v[68:71]
	v_mfma_f32_16x16x32_bf16 v[64:67], v[180:183], v[216:219], v[64:67]
	s_setprio 0
	s_barrier
	s_add_i32 s42, s79, s63
	v_lshl_add_u64 v[144:145], v[144:145], 0, s[8:9]
	s_mov_b32 m0, s42
	ds_read_b128 v[184:187], v151 offset:49152
	ds_read_b128 v[192:195], v151 offset:50176
	ds_read_b128 v[196:199], v151 offset:51200
	ds_read_b128 v[200:203], v151 offset:52224
	ds_read_b128 v[204:207], v151 offset:53248
	ds_read_b128 v[208:211], v151 offset:54272
	ds_read_b128 v[212:215], v151 offset:55296
	ds_read_b128 v[216:219], v151 offset:56320
	global_load_lds_dwordx4 v[144:145], off
	s_add_i32 m0, s42, 0x2000
	s_add_u32 s34, s34, 0x40080
	v_lshl_add_u64 v[144:145], v[188:189], 0, s[8:9]
	s_addc_u32 s35, s35, 0
	s_add_i32 s42, s80, s63
	global_load_lds_dwordx4 v[144:145], off
	s_mov_b32 m0, s42
	s_nop 0
	global_load_lds_dwordx4 v130, s[34:35]
	s_add_i32 m0, s42, 0x2000
	s_nop 0
	global_load_lds_dwordx4 v134, s[34:35]
	v_lshl_add_u64 v[144:145], v[220:221], 0, s[8:9]
	s_mov_b32 m0, s52
	s_nop 0
	global_load_lds_dwordx4 v[144:145], off
	v_lshl_add_u64 v[144:145], v[222:223], 0, s[8:9]
	s_mov_b32 m0, s53
	s_nop 0
	global_load_lds_dwordx4 v[144:145], off
	s_waitcnt vmcnt(8)
	s_waitcnt lgkmcnt(0)
	s_barrier
	s_setprio 1
	s_waitcnt lgkmcnt(0)
	v_mfma_f32_16x16x32_bf16 v[60:63], v[152:155], v[184:187], v[60:63]
	v_mfma_f32_16x16x32_bf16 v[56:59], v[160:163], v[184:187], v[56:59]
	v_mfma_f32_16x16x32_bf16 v[44:47], v[152:155], v[196:199], v[44:47]
	v_mfma_f32_16x16x32_bf16 v[40:43], v[160:163], v[196:199], v[40:43]
	v_mfma_f32_16x16x32_bf16 v[28:31], v[152:155], v[204:207], v[28:31]
	v_mfma_f32_16x16x32_bf16 v[24:27], v[160:163], v[204:207], v[24:27]
	v_mfma_f32_16x16x32_bf16 v[12:15], v[152:155], v[212:215], v[12:15]
	v_mfma_f32_16x16x32_bf16 v[8:11], v[160:163], v[212:215], v[8:11]
	v_mfma_f32_16x16x32_bf16 v[60:63], v[156:159], v[192:195], v[60:63]
	v_mfma_f32_16x16x32_bf16 v[56:59], v[164:167], v[192:195], v[56:59]
	v_mfma_f32_16x16x32_bf16 v[44:47], v[156:159], v[200:203], v[44:47]
	v_mfma_f32_16x16x32_bf16 v[40:43], v[164:167], v[200:203], v[40:43]
	v_mfma_f32_16x16x32_bf16 v[28:31], v[156:159], v[208:211], v[28:31]
	v_mfma_f32_16x16x32_bf16 v[24:27], v[164:167], v[208:211], v[24:27]
	v_mfma_f32_16x16x32_bf16 v[12:15], v[156:159], v[216:219], v[12:15]
	v_mfma_f32_16x16x32_bf16 v[8:11], v[164:167], v[216:219], v[8:11]
	s_setprio 0
	s_setprio 1
	v_mfma_f32_16x16x32_bf16 v[52:55], v[168:171], v[184:187], v[52:55]
	v_mfma_f32_16x16x32_bf16 v[48:51], v[176:179], v[184:187], v[48:51]
	v_mfma_f32_16x16x32_bf16 v[36:39], v[168:171], v[196:199], v[36:39]
	v_mfma_f32_16x16x32_bf16 v[32:35], v[176:179], v[196:199], v[32:35]
	v_mfma_f32_16x16x32_bf16 v[20:23], v[168:171], v[204:207], v[20:23]
	v_mfma_f32_16x16x32_bf16 v[16:19], v[176:179], v[204:207], v[16:19]
	v_mfma_f32_16x16x32_bf16 v[4:7], v[168:171], v[212:215], v[4:7]
	v_mfma_f32_16x16x32_bf16 v[0:3], v[176:179], v[212:215], v[0:3]
	v_mfma_f32_16x16x32_bf16 v[52:55], v[172:175], v[192:195], v[52:55]
	v_mfma_f32_16x16x32_bf16 v[48:51], v[180:183], v[192:195], v[48:51]
	v_mfma_f32_16x16x32_bf16 v[36:39], v[172:175], v[200:203], v[36:39]
	v_mfma_f32_16x16x32_bf16 v[32:35], v[180:183], v[200:203], v[32:35]
	v_mfma_f32_16x16x32_bf16 v[20:23], v[172:175], v[208:211], v[20:23]
	v_mfma_f32_16x16x32_bf16 v[16:19], v[180:183], v[208:211], v[16:19]
	v_mfma_f32_16x16x32_bf16 v[4:7], v[172:175], v[216:219], v[4:7]
	v_mfma_f32_16x16x32_bf16 v[0:3], v[180:183], v[216:219], v[0:3]
	s_setprio 0
	s_barrier
	s_add_i32 s77, s77, 2
	s_add_u32 s30, s30, 0x100
	s_addc_u32 s31, s31, 0
	s_add_u32 s75, s75, 0x100
	s_addc_u32 s76, s76, 0
	s_cmp_gt_u32 s77, 13
	s_cbranch_scc0 .LBB0_1571
	s_branch .Lpeel_exit11

.Lpeel_exit11:
	s_and_b64 vcc, exec, s[10:11]
	s_cbranch_vccz .LBB0_1574
	s_barrier

.LBB0_1649:
	s_ashr_i32 s23, s22, 31
	s_lshl_b64 s[24:25], s[22:23], 21
	s_add_u32 s24, s56, s24
	s_addc_u32 s25, s57, s25
	s_and_b64 s[26:27], s[0:1], exec
	s_cselect_b32 s23, s25, s31
	s_cselect_b32 s55, s24, s30
	s_ashr_i32 s21, s20, 31
	s_lshl_b64 s[26:27], s[20:21], 21
	s_add_u32 s26, s53, s26
	s_addc_u32 s27, s58, s27
	s_and_b64 s[42:43], s[0:1], exec
	s_cselect_b32 s21, s27, s35
	s_cselect_b32 s72, s26, s34
	s_add_u32 s30, s30, 0x100080
	s_addc_u32 s31, s31, 0
	s_add_u32 s73, s34, 0x100
	s_addc_u32 s74, s35, 0
	s_mov_b32 s75, -2
	ds_read_b128 v[152:155], v149
	ds_read_b128 v[156:159], v149 offset:1024
	ds_read_b128 v[160:163], v149 offset:2048
	ds_read_b128 v[164:167], v149 offset:3072
	ds_read_b128 v[168:171], v150
	ds_read_b128 v[172:175], v150 offset:1024
	ds_read_b128 v[176:179], v150 offset:2048
	ds_read_b128 v[180:183], v150 offset:3072
	s_add_u32 s34, s30, 0xfff00080
	s_addc_u32 s35, s31, -1
	s_cmp_eq_u32 s75, 60
	s_cselect_b32 s43, s23, s35
	s_cselect_b32 s42, s55, s34
	s_cselect_b32 s35, s21, s74
	s_cselect_b32 s34, s72, s73
	s_add_i32 m0, s29, 0xc000
	ds_read_b128 v[184:187], v151
	ds_read_b128 v[192:195], v151 offset:1024
	ds_read_b128 v[196:199], v151 offset:2048
	ds_read_b128 v[200:203], v151 offset:3072
	ds_read_b128 v[204:207], v151 offset:4096
	ds_read_b128 v[208:211], v151 offset:5120
	ds_read_b128 v[212:215], v151 offset:6144
	ds_read_b128 v[216:219], v151 offset:7168
	global_load_lds_dwordx4 v136, s[30:31]
	s_add_i32 m0, s29, 0xe000
	s_nop 0
	global_load_lds_dwordx4 v138, s[30:31]
	s_waitcnt vmcnt(8)
	s_waitcnt lgkmcnt(0)
	s_barrier
	s_setprio 1
	s_waitcnt lgkmcnt(0)
	v_mfma_f32_16x16x32_bf16 v[124:127], v[152:155], v[184:187], 0
	v_mfma_f32_16x16x32_bf16 v[120:123], v[160:163], v[184:187], 0
	v_mfma_f32_16x16x32_bf16 v[116:119], v[152:155], v[196:199], 0
	v_mfma_f32_16x16x32_bf16 v[108:111], v[160:163], v[196:199], 0
	v_mfma_f32_16x16x32_bf16 v[100:103], v[152:155], v[204:207], 0
	v_mfma_f32_16x16x32_bf16 v[92:95], v[160:163], v[204:207], 0
	v_mfma_f32_16x16x32_bf16 v[84:87], v[152:155], v[212:215], 0
	v_mfma_f32_16x16x32_bf16 v[76:79], v[160:163], v[212:215], 0
	v_mfma_f32_16x16x32_bf16 v[124:127], v[156:159], v[192:195], v[124:127]
	v_mfma_f32_16x16x32_bf16 v[120:123], v[164:167], v[192:195], v[120:123]
	v_mfma_f32_16x16x32_bf16 v[116:119], v[156:159], v[200:203], v[116:119]
	v_mfma_f32_16x16x32_bf16 v[108:111], v[164:167], v[200:203], v[108:111]
	v_mfma_f32_16x16x32_bf16 v[100:103], v[156:159], v[208:211], v[100:103]
	v_mfma_f32_16x16x32_bf16 v[92:95], v[164:167], v[208:211], v[92:95]
	v_mfma_f32_16x16x32_bf16 v[84:87], v[156:159], v[216:219], v[84:87]
	v_mfma_f32_16x16x32_bf16 v[76:79], v[164:167], v[216:219], v[76:79]
	s_setprio 0
	s_setprio 1
	v_mfma_f32_16x16x32_bf16 v[112:115], v[168:171], v[184:187], 0
	v_mfma_f32_16x16x32_bf16 v[104:107], v[176:179], v[184:187], 0
	v_mfma_f32_16x16x32_bf16 v[96:99], v[168:171], v[196:199], 0
	v_mfma_f32_16x16x32_bf16 v[88:91], v[176:179], v[196:199], 0
	v_mfma_f32_16x16x32_bf16 v[80:83], v[168:171], v[204:207], 0
	v_mfma_f32_16x16x32_bf16 v[72:75], v[176:179], v[204:207], 0
	v_mfma_f32_16x16x32_bf16 v[68:71], v[168:171], v[212:215], 0
	v_mfma_f32_16x16x32_bf16 v[64:67], v[176:179], v[212:215], 0
	v_mfma_f32_16x16x32_bf16 v[112:115], v[172:175], v[192:195], v[112:115]
	v_mfma_f32_16x16x32_bf16 v[104:107], v[180:183], v[192:195], v[104:107]
	v_mfma_f32_16x16x32_bf16 v[96:99], v[172:175], v[200:203], v[96:99]
	v_mfma_f32_16x16x32_bf16 v[88:91], v[180:183], v[200:203], v[88:91]
	v_mfma_f32_16x16x32_bf16 v[80:83], v[172:175], v[208:211], v[80:83]
	v_mfma_f32_16x16x32_bf16 v[72:75], v[180:183], v[208:211], v[72:75]
	v_mfma_f32_16x16x32_bf16 v[68:71], v[172:175], v[216:219], v[68:71]
	v_mfma_f32_16x16x32_bf16 v[64:67], v[180:183], v[216:219], v[64:67]
	s_setprio 0
	s_barrier
	s_add_i32 s76, s66, s59
	v_lshl_add_u64 v[144:145], s[34:35], 0, v[130:131]
	s_mov_b32 m0, s76
	ds_read_b128 v[184:187], v151 offset:16384
	ds_read_b128 v[192:195], v151 offset:17408
	ds_read_b128 v[196:199], v151 offset:18432
	ds_read_b128 v[200:203], v151 offset:19456
	ds_read_b128 v[204:207], v151 offset:20480
	ds_read_b128 v[208:211], v151 offset:21504
	ds_read_b128 v[212:215], v151 offset:22528
	ds_read_b128 v[216:219], v151 offset:23552
	global_load_lds_dwordx4 v[144:145], off
	s_add_i32 m0, s76, 0x2000
	s_add_u32 s76, s34, 0x100000
	v_lshl_add_u64 v[188:189], s[34:35], 0, v[134:135]
	s_addc_u32 s77, s35, 0
	s_add_i32 s79, s67, s59
	global_load_lds_dwordx4 v[188:189], off
	s_mov_b32 m0, s79
	v_lshl_add_u64 v[222:223], s[42:43], 0, v[132:133]
	global_load_lds_dwordx4 v130, s[76:77]
	s_add_i32 m0, s79, 0x2000
	s_nop 0
	global_load_lds_dwordx4 v134, s[76:77]
	v_lshl_add_u64 v[220:221], s[42:43], 0, v[128:129]
	s_mov_b32 m0, s29
	s_nop 0
	global_load_lds_dwordx4 v[220:221], off
	s_mov_b32 m0, s33
	s_nop 0
	global_load_lds_dwordx4 v[222:223], off
	s_waitcnt vmcnt(8)
	s_waitcnt lgkmcnt(0)
	s_barrier
	s_setprio 1
	s_waitcnt lgkmcnt(0)
	v_mfma_f32_16x16x32_bf16 v[60:63], v[152:155], v[184:187], 0
	v_mfma_f32_16x16x32_bf16 v[56:59], v[160:163], v[184:187], 0
	v_mfma_f32_16x16x32_bf16 v[52:55], v[152:155], v[196:199], 0
	v_mfma_f32_16x16x32_bf16 v[44:47], v[160:163], v[196:199], 0
	v_mfma_f32_16x16x32_bf16 v[36:39], v[152:155], v[204:207], 0
	v_mfma_f32_16x16x32_bf16 v[28:31], v[160:163], v[204:207], 0
	v_mfma_f32_16x16x32_bf16 v[20:23], v[152:155], v[212:215], 0
	v_mfma_f32_16x16x32_bf16 v[12:15], v[160:163], v[212:215], 0
	v_mfma_f32_16x16x32_bf16 v[60:63], v[156:159], v[192:195], v[60:63]
	v_mfma_f32_16x16x32_bf16 v[56:59], v[164:167], v[192:195], v[56:59]
	v_mfma_f32_16x16x32_bf16 v[52:55], v[156:159], v[200:203], v[52:55]
	v_mfma_f32_16x16x32_bf16 v[44:47], v[164:167], v[200:203], v[44:47]
	v_mfma_f32_16x16x32_bf16 v[36:39], v[156:159], v[208:211], v[36:39]
	v_mfma_f32_16x16x32_bf16 v[28:31], v[164:167], v[208:211], v[28:31]
	v_mfma_f32_16x16x32_bf16 v[20:23], v[156:159], v[216:219], v[20:23]
	v_mfma_f32_16x16x32_bf16 v[12:15], v[164:167], v[216:219], v[12:15]
	s_setprio 0
	s_setprio 1
	v_mfma_f32_16x16x32_bf16 v[48:51], v[168:171], v[184:187], 0
	v_mfma_f32_16x16x32_bf16 v[40:43], v[176:179], v[184:187], 0
	v_mfma_f32_16x16x32_bf16 v[32:35], v[168:171], v[196:199], 0
	v_mfma_f32_16x16x32_bf16 v[24:27], v[176:179], v[196:199], 0
	v_mfma_f32_16x16x32_bf16 v[16:19], v[168:171], v[204:207], 0
	v_mfma_f32_16x16x32_bf16 v[8:11], v[176:179], v[204:207], 0
	v_mfma_f32_16x16x32_bf16 v[4:7], v[168:171], v[212:215], 0
	v_mfma_f32_16x16x32_bf16 v[0:3], v[176:179], v[212:215], 0
	v_mfma_f32_16x16x32_bf16 v[48:51], v[172:175], v[192:195], v[48:51]
	v_mfma_f32_16x16x32_bf16 v[40:43], v[180:183], v[192:195], v[40:43]
	v_mfma_f32_16x16x32_bf16 v[32:35], v[172:175], v[200:203], v[32:35]
	v_mfma_f32_16x16x32_bf16 v[24:27], v[180:183], v[200:203], v[24:27]
	v_mfma_f32_16x16x32_bf16 v[16:19], v[172:175], v[208:211], v[16:19]
	v_mfma_f32_16x16x32_bf16 v[8:11], v[180:183], v[208:211], v[8:11]
	v_mfma_f32_16x16x32_bf16 v[4:7], v[172:175], v[216:219], v[4:7]
	v_mfma_f32_16x16x32_bf16 v[0:3], v[180:183], v[216:219], v[0:3]
	s_setprio 0
	s_barrier
	s_add_i32 s76, 0, 0x18000
	s_add_i32 s77, 0, 0x1c000
	v_add_u32_e32 v164, s76, v147
	v_add_u32_e32 v180, s77, v147
	ds_read_b128 v[152:155], v164
	ds_read_b128 v[156:159], v164 offset:1024
	ds_read_b128 v[160:163], v164 offset:2048
	ds_read_b128 v[164:167], v164 offset:3072
	ds_read_b128 v[168:171], v180
	ds_read_b128 v[172:175], v180 offset:1024
	ds_read_b128 v[176:179], v180 offset:2048
	ds_read_b128 v[180:183], v180 offset:3072
	s_add_u32 s42, s42, 0x100000
	s_addc_u32 s43, s43, 0
	s_mov_b32 m0, s60
	ds_read_b128 v[184:187], v151 offset:32768
	ds_read_b128 v[192:195], v151 offset:33792
	ds_read_b128 v[196:199], v151 offset:34816
	ds_read_b128 v[200:203], v151 offset:35840
	ds_read_b128 v[204:207], v151 offset:36864
	ds_read_b128 v[208:211], v151 offset:37888
	ds_read_b128 v[212:215], v151 offset:38912
	ds_read_b128 v[216:219], v151 offset:39936
	global_load_lds_dwordx4 v128, s[42:43]
	s_mov_b32 m0, s61
	s_nop 0
	global_load_lds_dwordx4 v132, s[42:43]
	s_waitcnt vmcnt(8)
	s_waitcnt lgkmcnt(0)
	s_barrier
	s_setprio 1
	s_waitcnt lgkmcnt(0)
	v_mfma_f32_16x16x32_bf16 v[124:127], v[152:155], v[184:187], v[124:127]
	v_mfma_f32_16x16x32_bf16 v[120:123], v[160:163], v[184:187], v[120:123]
	v_mfma_f32_16x16x32_bf16 v[116:119], v[152:155], v[196:199], v[116:119]
	v_mfma_f32_16x16x32_bf16 v[108:111], v[160:163], v[196:199], v[108:111]
	v_mfma_f32_16x16x32_bf16 v[100:103], v[152:155], v[204:207], v[100:103]
	v_mfma_f32_16x16x32_bf16 v[92:95], v[160:163], v[204:207], v[92:95]
	v_mfma_f32_16x16x32_bf16 v[84:87], v[152:155], v[212:215], v[84:87]
	v_mfma_f32_16x16x32_bf16 v[76:79], v[160:163], v[212:215], v[76:79]
	v_mfma_f32_16x16x32_bf16 v[124:127], v[156:159], v[192:195], v[124:127]
	v_mfma_f32_16x16x32_bf16 v[120:123], v[164:167], v[192:195], v[120:123]
	v_mfma_f32_16x16x32_bf16 v[116:119], v[156:159], v[200:203], v[116:119]
	v_mfma_f32_16x16x32_bf16 v[108:111], v[164:167], v[200:203], v[108:111]
	v_mfma_f32_16x16x32_bf16 v[100:103], v[156:159], v[208:211], v[100:103]
	v_mfma_f32_16x16x32_bf16 v[92:95], v[164:167], v[208:211], v[92:95]
	v_mfma_f32_16x16x32_bf16 v[84:87], v[156:159], v[216:219], v[84:87]
	v_mfma_f32_16x16x32_bf16 v[76:79], v[164:167], v[216:219], v[76:79]
	s_setprio 0
	s_setprio 1
	v_mfma_f32_16x16x32_bf16 v[112:115], v[168:171], v[184:187], v[112:115]
	v_mfma_f32_16x16x32_bf16 v[104:107], v[176:179], v[184:187], v[104:107]
	v_mfma_f32_16x16x32_bf16 v[96:99], v[168:171], v[196:199], v[96:99]
	v_mfma_f32_16x16x32_bf16 v[88:91], v[176:179], v[196:199], v[88:91]
	v_mfma_f32_16x16x32_bf16 v[80:83], v[168:171], v[204:207], v[80:83]
	v_mfma_f32_16x16x32_bf16 v[72:75], v[176:179], v[204:207], v[72:75]
	v_mfma_f32_16x16x32_bf16 v[68:71], v[168:171], v[212:215], v[68:71]
	v_mfma_f32_16x16x32_bf16 v[64:67], v[176:179], v[212:215], v[64:67]
	v_mfma_f32_16x16x32_bf16 v[112:115], v[172:175], v[192:195], v[112:115]
	v_mfma_f32_16x16x32_bf16 v[104:107], v[180:183], v[192:195], v[104:107]
	v_mfma_f32_16x16x32_bf16 v[96:99], v[172:175], v[200:203], v[96:99]
	v_mfma_f32_16x16x32_bf16 v[88:91], v[180:183], v[200:203], v[88:91]
	v_mfma_f32_16x16x32_bf16 v[80:83], v[172:175], v[208:211], v[80:83]
	v_mfma_f32_16x16x32_bf16 v[72:75], v[180:183], v[208:211], v[72:75]
	v_mfma_f32_16x16x32_bf16 v[68:71], v[172:175], v[216:219], v[68:71]
	v_mfma_f32_16x16x32_bf16 v[64:67], v[180:183], v[216:219], v[64:67]
	s_setprio 0
	s_barrier
	s_add_i32 s42, s76, s59
	v_lshl_add_u64 v[144:145], v[144:145], 0, s[8:9]
	s_mov_b32 m0, s42
	ds_read_b128 v[184:187], v151 offset:49152
	ds_read_b128 v[192:195], v151 offset:50176
	ds_read_b128 v[196:199], v151 offset:51200
	ds_read_b128 v[200:203], v151 offset:52224
	ds_read_b128 v[204:207], v151 offset:53248
	ds_read_b128 v[208:211], v151 offset:54272
	ds_read_b128 v[212:215], v151 offset:55296
	ds_read_b128 v[216:219], v151 offset:56320
	global_load_lds_dwordx4 v[144:145], off
	s_add_i32 m0, s42, 0x2000
	s_add_u32 s34, s34, 0x100080
	v_lshl_add_u64 v[144:145], v[188:189], 0, s[8:9]
	s_addc_u32 s35, s35, 0
	s_add_i32 s42, s77, s59
	global_load_lds_dwordx4 v[144:145], off
	s_mov_b32 m0, s42
	s_nop 0
	global_load_lds_dwordx4 v130, s[34:35]
	s_add_i32 m0, s42, 0x2000
	s_nop 0
	global_load_lds_dwordx4 v134, s[34:35]
	v_lshl_add_u64 v[144:145], v[220:221], 0, s[8:9]
	s_mov_b32 m0, s63
	s_nop 0
	global_load_lds_dwordx4 v[144:145], off
	v_lshl_add_u64 v[144:145], v[222:223], 0, s[8:9]
	s_mov_b32 m0, s64
	s_nop 0
	global_load_lds_dwordx4 v[144:145], off
	s_waitcnt vmcnt(8)
	s_waitcnt lgkmcnt(0)
	s_barrier
	s_setprio 1
	s_waitcnt lgkmcnt(0)
	v_mfma_f32_16x16x32_bf16 v[60:63], v[152:155], v[184:187], v[60:63]
	v_mfma_f32_16x16x32_bf16 v[56:59], v[160:163], v[184:187], v[56:59]
	v_mfma_f32_16x16x32_bf16 v[52:55], v[152:155], v[196:199], v[52:55]
	v_mfma_f32_16x16x32_bf16 v[44:47], v[160:163], v[196:199], v[44:47]
	v_mfma_f32_16x16x32_bf16 v[36:39], v[152:155], v[204:207], v[36:39]
	v_mfma_f32_16x16x32_bf16 v[28:31], v[160:163], v[204:207], v[28:31]
	v_mfma_f32_16x16x32_bf16 v[20:23], v[152:155], v[212:215], v[20:23]
	v_mfma_f32_16x16x32_bf16 v[12:15], v[160:163], v[212:215], v[12:15]
	v_mfma_f32_16x16x32_bf16 v[60:63], v[156:159], v[192:195], v[60:63]
	v_mfma_f32_16x16x32_bf16 v[56:59], v[164:167], v[192:195], v[56:59]
	v_mfma_f32_16x16x32_bf16 v[52:55], v[156:159], v[200:203], v[52:55]
	v_mfma_f32_16x16x32_bf16 v[44:47], v[164:167], v[200:203], v[44:47]
	v_mfma_f32_16x16x32_bf16 v[36:39], v[156:159], v[208:211], v[36:39]
	v_mfma_f32_16x16x32_bf16 v[28:31], v[164:167], v[208:211], v[28:31]
	v_mfma_f32_16x16x32_bf16 v[20:23], v[156:159], v[216:219], v[20:23]
	v_mfma_f32_16x16x32_bf16 v[12:15], v[164:167], v[216:219], v[12:15]
	s_setprio 0
	s_setprio 1
	v_mfma_f32_16x16x32_bf16 v[48:51], v[168:171], v[184:187], v[48:51]
	v_mfma_f32_16x16x32_bf16 v[40:43], v[176:179], v[184:187], v[40:43]
	v_mfma_f32_16x16x32_bf16 v[32:35], v[168:171], v[196:199], v[32:35]
	v_mfma_f32_16x16x32_bf16 v[24:27], v[176:179], v[196:199], v[24:27]
	v_mfma_f32_16x16x32_bf16 v[16:19], v[168:171], v[204:207], v[16:19]
	v_mfma_f32_16x16x32_bf16 v[8:11], v[176:179], v[204:207], v[8:11]
	v_mfma_f32_16x16x32_bf16 v[4:7], v[168:171], v[212:215], v[4:7]
	v_mfma_f32_16x16x32_bf16 v[0:3], v[176:179], v[212:215], v[0:3]
	v_mfma_f32_16x16x32_bf16 v[48:51], v[172:175], v[192:195], v[48:51]
	v_mfma_f32_16x16x32_bf16 v[40:43], v[180:183], v[192:195], v[40:43]
	v_mfma_f32_16x16x32_bf16 v[32:35], v[172:175], v[200:203], v[32:35]
	v_mfma_f32_16x16x32_bf16 v[24:27], v[180:183], v[200:203], v[24:27]
	v_mfma_f32_16x16x32_bf16 v[16:19], v[172:175], v[208:211], v[16:19]
	v_mfma_f32_16x16x32_bf16 v[8:11], v[180:183], v[208:211], v[8:11]
	v_mfma_f32_16x16x32_bf16 v[4:7], v[172:175], v[216:219], v[4:7]
	v_mfma_f32_16x16x32_bf16 v[0:3], v[180:183], v[216:219], v[0:3]
	s_setprio 0
	s_barrier
	s_add_i32 s75, s75, 2
	s_add_u32 s30, s30, 0x100
	s_addc_u32 s31, s31, 0
	s_add_u32 s73, s73, 0x100
	s_addc_u32 s74, s74, 0
	s_cmp_gt_u32 s75, 61
	s_cbranch_scc0 .LBB0_1650
	s_branch .Lpeel_exit12
